# chunk-prep triangular inverse rewritten by hand with packed f32 FMAs (x in place, 14-deep LDS vector ring)
# speedup vs baseline: 1.0514x; 1.0102x over previous
; #define PG8_LAS __attribute__((address_space(3)))
; __device__ __forceinline__ void solve64(float (&x)[64], const PG8_LAS float* sLt) {
;     f32x4 cur[16];
; #pragma unroll
;     for (int i4 = 0; i4 < 16; ++i4) cur[i4] = *(const PG8_LAS f32x4*)(sLt + 4 * i4);
;     asm volatile("" ::: "memory");
; #pragma unroll
;     for (int j = 0; j < 63; ++j) {
;         const float xj = x[j];
; #pragma unroll
;         for (int i4 = (j + 1) / 4; i4 < 16; ++i4) {
;             if (4 * i4 + 0 > j) x[4 * i4 + 0] -= cur[i4][0] * xj;
;             if (4 * i4 + 1 > j) x[4 * i4 + 1] -= cur[i4][1] * xj;
;             if (4 * i4 + 2 > j) x[4 * i4 + 2] -= cur[i4][2] * xj;
;             if (4 * i4 + 3 > j) x[4 * i4 + 3] -= cur[i4][3] * xj;
;             if (j + 1 < 63 && i4 >= (j + 2) / 4) cur[i4] = *(const PG8_LAS f32x4*)(sLt + (j + 1) * 64 + 4 * i4); }
;         asm volatile("" ::: "memory");
;     }
; __device__ __forceinline__ void phase_prep(const Args& a, PG8_LAS unsigned char* lds) {
;     ...
;         if (role == 0) {
;             float x[64];
; #pragma unroll
;             for (int i = 0; i < 64; ++i) x[i] = (i == lane) ? 1.0f : 0.0f;
;             __builtin_amdgcn_s_setprio(3);
;             solve64(x, sL);
;             __builtin_amdgcn_s_setprio(0);
.LBB0_298:
	s_andn2_b64 vcc, exec, s[26:27]
	s_cbranch_vccnz .LBB0_252
	s_setprio 3
	v_readlane_b32 s14, v252, 32
	s_nop 1
	v_mov_b32_e32 v251, s14
	ds_read_b128 v[0:3], v251 offset:1024
	ds_read_b128 v[4:7], v251 offset:1040
	ds_read_b128 v[8:11], v251 offset:1056
	ds_read_b128 v[12:15], v251 offset:1072
	ds_read_b128 v[16:19], v251 offset:1088
	ds_read_b128 v[20:23], v251 offset:1104
	ds_read_b128 v[24:27], v251 offset:1120
	ds_read_b128 v[28:31], v251 offset:1136
	ds_read_b128 v[126:129], v251 offset:1152
	ds_read_b128 v[230:233], v251 offset:1168
	ds_read_b128 v[234:237], v251 offset:1184
	ds_read_b128 v[238:241], v251 offset:1200
	ds_read_b128 v[242:245], v251 offset:1216
	ds_read_b128 v[246:249], v251 offset:1232
	s_waitcnt lgkmcnt(13)
	v_fma_f32 v33, -v1, v139, v140
	v_fma_f32 v34, -v2, v139, v141
	v_fma_f32 v35, -v3, v139, v142
	ds_read_b128 v[0:3], v251 offset:1248
	s_waitcnt lgkmcnt(13)
	v_fma_f32 v36, -v4, v139, v143
	v_fma_f32 v37, -v5, v139, v144
	v_fma_f32 v38, -v6, v139, v145
	v_fma_f32 v39, -v7, v139, v146
	ds_read_b128 v[4:7], v251 offset:1264
	s_waitcnt lgkmcnt(13)
	v_fma_f32 v40, -v8, v139, v147
	v_fma_f32 v41, -v9, v139, v148
	v_fma_f32 v42, -v10, v139, v149
	v_fma_f32 v43, -v11, v139, v150
	ds_read_b128 v[8:11], v251 offset:1280
	s_waitcnt lgkmcnt(13)
	v_fma_f32 v44, -v12, v139, v151
	v_fma_f32 v45, -v13, v139, v154
	v_fma_f32 v46, -v14, v139, v155
	v_fma_f32 v47, -v15, v139, v156
	ds_read_b128 v[12:15], v251 offset:1296
	s_waitcnt lgkmcnt(13)
	v_fma_f32 v48, -v16, v139, v157
	v_fma_f32 v49, -v17, v139, v158
	v_fma_f32 v50, -v18, v139, v159
	v_fma_f32 v51, -v19, v139, v160
	ds_read_b128 v[16:19], v251 offset:1312
	s_waitcnt lgkmcnt(13)
	v_fma_f32 v52, -v20, v139, v161
	v_fma_f32 v53, -v21, v139, v162
	v_fma_f32 v54, -v22, v139, v163
	v_fma_f32 v55, -v23, v139, v164
	ds_read_b128 v[20:23], v251 offset:1328
	s_waitcnt lgkmcnt(13)
	v_fma_f32 v56, -v24, v139, v165
	v_fma_f32 v57, -v25, v139, v166
	v_fma_f32 v58, -v26, v139, v167
	v_fma_f32 v59, -v27, v139, v168
	ds_read_b128 v[24:27], v251 offset:1344
	s_waitcnt lgkmcnt(13)
	v_fma_f32 v60, -v28, v139, v169
	v_fma_f32 v61, -v29, v139, v170
	v_fma_f32 v62, -v30, v139, v171
	v_fma_f32 v63, -v31, v139, v172
	ds_read_b128 v[28:31], v251 offset:1360
	s_waitcnt lgkmcnt(13)
	v_fma_f32 v64, -v126, v139, v173
	v_fma_f32 v65, -v127, v139, v174
	v_fma_f32 v66, -v128, v139, v175
	v_fma_f32 v67, -v129, v139, v176
	ds_read_b128 v[126:129], v251 offset:1376
	s_waitcnt lgkmcnt(13)
	v_fma_f32 v68, -v230, v139, v177
	v_fma_f32 v69, -v231, v139, v178
	v_fma_f32 v70, -v232, v139, v179
	v_fma_f32 v71, -v233, v139, v180
	ds_read_b128 v[230:233], v251 offset:1392
	s_waitcnt lgkmcnt(13)
	v_fma_f32 v72, -v234, v139, v181
	v_fma_f32 v73, -v235, v139, v182
	v_fma_f32 v74, -v236, v139, v183
	v_fma_f32 v75, -v237, v139, v184
	ds_read_b128 v[234:237], v251 offset:1408
	s_waitcnt lgkmcnt(13)
	v_fma_f32 v76, -v238, v139, v185
	v_fma_f32 v77, -v239, v139, v186
	v_fma_f32 v78, -v240, v139, v187
	v_fma_f32 v79, -v241, v139, v188
	ds_read_b128 v[238:241], v251 offset:1424
	s_waitcnt lgkmcnt(13)
	v_fma_f32 v80, -v242, v139, v189
	v_fma_f32 v81, -v243, v139, v190
	v_fma_f32 v82, -v244, v139, v191
	v_fma_f32 v83, -v245, v139, v192
	ds_read_b128 v[242:245], v251 offset:1440
	s_waitcnt lgkmcnt(13)
	v_fma_f32 v84, -v246, v139, v193
	v_fma_f32 v85, -v247, v139, v194
	v_fma_f32 v86, -v248, v139, v195
	v_fma_f32 v87, -v249, v139, v196
	ds_read_b128 v[246:249], v251 offset:1456
	s_waitcnt lgkmcnt(13)
	v_fma_f32 v88, -v0, v139, v197
	v_fma_f32 v89, -v1, v139, v198
	v_fma_f32 v90, -v2, v139, v199
	v_fma_f32 v91, -v3, v139, v200
	ds_read_b128 v[0:3], v251 offset:1472
	s_waitcnt lgkmcnt(13)
	v_fma_f32 v92, -v4, v139, v201
	v_fma_f32 v93, -v5, v139, v202
	v_fma_f32 v94, -v6, v139, v203
	v_fma_f32 v95, -v7, v139, v204
	ds_read_b128 v[4:7], v251 offset:1488
	s_waitcnt lgkmcnt(13)
	v_pk_fma_f32 v[34:35], v[10:11], v[32:33], v[34:35] op_sel:[0,1,0] op_sel_hi:[1,1,1] neg_lo:[1,0,0] neg_hi:[1,0,0]
	ds_read_b128 v[8:11], v251 offset:1504
	s_waitcnt lgkmcnt(13)
	v_pk_fma_f32 v[36:37], v[12:13], v[32:33], v[36:37] op_sel:[0,1,0] op_sel_hi:[1,1,1] neg_lo:[1,0,0] neg_hi:[1,0,0]
	v_pk_fma_f32 v[38:39], v[14:15], v[32:33], v[38:39] op_sel:[0,1,0] op_sel_hi:[1,1,1] neg_lo:[1,0,0] neg_hi:[1,0,0]
	ds_read_b128 v[12:15], v251 offset:1520
	s_waitcnt lgkmcnt(13)
	v_pk_fma_f32 v[40:41], v[16:17], v[32:33], v[40:41] op_sel:[0,1,0] op_sel_hi:[1,1,1] neg_lo:[1,0,0] neg_hi:[1,0,0]
	v_pk_fma_f32 v[42:43], v[18:19], v[32:33], v[42:43] op_sel:[0,1,0] op_sel_hi:[1,1,1] neg_lo:[1,0,0] neg_hi:[1,0,0]
	ds_read_b128 v[16:19], v251 offset:1536
	s_waitcnt lgkmcnt(13)
	v_pk_fma_f32 v[44:45], v[20:21], v[32:33], v[44:45] op_sel:[0,1,0] op_sel_hi:[1,1,1] neg_lo:[1,0,0] neg_hi:[1,0,0]
	v_pk_fma_f32 v[46:47], v[22:23], v[32:33], v[46:47] op_sel:[0,1,0] op_sel_hi:[1,1,1] neg_lo:[1,0,0] neg_hi:[1,0,0]
	ds_read_b128 v[20:23], v251 offset:1552
	s_waitcnt lgkmcnt(13)
	v_pk_fma_f32 v[48:49], v[24:25], v[32:33], v[48:49] op_sel:[0,1,0] op_sel_hi:[1,1,1] neg_lo:[1,0,0] neg_hi:[1,0,0]
	v_pk_fma_f32 v[50:51], v[26:27], v[32:33], v[50:51] op_sel:[0,1,0] op_sel_hi:[1,1,1] neg_lo:[1,0,0] neg_hi:[1,0,0]
	ds_read_b128 v[24:27], v251 offset:1568
	s_waitcnt lgkmcnt(13)
	v_pk_fma_f32 v[52:53], v[28:29], v[32:33], v[52:53] op_sel:[0,1,0] op_sel_hi:[1,1,1] neg_lo:[1,0,0] neg_hi:[1,0,0]
	v_pk_fma_f32 v[54:55], v[30:31], v[32:33], v[54:55] op_sel:[0,1,0] op_sel_hi:[1,1,1] neg_lo:[1,0,0] neg_hi:[1,0,0]
	ds_read_b128 v[28:31], v251 offset:1584
	s_waitcnt lgkmcnt(13)
; #define PG8_LAS __attribute__((address_space(3)))
; __device__ __forceinline__ void solve64(float (&x)[64], const PG8_LAS float* sLt) {
;     f32x4 cur[16];
; #pragma unroll
;     for (int i4 = 0; i4 < 16; ++i4) cur[i4] = *(const PG8_LAS f32x4*)(sLt + 4 * i4);
;     asm volatile("" ::: "memory");
; #pragma unroll
;     for (int j = 0; j < 63; ++j) {
;         const float xj = x[j];
; #pragma unroll
;         for (int i4 = (j + 1) / 4; i4 < 16; ++i4) {
;             if (4 * i4 + 0 > j) x[4 * i4 + 0] -= cur[i4][0] * xj;
;             if (4 * i4 + 1 > j) x[4 * i4 + 1] -= cur[i4][1] * xj;
;             if (4 * i4 + 2 > j) x[4 * i4 + 2] -= cur[i4][2] * xj;
;             if (4 * i4 + 3 > j) x[4 * i4 + 3] -= cur[i4][3] * xj;
;             if (j + 1 < 63 && i4 >= (j + 2) / 4) cur[i4] = *(const PG8_LAS f32x4*)(sLt + (j + 1) * 64 + 4 * i4); }
;         asm volatile("" ::: "memory");
;     }
	v_pk_fma_f32 v[56:57], v[126:127], v[32:33], v[56:57] op_sel:[0,1,0] op_sel_hi:[1,1,1] neg_lo:[1,0,0] neg_hi:[1,0,0]
	v_pk_fma_f32 v[58:59], v[128:129], v[32:33], v[58:59] op_sel:[0,1,0] op_sel_hi:[1,1,1] neg_lo:[1,0,0] neg_hi:[1,0,0]
	ds_read_b128 v[126:129], v251 offset:1600
	s_waitcnt lgkmcnt(13)
	v_pk_fma_f32 v[60:61], v[230:231], v[32:33], v[60:61] op_sel:[0,1,0] op_sel_hi:[1,1,1] neg_lo:[1,0,0] neg_hi:[1,0,0]
	v_pk_fma_f32 v[62:63], v[232:233], v[32:33], v[62:63] op_sel:[0,1,0] op_sel_hi:[1,1,1] neg_lo:[1,0,0] neg_hi:[1,0,0]
	ds_read_b128 v[230:233], v251 offset:1616
	s_waitcnt lgkmcnt(13)
	v_pk_fma_f32 v[64:65], v[234:235], v[32:33], v[64:65] op_sel:[0,1,0] op_sel_hi:[1,1,1] neg_lo:[1,0,0] neg_hi:[1,0,0]
	v_pk_fma_f32 v[66:67], v[236:237], v[32:33], v[66:67] op_sel:[0,1,0] op_sel_hi:[1,1,1] neg_lo:[1,0,0] neg_hi:[1,0,0]
	ds_read_b128 v[234:237], v251 offset:1632
	s_waitcnt lgkmcnt(13)
	v_pk_fma_f32 v[68:69], v[238:239], v[32:33], v[68:69] op_sel:[0,1,0] op_sel_hi:[1,1,1] neg_lo:[1,0,0] neg_hi:[1,0,0]
	v_pk_fma_f32 v[70:71], v[240:241], v[32:33], v[70:71] op_sel:[0,1,0] op_sel_hi:[1,1,1] neg_lo:[1,0,0] neg_hi:[1,0,0]
	ds_read_b128 v[238:241], v251 offset:1648
	s_waitcnt lgkmcnt(13)
	v_pk_fma_f32 v[72:73], v[242:243], v[32:33], v[72:73] op_sel:[0,1,0] op_sel_hi:[1,1,1] neg_lo:[1,0,0] neg_hi:[1,0,0]
	v_pk_fma_f32 v[74:75], v[244:245], v[32:33], v[74:75] op_sel:[0,1,0] op_sel_hi:[1,1,1] neg_lo:[1,0,0] neg_hi:[1,0,0]
	ds_read_b128 v[242:245], v251 offset:1664
	s_waitcnt lgkmcnt(13)
	v_pk_fma_f32 v[76:77], v[246:247], v[32:33], v[76:77] op_sel:[0,1,0] op_sel_hi:[1,1,1] neg_lo:[1,0,0] neg_hi:[1,0,0]
	v_pk_fma_f32 v[78:79], v[248:249], v[32:33], v[78:79] op_sel:[0,1,0] op_sel_hi:[1,1,1] neg_lo:[1,0,0] neg_hi:[1,0,0]
	ds_read_b128 v[246:249], v251 offset:1680
	s_waitcnt lgkmcnt(13)
	v_pk_fma_f32 v[80:81], v[0:1], v[32:33], v[80:81] op_sel:[0,1,0] op_sel_hi:[1,1,1] neg_lo:[1,0,0] neg_hi:[1,0,0]
	v_pk_fma_f32 v[82:83], v[2:3], v[32:33], v[82:83] op_sel:[0,1,0] op_sel_hi:[1,1,1] neg_lo:[1,0,0] neg_hi:[1,0,0]
	ds_read_b128 v[0:3], v251 offset:1696
	s_waitcnt lgkmcnt(13)
	v_pk_fma_f32 v[84:85], v[4:5], v[32:33], v[84:85] op_sel:[0,1,0] op_sel_hi:[1,1,1] neg_lo:[1,0,0] neg_hi:[1,0,0]
	v_pk_fma_f32 v[86:87], v[6:7], v[32:33], v[86:87] op_sel:[0,1,0] op_sel_hi:[1,1,1] neg_lo:[1,0,0] neg_hi:[1,0,0]
	ds_read_b128 v[4:7], v251 offset:1712
	s_waitcnt lgkmcnt(13)
	v_pk_fma_f32 v[88:89], v[8:9], v[32:33], v[88:89] op_sel:[0,1,0] op_sel_hi:[1,1,1] neg_lo:[1,0,0] neg_hi:[1,0,0]
	v_pk_fma_f32 v[90:91], v[10:11], v[32:33], v[90:91] op_sel:[0,1,0] op_sel_hi:[1,1,1] neg_lo:[1,0,0] neg_hi:[1,0,0]
	ds_read_b128 v[8:11], v251 offset:1728
	s_waitcnt lgkmcnt(13)
	v_pk_fma_f32 v[92:93], v[12:13], v[32:33], v[92:93] op_sel:[0,1,0] op_sel_hi:[1,1,1] neg_lo:[1,0,0] neg_hi:[1,0,0]
	v_pk_fma_f32 v[94:95], v[14:15], v[32:33], v[94:95] op_sel:[0,1,0] op_sel_hi:[1,1,1] neg_lo:[1,0,0] neg_hi:[1,0,0]
	ds_read_b128 v[12:15], v251 offset:1744
	s_waitcnt lgkmcnt(13)
	v_fma_f32 v35, -v19, v34, v35
	ds_read_b128 v[16:19], v251 offset:1760
	s_waitcnt lgkmcnt(13)
	v_pk_fma_f32 v[36:37], v[20:21], v[34:35], v[36:37] op_sel:[0,0,0] op_sel_hi:[1,0,1] neg_lo:[1,0,0] neg_hi:[1,0,0]
	v_pk_fma_f32 v[38:39], v[22:23], v[34:35], v[38:39] op_sel:[0,0,0] op_sel_hi:[1,0,1] neg_lo:[1,0,0] neg_hi:[1,0,0]
	ds_read_b128 v[20:23], v251 offset:1776
	s_waitcnt lgkmcnt(13)
	v_pk_fma_f32 v[40:41], v[24:25], v[34:35], v[40:41] op_sel:[0,0,0] op_sel_hi:[1,0,1] neg_lo:[1,0,0] neg_hi:[1,0,0]
	v_pk_fma_f32 v[42:43], v[26:27], v[34:35], v[42:43] op_sel:[0,0,0] op_sel_hi:[1,0,1] neg_lo:[1,0,0] neg_hi:[1,0,0]
	ds_read_b128 v[24:27], v251 offset:1808
	s_waitcnt lgkmcnt(13)
	v_pk_fma_f32 v[44:45], v[28:29], v[34:35], v[44:45] op_sel:[0,0,0] op_sel_hi:[1,0,1] neg_lo:[1,0,0] neg_hi:[1,0,0]
	v_pk_fma_f32 v[46:47], v[30:31], v[34:35], v[46:47] op_sel:[0,0,0] op_sel_hi:[1,0,1] neg_lo:[1,0,0] neg_hi:[1,0,0]
	ds_read_b128 v[28:31], v251 offset:1824
	s_waitcnt lgkmcnt(13)
	v_pk_fma_f32 v[48:49], v[126:127], v[34:35], v[48:49] op_sel:[0,0,0] op_sel_hi:[1,0,1] neg_lo:[1,0,0] neg_hi:[1,0,0]
	v_pk_fma_f32 v[50:51], v[128:129], v[34:35], v[50:51] op_sel:[0,0,0] op_sel_hi:[1,0,1] neg_lo:[1,0,0] neg_hi:[1,0,0]
	ds_read_b128 v[126:129], v251 offset:1840
	s_waitcnt lgkmcnt(13)
	v_pk_fma_f32 v[52:53], v[230:231], v[34:35], v[52:53] op_sel:[0,0,0] op_sel_hi:[1,0,1] neg_lo:[1,0,0] neg_hi:[1,0,0]
	v_pk_fma_f32 v[54:55], v[232:233], v[34:35], v[54:55] op_sel:[0,0,0] op_sel_hi:[1,0,1] neg_lo:[1,0,0] neg_hi:[1,0,0]
	ds_read_b128 v[230:233], v251 offset:1856
	s_waitcnt lgkmcnt(13)
	v_pk_fma_f32 v[56:57], v[234:235], v[34:35], v[56:57] op_sel:[0,0,0] op_sel_hi:[1,0,1] neg_lo:[1,0,0] neg_hi:[1,0,0]
	v_pk_fma_f32 v[58:59], v[236:237], v[34:35], v[58:59] op_sel:[0,0,0] op_sel_hi:[1,0,1] neg_lo:[1,0,0] neg_hi:[1,0,0]
	ds_read_b128 v[234:237], v251 offset:1872
	s_waitcnt lgkmcnt(13)
	v_pk_fma_f32 v[60:61], v[238:239], v[34:35], v[60:61] op_sel:[0,0,0] op_sel_hi:[1,0,1] neg_lo:[1,0,0] neg_hi:[1,0,0]
	v_pk_fma_f32 v[62:63], v[240:241], v[34:35], v[62:63] op_sel:[0,0,0] op_sel_hi:[1,0,1] neg_lo:[1,0,0] neg_hi:[1,0,0]
	ds_read_b128 v[238:241], v251 offset:1888
	s_waitcnt lgkmcnt(13)
	v_pk_fma_f32 v[64:65], v[242:243], v[34:35], v[64:65] op_sel:[0,0,0] op_sel_hi:[1,0,1] neg_lo:[1,0,0] neg_hi:[1,0,0]
	v_pk_fma_f32 v[66:67], v[244:245], v[34:35], v[66:67] op_sel:[0,0,0] op_sel_hi:[1,0,1] neg_lo:[1,0,0] neg_hi:[1,0,0]
	ds_read_b128 v[242:245], v251 offset:1904
	s_waitcnt lgkmcnt(13)
	v_pk_fma_f32 v[68:69], v[246:247], v[34:35], v[68:69] op_sel:[0,0,0] op_sel_hi:[1,0,1] neg_lo:[1,0,0] neg_hi:[1,0,0]
	v_pk_fma_f32 v[70:71], v[248:249], v[34:35], v[70:71] op_sel:[0,0,0] op_sel_hi:[1,0,1] neg_lo:[1,0,0] neg_hi:[1,0,0]
	ds_read_b128 v[246:249], v251 offset:1920
	s_waitcnt lgkmcnt(13)
; #define PG8_LAS __attribute__((address_space(3)))
; __device__ __forceinline__ void solve64(float (&x)[64], const PG8_LAS float* sLt) {
;     f32x4 cur[16];
; #pragma unroll
;     for (int i4 = 0; i4 < 16; ++i4) cur[i4] = *(const PG8_LAS f32x4*)(sLt + 4 * i4);
;     asm volatile("" ::: "memory");
; #pragma unroll
;     for (int j = 0; j < 63; ++j) {
;         const float xj = x[j];
; #pragma unroll
;         for (int i4 = (j + 1) / 4; i4 < 16; ++i4) {
;             if (4 * i4 + 0 > j) x[4 * i4 + 0] -= cur[i4][0] * xj;
;             if (4 * i4 + 1 > j) x[4 * i4 + 1] -= cur[i4][1] * xj;
;             if (4 * i4 + 2 > j) x[4 * i4 + 2] -= cur[i4][2] * xj;
;             if (4 * i4 + 3 > j) x[4 * i4 + 3] -= cur[i4][3] * xj;
;             if (j + 1 < 63 && i4 >= (j + 2) / 4) cur[i4] = *(const PG8_LAS f32x4*)(sLt + (j + 1) * 64 + 4 * i4); }
;         asm volatile("" ::: "memory");
;     }
	v_pk_fma_f32 v[72:73], v[0:1], v[34:35], v[72:73] op_sel:[0,0,0] op_sel_hi:[1,0,1] neg_lo:[1,0,0] neg_hi:[1,0,0]
	v_pk_fma_f32 v[74:75], v[2:3], v[34:35], v[74:75] op_sel:[0,0,0] op_sel_hi:[1,0,1] neg_lo:[1,0,0] neg_hi:[1,0,0]
	ds_read_b128 v[0:3], v251 offset:1936
	s_waitcnt lgkmcnt(13)
	v_pk_fma_f32 v[76:77], v[4:5], v[34:35], v[76:77] op_sel:[0,0,0] op_sel_hi:[1,0,1] neg_lo:[1,0,0] neg_hi:[1,0,0]
	v_pk_fma_f32 v[78:79], v[6:7], v[34:35], v[78:79] op_sel:[0,0,0] op_sel_hi:[1,0,1] neg_lo:[1,0,0] neg_hi:[1,0,0]
	ds_read_b128 v[4:7], v251 offset:1952
	s_waitcnt lgkmcnt(13)
	v_pk_fma_f32 v[80:81], v[8:9], v[34:35], v[80:81] op_sel:[0,0,0] op_sel_hi:[1,0,1] neg_lo:[1,0,0] neg_hi:[1,0,0]
	v_pk_fma_f32 v[82:83], v[10:11], v[34:35], v[82:83] op_sel:[0,0,0] op_sel_hi:[1,0,1] neg_lo:[1,0,0] neg_hi:[1,0,0]
	ds_read_b128 v[8:11], v251 offset:1968
	s_waitcnt lgkmcnt(13)
	v_pk_fma_f32 v[84:85], v[12:13], v[34:35], v[84:85] op_sel:[0,0,0] op_sel_hi:[1,0,1] neg_lo:[1,0,0] neg_hi:[1,0,0]
	v_pk_fma_f32 v[86:87], v[14:15], v[34:35], v[86:87] op_sel:[0,0,0] op_sel_hi:[1,0,1] neg_lo:[1,0,0] neg_hi:[1,0,0]
	ds_read_b128 v[12:15], v251 offset:1984
	s_waitcnt lgkmcnt(13)
	v_pk_fma_f32 v[88:89], v[16:17], v[34:35], v[88:89] op_sel:[0,0,0] op_sel_hi:[1,0,1] neg_lo:[1,0,0] neg_hi:[1,0,0]
	v_pk_fma_f32 v[90:91], v[18:19], v[34:35], v[90:91] op_sel:[0,0,0] op_sel_hi:[1,0,1] neg_lo:[1,0,0] neg_hi:[1,0,0]
	ds_read_b128 v[16:19], v251 offset:2000
	s_waitcnt lgkmcnt(13)
	v_pk_fma_f32 v[92:93], v[20:21], v[34:35], v[92:93] op_sel:[0,0,0] op_sel_hi:[1,0,1] neg_lo:[1,0,0] neg_hi:[1,0,0]
	v_pk_fma_f32 v[94:95], v[22:23], v[34:35], v[94:95] op_sel:[0,0,0] op_sel_hi:[1,0,1] neg_lo:[1,0,0] neg_hi:[1,0,0]
	ds_read_b128 v[20:23], v251 offset:2016
	s_waitcnt lgkmcnt(13)
	v_pk_fma_f32 v[36:37], v[24:25], v[34:35], v[36:37] op_sel:[0,1,0] op_sel_hi:[1,1,1] neg_lo:[1,0,0] neg_hi:[1,0,0]
	v_pk_fma_f32 v[38:39], v[26:27], v[34:35], v[38:39] op_sel:[0,1,0] op_sel_hi:[1,1,1] neg_lo:[1,0,0] neg_hi:[1,0,0]
	ds_read_b128 v[24:27], v251 offset:2032
	s_waitcnt lgkmcnt(13)
	v_pk_fma_f32 v[40:41], v[28:29], v[34:35], v[40:41] op_sel:[0,1,0] op_sel_hi:[1,1,1] neg_lo:[1,0,0] neg_hi:[1,0,0]
	v_pk_fma_f32 v[42:43], v[30:31], v[34:35], v[42:43] op_sel:[0,1,0] op_sel_hi:[1,1,1] neg_lo:[1,0,0] neg_hi:[1,0,0]
	ds_read_b128 v[28:31], v251 offset:2064
	s_waitcnt lgkmcnt(13)
	v_pk_fma_f32 v[44:45], v[126:127], v[34:35], v[44:45] op_sel:[0,1,0] op_sel_hi:[1,1,1] neg_lo:[1,0,0] neg_hi:[1,0,0]
	v_pk_fma_f32 v[46:47], v[128:129], v[34:35], v[46:47] op_sel:[0,1,0] op_sel_hi:[1,1,1] neg_lo:[1,0,0] neg_hi:[1,0,0]
	ds_read_b128 v[126:129], v251 offset:2080
	s_waitcnt lgkmcnt(13)
	v_pk_fma_f32 v[48:49], v[230:231], v[34:35], v[48:49] op_sel:[0,1,0] op_sel_hi:[1,1,1] neg_lo:[1,0,0] neg_hi:[1,0,0]
	v_pk_fma_f32 v[50:51], v[232:233], v[34:35], v[50:51] op_sel:[0,1,0] op_sel_hi:[1,1,1] neg_lo:[1,0,0] neg_hi:[1,0,0]
	ds_read_b128 v[230:233], v251 offset:2096
	s_waitcnt lgkmcnt(13)
	v_pk_fma_f32 v[52:53], v[234:235], v[34:35], v[52:53] op_sel:[0,1,0] op_sel_hi:[1,1,1] neg_lo:[1,0,0] neg_hi:[1,0,0]
	v_pk_fma_f32 v[54:55], v[236:237], v[34:35], v[54:55] op_sel:[0,1,0] op_sel_hi:[1,1,1] neg_lo:[1,0,0] neg_hi:[1,0,0]
	ds_read_b128 v[234:237], v251 offset:2112
	s_waitcnt lgkmcnt(13)
	v_pk_fma_f32 v[56:57], v[238:239], v[34:35], v[56:57] op_sel:[0,1,0] op_sel_hi:[1,1,1] neg_lo:[1,0,0] neg_hi:[1,0,0]
	v_pk_fma_f32 v[58:59], v[240:241], v[34:35], v[58:59] op_sel:[0,1,0] op_sel_hi:[1,1,1] neg_lo:[1,0,0] neg_hi:[1,0,0]
	ds_read_b128 v[238:241], v251 offset:2128
	s_waitcnt lgkmcnt(13)
	v_pk_fma_f32 v[60:61], v[242:243], v[34:35], v[60:61] op_sel:[0,1,0] op_sel_hi:[1,1,1] neg_lo:[1,0,0] neg_hi:[1,0,0]
	v_pk_fma_f32 v[62:63], v[244:245], v[34:35], v[62:63] op_sel:[0,1,0] op_sel_hi:[1,1,1] neg_lo:[1,0,0] neg_hi:[1,0,0]
	ds_read_b128 v[242:245], v251 offset:2144
	s_waitcnt lgkmcnt(13)
	v_pk_fma_f32 v[64:65], v[246:247], v[34:35], v[64:65] op_sel:[0,1,0] op_sel_hi:[1,1,1] neg_lo:[1,0,0] neg_hi:[1,0,0]
	v_pk_fma_f32 v[66:67], v[248:249], v[34:35], v[66:67] op_sel:[0,1,0] op_sel_hi:[1,1,1] neg_lo:[1,0,0] neg_hi:[1,0,0]
	ds_read_b128 v[246:249], v251 offset:2160
	s_waitcnt lgkmcnt(13)
	v_pk_fma_f32 v[68:69], v[0:1], v[34:35], v[68:69] op_sel:[0,1,0] op_sel_hi:[1,1,1] neg_lo:[1,0,0] neg_hi:[1,0,0]
	v_pk_fma_f32 v[70:71], v[2:3], v[34:35], v[70:71] op_sel:[0,1,0] op_sel_hi:[1,1,1] neg_lo:[1,0,0] neg_hi:[1,0,0]
	ds_read_b128 v[0:3], v251 offset:2176
	s_waitcnt lgkmcnt(13)
	v_pk_fma_f32 v[72:73], v[4:5], v[34:35], v[72:73] op_sel:[0,1,0] op_sel_hi:[1,1,1] neg_lo:[1,0,0] neg_hi:[1,0,0]
	v_pk_fma_f32 v[74:75], v[6:7], v[34:35], v[74:75] op_sel:[0,1,0] op_sel_hi:[1,1,1] neg_lo:[1,0,0] neg_hi:[1,0,0]
	ds_read_b128 v[4:7], v251 offset:2192
	s_waitcnt lgkmcnt(13)
	v_pk_fma_f32 v[76:77], v[8:9], v[34:35], v[76:77] op_sel:[0,1,0] op_sel_hi:[1,1,1] neg_lo:[1,0,0] neg_hi:[1,0,0]
	v_pk_fma_f32 v[78:79], v[10:11], v[34:35], v[78:79] op_sel:[0,1,0] op_sel_hi:[1,1,1] neg_lo:[1,0,0] neg_hi:[1,0,0]
	ds_read_b128 v[8:11], v251 offset:2208
	s_waitcnt lgkmcnt(13)
	v_pk_fma_f32 v[80:81], v[12:13], v[34:35], v[80:81] op_sel:[0,1,0] op_sel_hi:[1,1,1] neg_lo:[1,0,0] neg_hi:[1,0,0]
	v_pk_fma_f32 v[82:83], v[14:15], v[34:35], v[82:83] op_sel:[0,1,0] op_sel_hi:[1,1,1] neg_lo:[1,0,0] neg_hi:[1,0,0]
	ds_read_b128 v[12:15], v251 offset:2224
	s_waitcnt lgkmcnt(13)
	v_pk_fma_f32 v[84:85], v[16:17], v[34:35], v[84:85] op_sel:[0,1,0] op_sel_hi:[1,1,1] neg_lo:[1,0,0] neg_hi:[1,0,0]
	v_pk_fma_f32 v[86:87], v[18:19], v[34:35], v[86:87] op_sel:[0,1,0] op_sel_hi:[1,1,1] neg_lo:[1,0,0] neg_hi:[1,0,0]
	ds_read_b128 v[16:19], v251 offset:2240
	s_waitcnt lgkmcnt(13)
; #define PG8_LAS __attribute__((address_space(3)))
; __device__ __forceinline__ void solve64(float (&x)[64], const PG8_LAS float* sLt) {
;     f32x4 cur[16];
; #pragma unroll
;     for (int i4 = 0; i4 < 16; ++i4) cur[i4] = *(const PG8_LAS f32x4*)(sLt + 4 * i4);
;     asm volatile("" ::: "memory");
; #pragma unroll
;     for (int j = 0; j < 63; ++j) {
;         const float xj = x[j];
; #pragma unroll
;         for (int i4 = (j + 1) / 4; i4 < 16; ++i4) {
;             if (4 * i4 + 0 > j) x[4 * i4 + 0] -= cur[i4][0] * xj;
;             if (4 * i4 + 1 > j) x[4 * i4 + 1] -= cur[i4][1] * xj;
;             if (4 * i4 + 2 > j) x[4 * i4 + 2] -= cur[i4][2] * xj;
;             if (4 * i4 + 3 > j) x[4 * i4 + 3] -= cur[i4][3] * xj;
;             if (j + 1 < 63 && i4 >= (j + 2) / 4) cur[i4] = *(const PG8_LAS f32x4*)(sLt + (j + 1) * 64 + 4 * i4); }
;         asm volatile("" ::: "memory");
;     }
	v_pk_fma_f32 v[88:89], v[20:21], v[34:35], v[88:89] op_sel:[0,1,0] op_sel_hi:[1,1,1] neg_lo:[1,0,0] neg_hi:[1,0,0]
	v_pk_fma_f32 v[90:91], v[22:23], v[34:35], v[90:91] op_sel:[0,1,0] op_sel_hi:[1,1,1] neg_lo:[1,0,0] neg_hi:[1,0,0]
	ds_read_b128 v[20:23], v251 offset:2256
	s_waitcnt lgkmcnt(13)
	v_pk_fma_f32 v[92:93], v[24:25], v[34:35], v[92:93] op_sel:[0,1,0] op_sel_hi:[1,1,1] neg_lo:[1,0,0] neg_hi:[1,0,0]
	v_pk_fma_f32 v[94:95], v[26:27], v[34:35], v[94:95] op_sel:[0,1,0] op_sel_hi:[1,1,1] neg_lo:[1,0,0] neg_hi:[1,0,0]
	ds_read_b128 v[24:27], v251 offset:2272
	s_waitcnt lgkmcnt(13)
	v_fma_f32 v37, -v29, v36, v37
	v_pk_fma_f32 v[38:39], v[30:31], v[36:37], v[38:39] op_sel:[0,0,0] op_sel_hi:[1,0,1] neg_lo:[1,0,0] neg_hi:[1,0,0]
	ds_read_b128 v[28:31], v251 offset:2288
	s_waitcnt lgkmcnt(13)
	v_pk_fma_f32 v[40:41], v[126:127], v[36:37], v[40:41] op_sel:[0,0,0] op_sel_hi:[1,0,1] neg_lo:[1,0,0] neg_hi:[1,0,0]
	v_pk_fma_f32 v[42:43], v[128:129], v[36:37], v[42:43] op_sel:[0,0,0] op_sel_hi:[1,0,1] neg_lo:[1,0,0] neg_hi:[1,0,0]
	ds_read_b128 v[126:129], v251 offset:2320
	s_waitcnt lgkmcnt(13)
	v_pk_fma_f32 v[44:45], v[230:231], v[36:37], v[44:45] op_sel:[0,0,0] op_sel_hi:[1,0,1] neg_lo:[1,0,0] neg_hi:[1,0,0]
	v_pk_fma_f32 v[46:47], v[232:233], v[36:37], v[46:47] op_sel:[0,0,0] op_sel_hi:[1,0,1] neg_lo:[1,0,0] neg_hi:[1,0,0]
	ds_read_b128 v[230:233], v251 offset:2336
	s_waitcnt lgkmcnt(13)
	v_pk_fma_f32 v[48:49], v[234:235], v[36:37], v[48:49] op_sel:[0,0,0] op_sel_hi:[1,0,1] neg_lo:[1,0,0] neg_hi:[1,0,0]
	v_pk_fma_f32 v[50:51], v[236:237], v[36:37], v[50:51] op_sel:[0,0,0] op_sel_hi:[1,0,1] neg_lo:[1,0,0] neg_hi:[1,0,0]
	ds_read_b128 v[234:237], v251 offset:2352
	s_waitcnt lgkmcnt(13)
	v_pk_fma_f32 v[52:53], v[238:239], v[36:37], v[52:53] op_sel:[0,0,0] op_sel_hi:[1,0,1] neg_lo:[1,0,0] neg_hi:[1,0,0]
	v_pk_fma_f32 v[54:55], v[240:241], v[36:37], v[54:55] op_sel:[0,0,0] op_sel_hi:[1,0,1] neg_lo:[1,0,0] neg_hi:[1,0,0]
	ds_read_b128 v[238:241], v251 offset:2368
	s_waitcnt lgkmcnt(13)
	v_pk_fma_f32 v[56:57], v[242:243], v[36:37], v[56:57] op_sel:[0,0,0] op_sel_hi:[1,0,1] neg_lo:[1,0,0] neg_hi:[1,0,0]
	v_pk_fma_f32 v[58:59], v[244:245], v[36:37], v[58:59] op_sel:[0,0,0] op_sel_hi:[1,0,1] neg_lo:[1,0,0] neg_hi:[1,0,0]
	ds_read_b128 v[242:245], v251 offset:2384
	s_waitcnt lgkmcnt(13)
	v_pk_fma_f32 v[60:61], v[246:247], v[36:37], v[60:61] op_sel:[0,0,0] op_sel_hi:[1,0,1] neg_lo:[1,0,0] neg_hi:[1,0,0]
	v_pk_fma_f32 v[62:63], v[248:249], v[36:37], v[62:63] op_sel:[0,0,0] op_sel_hi:[1,0,1] neg_lo:[1,0,0] neg_hi:[1,0,0]
	ds_read_b128 v[246:249], v251 offset:2400
	s_waitcnt lgkmcnt(13)
	v_pk_fma_f32 v[64:65], v[0:1], v[36:37], v[64:65] op_sel:[0,0,0] op_sel_hi:[1,0,1] neg_lo:[1,0,0] neg_hi:[1,0,0]
	v_pk_fma_f32 v[66:67], v[2:3], v[36:37], v[66:67] op_sel:[0,0,0] op_sel_hi:[1,0,1] neg_lo:[1,0,0] neg_hi:[1,0,0]
	ds_read_b128 v[0:3], v251 offset:2416
	s_waitcnt lgkmcnt(13)
	v_pk_fma_f32 v[68:69], v[4:5], v[36:37], v[68:69] op_sel:[0,0,0] op_sel_hi:[1,0,1] neg_lo:[1,0,0] neg_hi:[1,0,0]
	v_pk_fma_f32 v[70:71], v[6:7], v[36:37], v[70:71] op_sel:[0,0,0] op_sel_hi:[1,0,1] neg_lo:[1,0,0] neg_hi:[1,0,0]
	ds_read_b128 v[4:7], v251 offset:2432
	s_waitcnt lgkmcnt(13)
	v_pk_fma_f32 v[72:73], v[8:9], v[36:37], v[72:73] op_sel:[0,0,0] op_sel_hi:[1,0,1] neg_lo:[1,0,0] neg_hi:[1,0,0]
	v_pk_fma_f32 v[74:75], v[10:11], v[36:37], v[74:75] op_sel:[0,0,0] op_sel_hi:[1,0,1] neg_lo:[1,0,0] neg_hi:[1,0,0]
	ds_read_b128 v[8:11], v251 offset:2448
	s_waitcnt lgkmcnt(13)
	v_pk_fma_f32 v[76:77], v[12:13], v[36:37], v[76:77] op_sel:[0,0,0] op_sel_hi:[1,0,1] neg_lo:[1,0,0] neg_hi:[1,0,0]
	v_pk_fma_f32 v[78:79], v[14:15], v[36:37], v[78:79] op_sel:[0,0,0] op_sel_hi:[1,0,1] neg_lo:[1,0,0] neg_hi:[1,0,0]
	ds_read_b128 v[12:15], v251 offset:2464
	s_waitcnt lgkmcnt(13)
	v_pk_fma_f32 v[80:81], v[16:17], v[36:37], v[80:81] op_sel:[0,0,0] op_sel_hi:[1,0,1] neg_lo:[1,0,0] neg_hi:[1,0,0]
	v_pk_fma_f32 v[82:83], v[18:19], v[36:37], v[82:83] op_sel:[0,0,0] op_sel_hi:[1,0,1] neg_lo:[1,0,0] neg_hi:[1,0,0]
	ds_read_b128 v[16:19], v251 offset:2480
	s_waitcnt lgkmcnt(13)
	v_pk_fma_f32 v[84:85], v[20:21], v[36:37], v[84:85] op_sel:[0,0,0] op_sel_hi:[1,0,1] neg_lo:[1,0,0] neg_hi:[1,0,0]
	v_pk_fma_f32 v[86:87], v[22:23], v[36:37], v[86:87] op_sel:[0,0,0] op_sel_hi:[1,0,1] neg_lo:[1,0,0] neg_hi:[1,0,0]
	ds_read_b128 v[20:23], v251 offset:2496
	s_waitcnt lgkmcnt(13)
	v_pk_fma_f32 v[88:89], v[24:25], v[36:37], v[88:89] op_sel:[0,0,0] op_sel_hi:[1,0,1] neg_lo:[1,0,0] neg_hi:[1,0,0]
	v_pk_fma_f32 v[90:91], v[26:27], v[36:37], v[90:91] op_sel:[0,0,0] op_sel_hi:[1,0,1] neg_lo:[1,0,0] neg_hi:[1,0,0]
	ds_read_b128 v[24:27], v251 offset:2512
	s_waitcnt lgkmcnt(13)
	v_pk_fma_f32 v[92:93], v[28:29], v[36:37], v[92:93] op_sel:[0,0,0] op_sel_hi:[1,0,1] neg_lo:[1,0,0] neg_hi:[1,0,0]
	v_pk_fma_f32 v[94:95], v[30:31], v[36:37], v[94:95] op_sel:[0,0,0] op_sel_hi:[1,0,1] neg_lo:[1,0,0] neg_hi:[1,0,0]
	ds_read_b128 v[28:31], v251 offset:2528
	s_waitcnt lgkmcnt(13)
	v_pk_fma_f32 v[38:39], v[128:129], v[36:37], v[38:39] op_sel:[0,1,0] op_sel_hi:[1,1,1] neg_lo:[1,0,0] neg_hi:[1,0,0]
	ds_read_b128 v[126:129], v251 offset:2544
	s_waitcnt lgkmcnt(13)
	v_pk_fma_f32 v[40:41], v[230:231], v[36:37], v[40:41] op_sel:[0,1,0] op_sel_hi:[1,1,1] neg_lo:[1,0,0] neg_hi:[1,0,0]
	v_pk_fma_f32 v[42:43], v[232:233], v[36:37], v[42:43] op_sel:[0,1,0] op_sel_hi:[1,1,1] neg_lo:[1,0,0] neg_hi:[1,0,0]
	ds_read_b128 v[230:233], v251 offset:2576
	s_waitcnt lgkmcnt(13)
	v_pk_fma_f32 v[44:45], v[234:235], v[36:37], v[44:45] op_sel:[0,1,0] op_sel_hi:[1,1,1] neg_lo:[1,0,0] neg_hi:[1,0,0]
	v_pk_fma_f32 v[46:47], v[236:237], v[36:37], v[46:47] op_sel:[0,1,0] op_sel_hi:[1,1,1] neg_lo:[1,0,0] neg_hi:[1,0,0]
	ds_read_b128 v[234:237], v251 offset:2592
	s_waitcnt lgkmcnt(13)
; #define PG8_LAS __attribute__((address_space(3)))
; __device__ __forceinline__ void solve64(float (&x)[64], const PG8_LAS float* sLt) {
;     f32x4 cur[16];
; #pragma unroll
;     for (int i4 = 0; i4 < 16; ++i4) cur[i4] = *(const PG8_LAS f32x4*)(sLt + 4 * i4);
;     asm volatile("" ::: "memory");
; #pragma unroll
;     for (int j = 0; j < 63; ++j) {
;         const float xj = x[j];
; #pragma unroll
;         for (int i4 = (j + 1) / 4; i4 < 16; ++i4) {
;             if (4 * i4 + 0 > j) x[4 * i4 + 0] -= cur[i4][0] * xj;
;             if (4 * i4 + 1 > j) x[4 * i4 + 1] -= cur[i4][1] * xj;
;             if (4 * i4 + 2 > j) x[4 * i4 + 2] -= cur[i4][2] * xj;
;             if (4 * i4 + 3 > j) x[4 * i4 + 3] -= cur[i4][3] * xj;
;             if (j + 1 < 63 && i4 >= (j + 2) / 4) cur[i4] = *(const PG8_LAS f32x4*)(sLt + (j + 1) * 64 + 4 * i4); }
;         asm volatile("" ::: "memory");
;     }
	v_pk_fma_f32 v[48:49], v[238:239], v[36:37], v[48:49] op_sel:[0,1,0] op_sel_hi:[1,1,1] neg_lo:[1,0,0] neg_hi:[1,0,0]
	v_pk_fma_f32 v[50:51], v[240:241], v[36:37], v[50:51] op_sel:[0,1,0] op_sel_hi:[1,1,1] neg_lo:[1,0,0] neg_hi:[1,0,0]
	ds_read_b128 v[238:241], v251 offset:2608
	s_waitcnt lgkmcnt(13)
	v_pk_fma_f32 v[52:53], v[242:243], v[36:37], v[52:53] op_sel:[0,1,0] op_sel_hi:[1,1,1] neg_lo:[1,0,0] neg_hi:[1,0,0]
	v_pk_fma_f32 v[54:55], v[244:245], v[36:37], v[54:55] op_sel:[0,1,0] op_sel_hi:[1,1,1] neg_lo:[1,0,0] neg_hi:[1,0,0]
	ds_read_b128 v[242:245], v251 offset:2624
	s_waitcnt lgkmcnt(13)
	v_pk_fma_f32 v[56:57], v[246:247], v[36:37], v[56:57] op_sel:[0,1,0] op_sel_hi:[1,1,1] neg_lo:[1,0,0] neg_hi:[1,0,0]
	v_pk_fma_f32 v[58:59], v[248:249], v[36:37], v[58:59] op_sel:[0,1,0] op_sel_hi:[1,1,1] neg_lo:[1,0,0] neg_hi:[1,0,0]
	ds_read_b128 v[246:249], v251 offset:2640
	s_waitcnt lgkmcnt(13)
	v_pk_fma_f32 v[60:61], v[0:1], v[36:37], v[60:61] op_sel:[0,1,0] op_sel_hi:[1,1,1] neg_lo:[1,0,0] neg_hi:[1,0,0]
	v_pk_fma_f32 v[62:63], v[2:3], v[36:37], v[62:63] op_sel:[0,1,0] op_sel_hi:[1,1,1] neg_lo:[1,0,0] neg_hi:[1,0,0]
	ds_read_b128 v[0:3], v251 offset:2656
	s_waitcnt lgkmcnt(13)
	v_pk_fma_f32 v[64:65], v[4:5], v[36:37], v[64:65] op_sel:[0,1,0] op_sel_hi:[1,1,1] neg_lo:[1,0,0] neg_hi:[1,0,0]
	v_pk_fma_f32 v[66:67], v[6:7], v[36:37], v[66:67] op_sel:[0,1,0] op_sel_hi:[1,1,1] neg_lo:[1,0,0] neg_hi:[1,0,0]
	ds_read_b128 v[4:7], v251 offset:2672
	s_waitcnt lgkmcnt(13)
	v_pk_fma_f32 v[68:69], v[8:9], v[36:37], v[68:69] op_sel:[0,1,0] op_sel_hi:[1,1,1] neg_lo:[1,0,0] neg_hi:[1,0,0]
	v_pk_fma_f32 v[70:71], v[10:11], v[36:37], v[70:71] op_sel:[0,1,0] op_sel_hi:[1,1,1] neg_lo:[1,0,0] neg_hi:[1,0,0]
	ds_read_b128 v[8:11], v251 offset:2688
	s_waitcnt lgkmcnt(13)
	v_pk_fma_f32 v[72:73], v[12:13], v[36:37], v[72:73] op_sel:[0,1,0] op_sel_hi:[1,1,1] neg_lo:[1,0,0] neg_hi:[1,0,0]
	v_pk_fma_f32 v[74:75], v[14:15], v[36:37], v[74:75] op_sel:[0,1,0] op_sel_hi:[1,1,1] neg_lo:[1,0,0] neg_hi:[1,0,0]
	ds_read_b128 v[12:15], v251 offset:2704
	s_waitcnt lgkmcnt(13)
	v_pk_fma_f32 v[76:77], v[16:17], v[36:37], v[76:77] op_sel:[0,1,0] op_sel_hi:[1,1,1] neg_lo:[1,0,0] neg_hi:[1,0,0]
	v_pk_fma_f32 v[78:79], v[18:19], v[36:37], v[78:79] op_sel:[0,1,0] op_sel_hi:[1,1,1] neg_lo:[1,0,0] neg_hi:[1,0,0]
	ds_read_b128 v[16:19], v251 offset:2720
	s_waitcnt lgkmcnt(13)
	v_pk_fma_f32 v[80:81], v[20:21], v[36:37], v[80:81] op_sel:[0,1,0] op_sel_hi:[1,1,1] neg_lo:[1,0,0] neg_hi:[1,0,0]
	v_pk_fma_f32 v[82:83], v[22:23], v[36:37], v[82:83] op_sel:[0,1,0] op_sel_hi:[1,1,1] neg_lo:[1,0,0] neg_hi:[1,0,0]
	ds_read_b128 v[20:23], v251 offset:2736
	s_waitcnt lgkmcnt(13)
	v_pk_fma_f32 v[84:85], v[24:25], v[36:37], v[84:85] op_sel:[0,1,0] op_sel_hi:[1,1,1] neg_lo:[1,0,0] neg_hi:[1,0,0]
	v_pk_fma_f32 v[86:87], v[26:27], v[36:37], v[86:87] op_sel:[0,1,0] op_sel_hi:[1,1,1] neg_lo:[1,0,0] neg_hi:[1,0,0]
	ds_read_b128 v[24:27], v251 offset:2752
	s_waitcnt lgkmcnt(13)
	v_pk_fma_f32 v[88:89], v[28:29], v[36:37], v[88:89] op_sel:[0,1,0] op_sel_hi:[1,1,1] neg_lo:[1,0,0] neg_hi:[1,0,0]
	v_pk_fma_f32 v[90:91], v[30:31], v[36:37], v[90:91] op_sel:[0,1,0] op_sel_hi:[1,1,1] neg_lo:[1,0,0] neg_hi:[1,0,0]
	ds_read_b128 v[28:31], v251 offset:2768
	s_waitcnt lgkmcnt(13)
	v_pk_fma_f32 v[92:93], v[126:127], v[36:37], v[92:93] op_sel:[0,1,0] op_sel_hi:[1,1,1] neg_lo:[1,0,0] neg_hi:[1,0,0]
	v_pk_fma_f32 v[94:95], v[128:129], v[36:37], v[94:95] op_sel:[0,1,0] op_sel_hi:[1,1,1] neg_lo:[1,0,0] neg_hi:[1,0,0]
	ds_read_b128 v[126:129], v251 offset:2784
	s_waitcnt lgkmcnt(13)
	v_fma_f32 v39, -v233, v38, v39
	ds_read_b128 v[230:233], v251 offset:2800
	s_waitcnt lgkmcnt(13)
	v_pk_fma_f32 v[40:41], v[234:235], v[38:39], v[40:41] op_sel:[0,0,0] op_sel_hi:[1,0,1] neg_lo:[1,0,0] neg_hi:[1,0,0]
	v_pk_fma_f32 v[42:43], v[236:237], v[38:39], v[42:43] op_sel:[0,0,0] op_sel_hi:[1,0,1] neg_lo:[1,0,0] neg_hi:[1,0,0]
	ds_read_b128 v[234:237], v251 offset:2848
	s_waitcnt lgkmcnt(13)
	v_pk_fma_f32 v[44:45], v[238:239], v[38:39], v[44:45] op_sel:[0,0,0] op_sel_hi:[1,0,1] neg_lo:[1,0,0] neg_hi:[1,0,0]
	v_pk_fma_f32 v[46:47], v[240:241], v[38:39], v[46:47] op_sel:[0,0,0] op_sel_hi:[1,0,1] neg_lo:[1,0,0] neg_hi:[1,0,0]
	ds_read_b128 v[238:241], v251 offset:2864
	s_waitcnt lgkmcnt(13)
	v_pk_fma_f32 v[48:49], v[242:243], v[38:39], v[48:49] op_sel:[0,0,0] op_sel_hi:[1,0,1] neg_lo:[1,0,0] neg_hi:[1,0,0]
	v_pk_fma_f32 v[50:51], v[244:245], v[38:39], v[50:51] op_sel:[0,0,0] op_sel_hi:[1,0,1] neg_lo:[1,0,0] neg_hi:[1,0,0]
	ds_read_b128 v[242:245], v251 offset:2880
	s_waitcnt lgkmcnt(13)
	v_pk_fma_f32 v[52:53], v[246:247], v[38:39], v[52:53] op_sel:[0,0,0] op_sel_hi:[1,0,1] neg_lo:[1,0,0] neg_hi:[1,0,0]
	v_pk_fma_f32 v[54:55], v[248:249], v[38:39], v[54:55] op_sel:[0,0,0] op_sel_hi:[1,0,1] neg_lo:[1,0,0] neg_hi:[1,0,0]
	ds_read_b128 v[246:249], v251 offset:2896
	s_waitcnt lgkmcnt(13)
	v_pk_fma_f32 v[56:57], v[0:1], v[38:39], v[56:57] op_sel:[0,0,0] op_sel_hi:[1,0,1] neg_lo:[1,0,0] neg_hi:[1,0,0]
	v_pk_fma_f32 v[58:59], v[2:3], v[38:39], v[58:59] op_sel:[0,0,0] op_sel_hi:[1,0,1] neg_lo:[1,0,0] neg_hi:[1,0,0]
	ds_read_b128 v[0:3], v251 offset:2912
	s_waitcnt lgkmcnt(13)
	v_pk_fma_f32 v[60:61], v[4:5], v[38:39], v[60:61] op_sel:[0,0,0] op_sel_hi:[1,0,1] neg_lo:[1,0,0] neg_hi:[1,0,0]
	v_pk_fma_f32 v[62:63], v[6:7], v[38:39], v[62:63] op_sel:[0,0,0] op_sel_hi:[1,0,1] neg_lo:[1,0,0] neg_hi:[1,0,0]
	ds_read_b128 v[4:7], v251 offset:2928
	s_waitcnt lgkmcnt(13)
	v_pk_fma_f32 v[64:65], v[8:9], v[38:39], v[64:65] op_sel:[0,0,0] op_sel_hi:[1,0,1] neg_lo:[1,0,0] neg_hi:[1,0,0]
	v_pk_fma_f32 v[66:67], v[10:11], v[38:39], v[66:67] op_sel:[0,0,0] op_sel_hi:[1,0,1] neg_lo:[1,0,0] neg_hi:[1,0,0]
	ds_read_b128 v[8:11], v251 offset:2944
	s_waitcnt lgkmcnt(13)
; #define PG8_LAS __attribute__((address_space(3)))
; __device__ __forceinline__ void solve64(float (&x)[64], const PG8_LAS float* sLt) {
;     f32x4 cur[16];
; #pragma unroll
;     for (int i4 = 0; i4 < 16; ++i4) cur[i4] = *(const PG8_LAS f32x4*)(sLt + 4 * i4);
;     asm volatile("" ::: "memory");
; #pragma unroll
;     for (int j = 0; j < 63; ++j) {
;         const float xj = x[j];
; #pragma unroll
;         for (int i4 = (j + 1) / 4; i4 < 16; ++i4) {
;             if (4 * i4 + 0 > j) x[4 * i4 + 0] -= cur[i4][0] * xj;
;             if (4 * i4 + 1 > j) x[4 * i4 + 1] -= cur[i4][1] * xj;
;             if (4 * i4 + 2 > j) x[4 * i4 + 2] -= cur[i4][2] * xj;
;             if (4 * i4 + 3 > j) x[4 * i4 + 3] -= cur[i4][3] * xj;
;             if (j + 1 < 63 && i4 >= (j + 2) / 4) cur[i4] = *(const PG8_LAS f32x4*)(sLt + (j + 1) * 64 + 4 * i4); }
;         asm volatile("" ::: "memory");
;     }
	v_pk_fma_f32 v[68:69], v[12:13], v[38:39], v[68:69] op_sel:[0,0,0] op_sel_hi:[1,0,1] neg_lo:[1,0,0] neg_hi:[1,0,0]
	v_pk_fma_f32 v[70:71], v[14:15], v[38:39], v[70:71] op_sel:[0,0,0] op_sel_hi:[1,0,1] neg_lo:[1,0,0] neg_hi:[1,0,0]
	ds_read_b128 v[12:15], v251 offset:2960
	s_waitcnt lgkmcnt(13)
	v_pk_fma_f32 v[72:73], v[16:17], v[38:39], v[72:73] op_sel:[0,0,0] op_sel_hi:[1,0,1] neg_lo:[1,0,0] neg_hi:[1,0,0]
	v_pk_fma_f32 v[74:75], v[18:19], v[38:39], v[74:75] op_sel:[0,0,0] op_sel_hi:[1,0,1] neg_lo:[1,0,0] neg_hi:[1,0,0]
	ds_read_b128 v[16:19], v251 offset:2976
	s_waitcnt lgkmcnt(13)
	v_pk_fma_f32 v[76:77], v[20:21], v[38:39], v[76:77] op_sel:[0,0,0] op_sel_hi:[1,0,1] neg_lo:[1,0,0] neg_hi:[1,0,0]
	v_pk_fma_f32 v[78:79], v[22:23], v[38:39], v[78:79] op_sel:[0,0,0] op_sel_hi:[1,0,1] neg_lo:[1,0,0] neg_hi:[1,0,0]
	ds_read_b128 v[20:23], v251 offset:2992
	s_waitcnt lgkmcnt(13)
	v_pk_fma_f32 v[80:81], v[24:25], v[38:39], v[80:81] op_sel:[0,0,0] op_sel_hi:[1,0,1] neg_lo:[1,0,0] neg_hi:[1,0,0]
	v_pk_fma_f32 v[82:83], v[26:27], v[38:39], v[82:83] op_sel:[0,0,0] op_sel_hi:[1,0,1] neg_lo:[1,0,0] neg_hi:[1,0,0]
	ds_read_b128 v[24:27], v251 offset:3008
	s_waitcnt lgkmcnt(13)
	v_pk_fma_f32 v[84:85], v[28:29], v[38:39], v[84:85] op_sel:[0,0,0] op_sel_hi:[1,0,1] neg_lo:[1,0,0] neg_hi:[1,0,0]
	v_pk_fma_f32 v[86:87], v[30:31], v[38:39], v[86:87] op_sel:[0,0,0] op_sel_hi:[1,0,1] neg_lo:[1,0,0] neg_hi:[1,0,0]
	ds_read_b128 v[28:31], v251 offset:3024
	s_waitcnt lgkmcnt(13)
	v_pk_fma_f32 v[88:89], v[126:127], v[38:39], v[88:89] op_sel:[0,0,0] op_sel_hi:[1,0,1] neg_lo:[1,0,0] neg_hi:[1,0,0]
	v_pk_fma_f32 v[90:91], v[128:129], v[38:39], v[90:91] op_sel:[0,0,0] op_sel_hi:[1,0,1] neg_lo:[1,0,0] neg_hi:[1,0,0]
	ds_read_b128 v[126:129], v251 offset:3040
	s_waitcnt lgkmcnt(13)
	v_pk_fma_f32 v[92:93], v[230:231], v[38:39], v[92:93] op_sel:[0,0,0] op_sel_hi:[1,0,1] neg_lo:[1,0,0] neg_hi:[1,0,0]
	v_pk_fma_f32 v[94:95], v[232:233], v[38:39], v[94:95] op_sel:[0,0,0] op_sel_hi:[1,0,1] neg_lo:[1,0,0] neg_hi:[1,0,0]
	ds_read_b128 v[230:233], v251 offset:3056
	s_waitcnt lgkmcnt(13)
	v_pk_fma_f32 v[40:41], v[234:235], v[38:39], v[40:41] op_sel:[0,1,0] op_sel_hi:[1,1,1] neg_lo:[1,0,0] neg_hi:[1,0,0]
	v_pk_fma_f32 v[42:43], v[236:237], v[38:39], v[42:43] op_sel:[0,1,0] op_sel_hi:[1,1,1] neg_lo:[1,0,0] neg_hi:[1,0,0]
	ds_read_b128 v[234:237], v251 offset:3104
	s_waitcnt lgkmcnt(13)
	v_pk_fma_f32 v[44:45], v[238:239], v[38:39], v[44:45] op_sel:[0,1,0] op_sel_hi:[1,1,1] neg_lo:[1,0,0] neg_hi:[1,0,0]
	v_pk_fma_f32 v[46:47], v[240:241], v[38:39], v[46:47] op_sel:[0,1,0] op_sel_hi:[1,1,1] neg_lo:[1,0,0] neg_hi:[1,0,0]
	ds_read_b128 v[238:241], v251 offset:3120
	s_waitcnt lgkmcnt(13)
	v_pk_fma_f32 v[48:49], v[242:243], v[38:39], v[48:49] op_sel:[0,1,0] op_sel_hi:[1,1,1] neg_lo:[1,0,0] neg_hi:[1,0,0]
	v_pk_fma_f32 v[50:51], v[244:245], v[38:39], v[50:51] op_sel:[0,1,0] op_sel_hi:[1,1,1] neg_lo:[1,0,0] neg_hi:[1,0,0]
	ds_read_b128 v[242:245], v251 offset:3136
	s_waitcnt lgkmcnt(13)
	v_pk_fma_f32 v[52:53], v[246:247], v[38:39], v[52:53] op_sel:[0,1,0] op_sel_hi:[1,1,1] neg_lo:[1,0,0] neg_hi:[1,0,0]
	v_pk_fma_f32 v[54:55], v[248:249], v[38:39], v[54:55] op_sel:[0,1,0] op_sel_hi:[1,1,1] neg_lo:[1,0,0] neg_hi:[1,0,0]
	ds_read_b128 v[246:249], v251 offset:3152
	s_waitcnt lgkmcnt(13)
	v_pk_fma_f32 v[56:57], v[0:1], v[38:39], v[56:57] op_sel:[0,1,0] op_sel_hi:[1,1,1] neg_lo:[1,0,0] neg_hi:[1,0,0]
	v_pk_fma_f32 v[58:59], v[2:3], v[38:39], v[58:59] op_sel:[0,1,0] op_sel_hi:[1,1,1] neg_lo:[1,0,0] neg_hi:[1,0,0]
	ds_read_b128 v[0:3], v251 offset:3168
	s_waitcnt lgkmcnt(13)
	v_pk_fma_f32 v[60:61], v[4:5], v[38:39], v[60:61] op_sel:[0,1,0] op_sel_hi:[1,1,1] neg_lo:[1,0,0] neg_hi:[1,0,0]
	v_pk_fma_f32 v[62:63], v[6:7], v[38:39], v[62:63] op_sel:[0,1,0] op_sel_hi:[1,1,1] neg_lo:[1,0,0] neg_hi:[1,0,0]
	ds_read_b128 v[4:7], v251 offset:3184
	s_waitcnt lgkmcnt(13)
	v_pk_fma_f32 v[64:65], v[8:9], v[38:39], v[64:65] op_sel:[0,1,0] op_sel_hi:[1,1,1] neg_lo:[1,0,0] neg_hi:[1,0,0]
	v_pk_fma_f32 v[66:67], v[10:11], v[38:39], v[66:67] op_sel:[0,1,0] op_sel_hi:[1,1,1] neg_lo:[1,0,0] neg_hi:[1,0,0]
	ds_read_b128 v[8:11], v251 offset:3200
	s_waitcnt lgkmcnt(13)
	v_pk_fma_f32 v[68:69], v[12:13], v[38:39], v[68:69] op_sel:[0,1,0] op_sel_hi:[1,1,1] neg_lo:[1,0,0] neg_hi:[1,0,0]
	v_pk_fma_f32 v[70:71], v[14:15], v[38:39], v[70:71] op_sel:[0,1,0] op_sel_hi:[1,1,1] neg_lo:[1,0,0] neg_hi:[1,0,0]
	ds_read_b128 v[12:15], v251 offset:3216
	s_waitcnt lgkmcnt(13)
	v_pk_fma_f32 v[72:73], v[16:17], v[38:39], v[72:73] op_sel:[0,1,0] op_sel_hi:[1,1,1] neg_lo:[1,0,0] neg_hi:[1,0,0]
	v_pk_fma_f32 v[74:75], v[18:19], v[38:39], v[74:75] op_sel:[0,1,0] op_sel_hi:[1,1,1] neg_lo:[1,0,0] neg_hi:[1,0,0]
	ds_read_b128 v[16:19], v251 offset:3232
	s_waitcnt lgkmcnt(13)
	v_pk_fma_f32 v[76:77], v[20:21], v[38:39], v[76:77] op_sel:[0,1,0] op_sel_hi:[1,1,1] neg_lo:[1,0,0] neg_hi:[1,0,0]
	v_pk_fma_f32 v[78:79], v[22:23], v[38:39], v[78:79] op_sel:[0,1,0] op_sel_hi:[1,1,1] neg_lo:[1,0,0] neg_hi:[1,0,0]
	ds_read_b128 v[20:23], v251 offset:3248
	s_waitcnt lgkmcnt(13)
	v_pk_fma_f32 v[80:81], v[24:25], v[38:39], v[80:81] op_sel:[0,1,0] op_sel_hi:[1,1,1] neg_lo:[1,0,0] neg_hi:[1,0,0]
	v_pk_fma_f32 v[82:83], v[26:27], v[38:39], v[82:83] op_sel:[0,1,0] op_sel_hi:[1,1,1] neg_lo:[1,0,0] neg_hi:[1,0,0]
	ds_read_b128 v[24:27], v251 offset:3264
	s_waitcnt lgkmcnt(13)
	v_pk_fma_f32 v[84:85], v[28:29], v[38:39], v[84:85] op_sel:[0,1,0] op_sel_hi:[1,1,1] neg_lo:[1,0,0] neg_hi:[1,0,0]
	v_pk_fma_f32 v[86:87], v[30:31], v[38:39], v[86:87] op_sel:[0,1,0] op_sel_hi:[1,1,1] neg_lo:[1,0,0] neg_hi:[1,0,0]
	ds_read_b128 v[28:31], v251 offset:3280
	s_waitcnt lgkmcnt(13)
; #define PG8_LAS __attribute__((address_space(3)))
; __device__ __forceinline__ void solve64(float (&x)[64], const PG8_LAS float* sLt) {
;     f32x4 cur[16];
; #pragma unroll
;     for (int i4 = 0; i4 < 16; ++i4) cur[i4] = *(const PG8_LAS f32x4*)(sLt + 4 * i4);
;     asm volatile("" ::: "memory");
; #pragma unroll
;     for (int j = 0; j < 63; ++j) {
;         const float xj = x[j];
; #pragma unroll
;         for (int i4 = (j + 1) / 4; i4 < 16; ++i4) {
;             if (4 * i4 + 0 > j) x[4 * i4 + 0] -= cur[i4][0] * xj;
;             if (4 * i4 + 1 > j) x[4 * i4 + 1] -= cur[i4][1] * xj;
;             if (4 * i4 + 2 > j) x[4 * i4 + 2] -= cur[i4][2] * xj;
;             if (4 * i4 + 3 > j) x[4 * i4 + 3] -= cur[i4][3] * xj;
;             if (j + 1 < 63 && i4 >= (j + 2) / 4) cur[i4] = *(const PG8_LAS f32x4*)(sLt + (j + 1) * 64 + 4 * i4); }
;         asm volatile("" ::: "memory");
;     }
	v_pk_fma_f32 v[88:89], v[126:127], v[38:39], v[88:89] op_sel:[0,1,0] op_sel_hi:[1,1,1] neg_lo:[1,0,0] neg_hi:[1,0,0]
	v_pk_fma_f32 v[90:91], v[128:129], v[38:39], v[90:91] op_sel:[0,1,0] op_sel_hi:[1,1,1] neg_lo:[1,0,0] neg_hi:[1,0,0]
	ds_read_b128 v[126:129], v251 offset:3296
	s_waitcnt lgkmcnt(13)
	v_pk_fma_f32 v[92:93], v[230:231], v[38:39], v[92:93] op_sel:[0,1,0] op_sel_hi:[1,1,1] neg_lo:[1,0,0] neg_hi:[1,0,0]
	v_pk_fma_f32 v[94:95], v[232:233], v[38:39], v[94:95] op_sel:[0,1,0] op_sel_hi:[1,1,1] neg_lo:[1,0,0] neg_hi:[1,0,0]
	ds_read_b128 v[230:233], v251 offset:3312
	s_waitcnt lgkmcnt(13)
	v_fma_f32 v41, -v235, v40, v41
	v_pk_fma_f32 v[42:43], v[236:237], v[40:41], v[42:43] op_sel:[0,0,0] op_sel_hi:[1,0,1] neg_lo:[1,0,0] neg_hi:[1,0,0]
	ds_read_b128 v[234:237], v251 offset:3360
	s_waitcnt lgkmcnt(13)
	v_pk_fma_f32 v[44:45], v[238:239], v[40:41], v[44:45] op_sel:[0,0,0] op_sel_hi:[1,0,1] neg_lo:[1,0,0] neg_hi:[1,0,0]
	v_pk_fma_f32 v[46:47], v[240:241], v[40:41], v[46:47] op_sel:[0,0,0] op_sel_hi:[1,0,1] neg_lo:[1,0,0] neg_hi:[1,0,0]
	ds_read_b128 v[238:241], v251 offset:3376
	s_waitcnt lgkmcnt(13)
	v_pk_fma_f32 v[48:49], v[242:243], v[40:41], v[48:49] op_sel:[0,0,0] op_sel_hi:[1,0,1] neg_lo:[1,0,0] neg_hi:[1,0,0]
	v_pk_fma_f32 v[50:51], v[244:245], v[40:41], v[50:51] op_sel:[0,0,0] op_sel_hi:[1,0,1] neg_lo:[1,0,0] neg_hi:[1,0,0]
	ds_read_b128 v[242:245], v251 offset:3392
	s_waitcnt lgkmcnt(13)
	v_pk_fma_f32 v[52:53], v[246:247], v[40:41], v[52:53] op_sel:[0,0,0] op_sel_hi:[1,0,1] neg_lo:[1,0,0] neg_hi:[1,0,0]
	v_pk_fma_f32 v[54:55], v[248:249], v[40:41], v[54:55] op_sel:[0,0,0] op_sel_hi:[1,0,1] neg_lo:[1,0,0] neg_hi:[1,0,0]
	ds_read_b128 v[246:249], v251 offset:3408
	s_waitcnt lgkmcnt(13)
	v_pk_fma_f32 v[56:57], v[0:1], v[40:41], v[56:57] op_sel:[0,0,0] op_sel_hi:[1,0,1] neg_lo:[1,0,0] neg_hi:[1,0,0]
	v_pk_fma_f32 v[58:59], v[2:3], v[40:41], v[58:59] op_sel:[0,0,0] op_sel_hi:[1,0,1] neg_lo:[1,0,0] neg_hi:[1,0,0]
	ds_read_b128 v[0:3], v251 offset:3424
	s_waitcnt lgkmcnt(13)
	v_pk_fma_f32 v[60:61], v[4:5], v[40:41], v[60:61] op_sel:[0,0,0] op_sel_hi:[1,0,1] neg_lo:[1,0,0] neg_hi:[1,0,0]
	v_pk_fma_f32 v[62:63], v[6:7], v[40:41], v[62:63] op_sel:[0,0,0] op_sel_hi:[1,0,1] neg_lo:[1,0,0] neg_hi:[1,0,0]
	ds_read_b128 v[4:7], v251 offset:3440
	s_waitcnt lgkmcnt(13)
	v_pk_fma_f32 v[64:65], v[8:9], v[40:41], v[64:65] op_sel:[0,0,0] op_sel_hi:[1,0,1] neg_lo:[1,0,0] neg_hi:[1,0,0]
	v_pk_fma_f32 v[66:67], v[10:11], v[40:41], v[66:67] op_sel:[0,0,0] op_sel_hi:[1,0,1] neg_lo:[1,0,0] neg_hi:[1,0,0]
	ds_read_b128 v[8:11], v251 offset:3456
	s_waitcnt lgkmcnt(13)
	v_pk_fma_f32 v[68:69], v[12:13], v[40:41], v[68:69] op_sel:[0,0,0] op_sel_hi:[1,0,1] neg_lo:[1,0,0] neg_hi:[1,0,0]
	v_pk_fma_f32 v[70:71], v[14:15], v[40:41], v[70:71] op_sel:[0,0,0] op_sel_hi:[1,0,1] neg_lo:[1,0,0] neg_hi:[1,0,0]
	ds_read_b128 v[12:15], v251 offset:3472
	s_waitcnt lgkmcnt(13)
	v_pk_fma_f32 v[72:73], v[16:17], v[40:41], v[72:73] op_sel:[0,0,0] op_sel_hi:[1,0,1] neg_lo:[1,0,0] neg_hi:[1,0,0]
	v_pk_fma_f32 v[74:75], v[18:19], v[40:41], v[74:75] op_sel:[0,0,0] op_sel_hi:[1,0,1] neg_lo:[1,0,0] neg_hi:[1,0,0]
	ds_read_b128 v[16:19], v251 offset:3488
	s_waitcnt lgkmcnt(13)
	v_pk_fma_f32 v[76:77], v[20:21], v[40:41], v[76:77] op_sel:[0,0,0] op_sel_hi:[1,0,1] neg_lo:[1,0,0] neg_hi:[1,0,0]
	v_pk_fma_f32 v[78:79], v[22:23], v[40:41], v[78:79] op_sel:[0,0,0] op_sel_hi:[1,0,1] neg_lo:[1,0,0] neg_hi:[1,0,0]
	ds_read_b128 v[20:23], v251 offset:3504
	s_waitcnt lgkmcnt(13)
	v_pk_fma_f32 v[80:81], v[24:25], v[40:41], v[80:81] op_sel:[0,0,0] op_sel_hi:[1,0,1] neg_lo:[1,0,0] neg_hi:[1,0,0]
	v_pk_fma_f32 v[82:83], v[26:27], v[40:41], v[82:83] op_sel:[0,0,0] op_sel_hi:[1,0,1] neg_lo:[1,0,0] neg_hi:[1,0,0]
	ds_read_b128 v[24:27], v251 offset:3520
	s_waitcnt lgkmcnt(13)
	v_pk_fma_f32 v[84:85], v[28:29], v[40:41], v[84:85] op_sel:[0,0,0] op_sel_hi:[1,0,1] neg_lo:[1,0,0] neg_hi:[1,0,0]
	v_pk_fma_f32 v[86:87], v[30:31], v[40:41], v[86:87] op_sel:[0,0,0] op_sel_hi:[1,0,1] neg_lo:[1,0,0] neg_hi:[1,0,0]
	ds_read_b128 v[28:31], v251 offset:3536
	s_waitcnt lgkmcnt(13)
	v_pk_fma_f32 v[88:89], v[126:127], v[40:41], v[88:89] op_sel:[0,0,0] op_sel_hi:[1,0,1] neg_lo:[1,0,0] neg_hi:[1,0,0]
	v_pk_fma_f32 v[90:91], v[128:129], v[40:41], v[90:91] op_sel:[0,0,0] op_sel_hi:[1,0,1] neg_lo:[1,0,0] neg_hi:[1,0,0]
	ds_read_b128 v[126:129], v251 offset:3552
	s_waitcnt lgkmcnt(13)
	v_pk_fma_f32 v[92:93], v[230:231], v[40:41], v[92:93] op_sel:[0,0,0] op_sel_hi:[1,0,1] neg_lo:[1,0,0] neg_hi:[1,0,0]
	v_pk_fma_f32 v[94:95], v[232:233], v[40:41], v[94:95] op_sel:[0,0,0] op_sel_hi:[1,0,1] neg_lo:[1,0,0] neg_hi:[1,0,0]
	ds_read_b128 v[230:233], v251 offset:3568
	s_waitcnt lgkmcnt(13)
	v_pk_fma_f32 v[42:43], v[236:237], v[40:41], v[42:43] op_sel:[0,1,0] op_sel_hi:[1,1,1] neg_lo:[1,0,0] neg_hi:[1,0,0]
	ds_read_b128 v[234:237], v251 offset:3616
	s_waitcnt lgkmcnt(13)
	v_pk_fma_f32 v[44:45], v[238:239], v[40:41], v[44:45] op_sel:[0,1,0] op_sel_hi:[1,1,1] neg_lo:[1,0,0] neg_hi:[1,0,0]
	v_pk_fma_f32 v[46:47], v[240:241], v[40:41], v[46:47] op_sel:[0,1,0] op_sel_hi:[1,1,1] neg_lo:[1,0,0] neg_hi:[1,0,0]
	ds_read_b128 v[238:241], v251 offset:3632
	s_waitcnt lgkmcnt(13)
	v_pk_fma_f32 v[48:49], v[242:243], v[40:41], v[48:49] op_sel:[0,1,0] op_sel_hi:[1,1,1] neg_lo:[1,0,0] neg_hi:[1,0,0]
	v_pk_fma_f32 v[50:51], v[244:245], v[40:41], v[50:51] op_sel:[0,1,0] op_sel_hi:[1,1,1] neg_lo:[1,0,0] neg_hi:[1,0,0]
	ds_read_b128 v[242:245], v251 offset:3648
	s_waitcnt lgkmcnt(13)
	v_pk_fma_f32 v[52:53], v[246:247], v[40:41], v[52:53] op_sel:[0,1,0] op_sel_hi:[1,1,1] neg_lo:[1,0,0] neg_hi:[1,0,0]
	v_pk_fma_f32 v[54:55], v[248:249], v[40:41], v[54:55] op_sel:[0,1,0] op_sel_hi:[1,1,1] neg_lo:[1,0,0] neg_hi:[1,0,0]
	ds_read_b128 v[246:249], v251 offset:3664
	s_waitcnt lgkmcnt(13)
; #define PG8_LAS __attribute__((address_space(3)))
; __device__ __forceinline__ void solve64(float (&x)[64], const PG8_LAS float* sLt) {
;     f32x4 cur[16];
; #pragma unroll
;     for (int i4 = 0; i4 < 16; ++i4) cur[i4] = *(const PG8_LAS f32x4*)(sLt + 4 * i4);
;     asm volatile("" ::: "memory");
; #pragma unroll
;     for (int j = 0; j < 63; ++j) {
;         const float xj = x[j];
; #pragma unroll
;         for (int i4 = (j + 1) / 4; i4 < 16; ++i4) {
;             if (4 * i4 + 0 > j) x[4 * i4 + 0] -= cur[i4][0] * xj;
;             if (4 * i4 + 1 > j) x[4 * i4 + 1] -= cur[i4][1] * xj;
;             if (4 * i4 + 2 > j) x[4 * i4 + 2] -= cur[i4][2] * xj;
;             if (4 * i4 + 3 > j) x[4 * i4 + 3] -= cur[i4][3] * xj;
;             if (j + 1 < 63 && i4 >= (j + 2) / 4) cur[i4] = *(const PG8_LAS f32x4*)(sLt + (j + 1) * 64 + 4 * i4); }
;         asm volatile("" ::: "memory");
;     }
	v_pk_fma_f32 v[56:57], v[0:1], v[40:41], v[56:57] op_sel:[0,1,0] op_sel_hi:[1,1,1] neg_lo:[1,0,0] neg_hi:[1,0,0]
	v_pk_fma_f32 v[58:59], v[2:3], v[40:41], v[58:59] op_sel:[0,1,0] op_sel_hi:[1,1,1] neg_lo:[1,0,0] neg_hi:[1,0,0]
	ds_read_b128 v[0:3], v251 offset:3680
	s_waitcnt lgkmcnt(13)
	v_pk_fma_f32 v[60:61], v[4:5], v[40:41], v[60:61] op_sel:[0,1,0] op_sel_hi:[1,1,1] neg_lo:[1,0,0] neg_hi:[1,0,0]
	v_pk_fma_f32 v[62:63], v[6:7], v[40:41], v[62:63] op_sel:[0,1,0] op_sel_hi:[1,1,1] neg_lo:[1,0,0] neg_hi:[1,0,0]
	ds_read_b128 v[4:7], v251 offset:3696
	s_waitcnt lgkmcnt(13)
	v_pk_fma_f32 v[64:65], v[8:9], v[40:41], v[64:65] op_sel:[0,1,0] op_sel_hi:[1,1,1] neg_lo:[1,0,0] neg_hi:[1,0,0]
	v_pk_fma_f32 v[66:67], v[10:11], v[40:41], v[66:67] op_sel:[0,1,0] op_sel_hi:[1,1,1] neg_lo:[1,0,0] neg_hi:[1,0,0]
	ds_read_b128 v[8:11], v251 offset:3712
	s_waitcnt lgkmcnt(13)
	v_pk_fma_f32 v[68:69], v[12:13], v[40:41], v[68:69] op_sel:[0,1,0] op_sel_hi:[1,1,1] neg_lo:[1,0,0] neg_hi:[1,0,0]
	v_pk_fma_f32 v[70:71], v[14:15], v[40:41], v[70:71] op_sel:[0,1,0] op_sel_hi:[1,1,1] neg_lo:[1,0,0] neg_hi:[1,0,0]
	ds_read_b128 v[12:15], v251 offset:3728
	s_waitcnt lgkmcnt(13)
	v_pk_fma_f32 v[72:73], v[16:17], v[40:41], v[72:73] op_sel:[0,1,0] op_sel_hi:[1,1,1] neg_lo:[1,0,0] neg_hi:[1,0,0]
	v_pk_fma_f32 v[74:75], v[18:19], v[40:41], v[74:75] op_sel:[0,1,0] op_sel_hi:[1,1,1] neg_lo:[1,0,0] neg_hi:[1,0,0]
	ds_read_b128 v[16:19], v251 offset:3744
	s_waitcnt lgkmcnt(13)
	v_pk_fma_f32 v[76:77], v[20:21], v[40:41], v[76:77] op_sel:[0,1,0] op_sel_hi:[1,1,1] neg_lo:[1,0,0] neg_hi:[1,0,0]
	v_pk_fma_f32 v[78:79], v[22:23], v[40:41], v[78:79] op_sel:[0,1,0] op_sel_hi:[1,1,1] neg_lo:[1,0,0] neg_hi:[1,0,0]
	ds_read_b128 v[20:23], v251 offset:3760
	s_waitcnt lgkmcnt(13)
	v_pk_fma_f32 v[80:81], v[24:25], v[40:41], v[80:81] op_sel:[0,1,0] op_sel_hi:[1,1,1] neg_lo:[1,0,0] neg_hi:[1,0,0]
	v_pk_fma_f32 v[82:83], v[26:27], v[40:41], v[82:83] op_sel:[0,1,0] op_sel_hi:[1,1,1] neg_lo:[1,0,0] neg_hi:[1,0,0]
	ds_read_b128 v[24:27], v251 offset:3776
	s_waitcnt lgkmcnt(13)
	v_pk_fma_f32 v[84:85], v[28:29], v[40:41], v[84:85] op_sel:[0,1,0] op_sel_hi:[1,1,1] neg_lo:[1,0,0] neg_hi:[1,0,0]
	v_pk_fma_f32 v[86:87], v[30:31], v[40:41], v[86:87] op_sel:[0,1,0] op_sel_hi:[1,1,1] neg_lo:[1,0,0] neg_hi:[1,0,0]
	ds_read_b128 v[28:31], v251 offset:3792
	s_waitcnt lgkmcnt(13)
	v_pk_fma_f32 v[88:89], v[126:127], v[40:41], v[88:89] op_sel:[0,1,0] op_sel_hi:[1,1,1] neg_lo:[1,0,0] neg_hi:[1,0,0]
	v_pk_fma_f32 v[90:91], v[128:129], v[40:41], v[90:91] op_sel:[0,1,0] op_sel_hi:[1,1,1] neg_lo:[1,0,0] neg_hi:[1,0,0]
	ds_read_b128 v[126:129], v251 offset:3808
	s_waitcnt lgkmcnt(13)
	v_pk_fma_f32 v[92:93], v[230:231], v[40:41], v[92:93] op_sel:[0,1,0] op_sel_hi:[1,1,1] neg_lo:[1,0,0] neg_hi:[1,0,0]
	v_pk_fma_f32 v[94:95], v[232:233], v[40:41], v[94:95] op_sel:[0,1,0] op_sel_hi:[1,1,1] neg_lo:[1,0,0] neg_hi:[1,0,0]
	ds_read_b128 v[230:233], v251 offset:3824
	s_waitcnt lgkmcnt(13)
	v_fma_f32 v43, -v237, v42, v43
	ds_read_b128 v[234:237], v251 offset:3888
	s_waitcnt lgkmcnt(13)
	v_pk_fma_f32 v[44:45], v[238:239], v[42:43], v[44:45] op_sel:[0,0,0] op_sel_hi:[1,0,1] neg_lo:[1,0,0] neg_hi:[1,0,0]
	v_pk_fma_f32 v[46:47], v[240:241], v[42:43], v[46:47] op_sel:[0,0,0] op_sel_hi:[1,0,1] neg_lo:[1,0,0] neg_hi:[1,0,0]
	ds_read_b128 v[238:241], v251 offset:3904
	s_waitcnt lgkmcnt(13)
	v_pk_fma_f32 v[48:49], v[242:243], v[42:43], v[48:49] op_sel:[0,0,0] op_sel_hi:[1,0,1] neg_lo:[1,0,0] neg_hi:[1,0,0]
	v_pk_fma_f32 v[50:51], v[244:245], v[42:43], v[50:51] op_sel:[0,0,0] op_sel_hi:[1,0,1] neg_lo:[1,0,0] neg_hi:[1,0,0]
	ds_read_b128 v[242:245], v251 offset:3920
	s_waitcnt lgkmcnt(13)
	v_pk_fma_f32 v[52:53], v[246:247], v[42:43], v[52:53] op_sel:[0,0,0] op_sel_hi:[1,0,1] neg_lo:[1,0,0] neg_hi:[1,0,0]
	v_pk_fma_f32 v[54:55], v[248:249], v[42:43], v[54:55] op_sel:[0,0,0] op_sel_hi:[1,0,1] neg_lo:[1,0,0] neg_hi:[1,0,0]
	ds_read_b128 v[246:249], v251 offset:3936
	s_waitcnt lgkmcnt(13)
	v_pk_fma_f32 v[56:57], v[0:1], v[42:43], v[56:57] op_sel:[0,0,0] op_sel_hi:[1,0,1] neg_lo:[1,0,0] neg_hi:[1,0,0]
	v_pk_fma_f32 v[58:59], v[2:3], v[42:43], v[58:59] op_sel:[0,0,0] op_sel_hi:[1,0,1] neg_lo:[1,0,0] neg_hi:[1,0,0]
	ds_read_b128 v[0:3], v251 offset:3952
	s_waitcnt lgkmcnt(13)
	v_pk_fma_f32 v[60:61], v[4:5], v[42:43], v[60:61] op_sel:[0,0,0] op_sel_hi:[1,0,1] neg_lo:[1,0,0] neg_hi:[1,0,0]
	v_pk_fma_f32 v[62:63], v[6:7], v[42:43], v[62:63] op_sel:[0,0,0] op_sel_hi:[1,0,1] neg_lo:[1,0,0] neg_hi:[1,0,0]
	ds_read_b128 v[4:7], v251 offset:3968
	s_waitcnt lgkmcnt(13)
	v_pk_fma_f32 v[64:65], v[8:9], v[42:43], v[64:65] op_sel:[0,0,0] op_sel_hi:[1,0,1] neg_lo:[1,0,0] neg_hi:[1,0,0]
	v_pk_fma_f32 v[66:67], v[10:11], v[42:43], v[66:67] op_sel:[0,0,0] op_sel_hi:[1,0,1] neg_lo:[1,0,0] neg_hi:[1,0,0]
	ds_read_b128 v[8:11], v251 offset:3984
	s_waitcnt lgkmcnt(13)
	v_pk_fma_f32 v[68:69], v[12:13], v[42:43], v[68:69] op_sel:[0,0,0] op_sel_hi:[1,0,1] neg_lo:[1,0,0] neg_hi:[1,0,0]
	v_pk_fma_f32 v[70:71], v[14:15], v[42:43], v[70:71] op_sel:[0,0,0] op_sel_hi:[1,0,1] neg_lo:[1,0,0] neg_hi:[1,0,0]
	ds_read_b128 v[12:15], v251 offset:4000
	s_waitcnt lgkmcnt(13)
	v_pk_fma_f32 v[72:73], v[16:17], v[42:43], v[72:73] op_sel:[0,0,0] op_sel_hi:[1,0,1] neg_lo:[1,0,0] neg_hi:[1,0,0]
	v_pk_fma_f32 v[74:75], v[18:19], v[42:43], v[74:75] op_sel:[0,0,0] op_sel_hi:[1,0,1] neg_lo:[1,0,0] neg_hi:[1,0,0]
	ds_read_b128 v[16:19], v251 offset:4016
	s_waitcnt lgkmcnt(13)
	v_pk_fma_f32 v[76:77], v[20:21], v[42:43], v[76:77] op_sel:[0,0,0] op_sel_hi:[1,0,1] neg_lo:[1,0,0] neg_hi:[1,0,0]
	v_pk_fma_f32 v[78:79], v[22:23], v[42:43], v[78:79] op_sel:[0,0,0] op_sel_hi:[1,0,1] neg_lo:[1,0,0] neg_hi:[1,0,0]
	ds_read_b128 v[20:23], v251 offset:4032
	s_waitcnt lgkmcnt(13)
; #define PG8_LAS __attribute__((address_space(3)))
; __device__ __forceinline__ void solve64(float (&x)[64], const PG8_LAS float* sLt) {
;     f32x4 cur[16];
; #pragma unroll
;     for (int i4 = 0; i4 < 16; ++i4) cur[i4] = *(const PG8_LAS f32x4*)(sLt + 4 * i4);
;     asm volatile("" ::: "memory");
; #pragma unroll
;     for (int j = 0; j < 63; ++j) {
;         const float xj = x[j];
; #pragma unroll
;         for (int i4 = (j + 1) / 4; i4 < 16; ++i4) {
;             if (4 * i4 + 0 > j) x[4 * i4 + 0] -= cur[i4][0] * xj;
;             if (4 * i4 + 1 > j) x[4 * i4 + 1] -= cur[i4][1] * xj;
;             if (4 * i4 + 2 > j) x[4 * i4 + 2] -= cur[i4][2] * xj;
;             if (4 * i4 + 3 > j) x[4 * i4 + 3] -= cur[i4][3] * xj;
;             if (j + 1 < 63 && i4 >= (j + 2) / 4) cur[i4] = *(const PG8_LAS f32x4*)(sLt + (j + 1) * 64 + 4 * i4); }
;         asm volatile("" ::: "memory");
;     }
	v_pk_fma_f32 v[80:81], v[24:25], v[42:43], v[80:81] op_sel:[0,0,0] op_sel_hi:[1,0,1] neg_lo:[1,0,0] neg_hi:[1,0,0]
	v_pk_fma_f32 v[82:83], v[26:27], v[42:43], v[82:83] op_sel:[0,0,0] op_sel_hi:[1,0,1] neg_lo:[1,0,0] neg_hi:[1,0,0]
	ds_read_b128 v[24:27], v251 offset:4048
	s_waitcnt lgkmcnt(13)
	v_pk_fma_f32 v[84:85], v[28:29], v[42:43], v[84:85] op_sel:[0,0,0] op_sel_hi:[1,0,1] neg_lo:[1,0,0] neg_hi:[1,0,0]
	v_pk_fma_f32 v[86:87], v[30:31], v[42:43], v[86:87] op_sel:[0,0,0] op_sel_hi:[1,0,1] neg_lo:[1,0,0] neg_hi:[1,0,0]
	ds_read_b128 v[28:31], v251 offset:4064
	s_waitcnt lgkmcnt(13)
	v_pk_fma_f32 v[88:89], v[126:127], v[42:43], v[88:89] op_sel:[0,0,0] op_sel_hi:[1,0,1] neg_lo:[1,0,0] neg_hi:[1,0,0]
	v_pk_fma_f32 v[90:91], v[128:129], v[42:43], v[90:91] op_sel:[0,0,0] op_sel_hi:[1,0,1] neg_lo:[1,0,0] neg_hi:[1,0,0]
	ds_read_b128 v[126:129], v251 offset:4080
	s_waitcnt lgkmcnt(13)
	v_pk_fma_f32 v[92:93], v[230:231], v[42:43], v[92:93] op_sel:[0,0,0] op_sel_hi:[1,0,1] neg_lo:[1,0,0] neg_hi:[1,0,0]
	v_pk_fma_f32 v[94:95], v[232:233], v[42:43], v[94:95] op_sel:[0,0,0] op_sel_hi:[1,0,1] neg_lo:[1,0,0] neg_hi:[1,0,0]
	ds_read_b128 v[230:233], v251 offset:4144
	s_waitcnt lgkmcnt(13)
	v_pk_fma_f32 v[44:45], v[234:235], v[42:43], v[44:45] op_sel:[0,1,0] op_sel_hi:[1,1,1] neg_lo:[1,0,0] neg_hi:[1,0,0]
	v_pk_fma_f32 v[46:47], v[236:237], v[42:43], v[46:47] op_sel:[0,1,0] op_sel_hi:[1,1,1] neg_lo:[1,0,0] neg_hi:[1,0,0]
	ds_read_b128 v[234:237], v251 offset:4160
	s_waitcnt lgkmcnt(13)
	v_pk_fma_f32 v[48:49], v[238:239], v[42:43], v[48:49] op_sel:[0,1,0] op_sel_hi:[1,1,1] neg_lo:[1,0,0] neg_hi:[1,0,0]
	v_pk_fma_f32 v[50:51], v[240:241], v[42:43], v[50:51] op_sel:[0,1,0] op_sel_hi:[1,1,1] neg_lo:[1,0,0] neg_hi:[1,0,0]
	ds_read_b128 v[238:241], v251 offset:4176
	s_waitcnt lgkmcnt(13)
	v_pk_fma_f32 v[52:53], v[242:243], v[42:43], v[52:53] op_sel:[0,1,0] op_sel_hi:[1,1,1] neg_lo:[1,0,0] neg_hi:[1,0,0]
	v_pk_fma_f32 v[54:55], v[244:245], v[42:43], v[54:55] op_sel:[0,1,0] op_sel_hi:[1,1,1] neg_lo:[1,0,0] neg_hi:[1,0,0]
	ds_read_b128 v[242:245], v251 offset:4192
	s_waitcnt lgkmcnt(13)
	v_pk_fma_f32 v[56:57], v[246:247], v[42:43], v[56:57] op_sel:[0,1,0] op_sel_hi:[1,1,1] neg_lo:[1,0,0] neg_hi:[1,0,0]
	v_pk_fma_f32 v[58:59], v[248:249], v[42:43], v[58:59] op_sel:[0,1,0] op_sel_hi:[1,1,1] neg_lo:[1,0,0] neg_hi:[1,0,0]
	ds_read_b128 v[246:249], v251 offset:4208
	s_waitcnt lgkmcnt(13)
	v_pk_fma_f32 v[60:61], v[0:1], v[42:43], v[60:61] op_sel:[0,1,0] op_sel_hi:[1,1,1] neg_lo:[1,0,0] neg_hi:[1,0,0]
	v_pk_fma_f32 v[62:63], v[2:3], v[42:43], v[62:63] op_sel:[0,1,0] op_sel_hi:[1,1,1] neg_lo:[1,0,0] neg_hi:[1,0,0]
	ds_read_b128 v[0:3], v251 offset:4224
	s_waitcnt lgkmcnt(13)
	v_pk_fma_f32 v[64:65], v[4:5], v[42:43], v[64:65] op_sel:[0,1,0] op_sel_hi:[1,1,1] neg_lo:[1,0,0] neg_hi:[1,0,0]
	v_pk_fma_f32 v[66:67], v[6:7], v[42:43], v[66:67] op_sel:[0,1,0] op_sel_hi:[1,1,1] neg_lo:[1,0,0] neg_hi:[1,0,0]
	ds_read_b128 v[4:7], v251 offset:4240
	s_waitcnt lgkmcnt(13)
	v_pk_fma_f32 v[68:69], v[8:9], v[42:43], v[68:69] op_sel:[0,1,0] op_sel_hi:[1,1,1] neg_lo:[1,0,0] neg_hi:[1,0,0]
	v_pk_fma_f32 v[70:71], v[10:11], v[42:43], v[70:71] op_sel:[0,1,0] op_sel_hi:[1,1,1] neg_lo:[1,0,0] neg_hi:[1,0,0]
	ds_read_b128 v[8:11], v251 offset:4256
	s_waitcnt lgkmcnt(13)
	v_pk_fma_f32 v[72:73], v[12:13], v[42:43], v[72:73] op_sel:[0,1,0] op_sel_hi:[1,1,1] neg_lo:[1,0,0] neg_hi:[1,0,0]
	v_pk_fma_f32 v[74:75], v[14:15], v[42:43], v[74:75] op_sel:[0,1,0] op_sel_hi:[1,1,1] neg_lo:[1,0,0] neg_hi:[1,0,0]
	ds_read_b128 v[12:15], v251 offset:4272
	s_waitcnt lgkmcnt(13)
	v_pk_fma_f32 v[76:77], v[16:17], v[42:43], v[76:77] op_sel:[0,1,0] op_sel_hi:[1,1,1] neg_lo:[1,0,0] neg_hi:[1,0,0]
	v_pk_fma_f32 v[78:79], v[18:19], v[42:43], v[78:79] op_sel:[0,1,0] op_sel_hi:[1,1,1] neg_lo:[1,0,0] neg_hi:[1,0,0]
	ds_read_b128 v[16:19], v251 offset:4288
	s_waitcnt lgkmcnt(13)
	v_pk_fma_f32 v[80:81], v[20:21], v[42:43], v[80:81] op_sel:[0,1,0] op_sel_hi:[1,1,1] neg_lo:[1,0,0] neg_hi:[1,0,0]
	v_pk_fma_f32 v[82:83], v[22:23], v[42:43], v[82:83] op_sel:[0,1,0] op_sel_hi:[1,1,1] neg_lo:[1,0,0] neg_hi:[1,0,0]
	ds_read_b128 v[20:23], v251 offset:4304
	s_waitcnt lgkmcnt(13)
	v_pk_fma_f32 v[84:85], v[24:25], v[42:43], v[84:85] op_sel:[0,1,0] op_sel_hi:[1,1,1] neg_lo:[1,0,0] neg_hi:[1,0,0]
	v_pk_fma_f32 v[86:87], v[26:27], v[42:43], v[86:87] op_sel:[0,1,0] op_sel_hi:[1,1,1] neg_lo:[1,0,0] neg_hi:[1,0,0]
	ds_read_b128 v[24:27], v251 offset:4320
	s_waitcnt lgkmcnt(13)
	v_pk_fma_f32 v[88:89], v[28:29], v[42:43], v[88:89] op_sel:[0,1,0] op_sel_hi:[1,1,1] neg_lo:[1,0,0] neg_hi:[1,0,0]
	v_pk_fma_f32 v[90:91], v[30:31], v[42:43], v[90:91] op_sel:[0,1,0] op_sel_hi:[1,1,1] neg_lo:[1,0,0] neg_hi:[1,0,0]
	ds_read_b128 v[28:31], v251 offset:4336
	s_waitcnt lgkmcnt(13)
	v_pk_fma_f32 v[92:93], v[126:127], v[42:43], v[92:93] op_sel:[0,1,0] op_sel_hi:[1,1,1] neg_lo:[1,0,0] neg_hi:[1,0,0]
	v_pk_fma_f32 v[94:95], v[128:129], v[42:43], v[94:95] op_sel:[0,1,0] op_sel_hi:[1,1,1] neg_lo:[1,0,0] neg_hi:[1,0,0]
	ds_read_b128 v[126:129], v251 offset:4400
	s_waitcnt lgkmcnt(13)
	v_fma_f32 v45, -v231, v44, v45
	v_pk_fma_f32 v[46:47], v[232:233], v[44:45], v[46:47] op_sel:[0,0,0] op_sel_hi:[1,0,1] neg_lo:[1,0,0] neg_hi:[1,0,0]
	ds_read_b128 v[230:233], v251 offset:4416
	s_waitcnt lgkmcnt(13)
	v_pk_fma_f32 v[48:49], v[234:235], v[44:45], v[48:49] op_sel:[0,0,0] op_sel_hi:[1,0,1] neg_lo:[1,0,0] neg_hi:[1,0,0]
	v_pk_fma_f32 v[50:51], v[236:237], v[44:45], v[50:51] op_sel:[0,0,0] op_sel_hi:[1,0,1] neg_lo:[1,0,0] neg_hi:[1,0,0]
	ds_read_b128 v[234:237], v251 offset:4432
	s_waitcnt lgkmcnt(13)
; #define PG8_LAS __attribute__((address_space(3)))
; __device__ __forceinline__ void solve64(float (&x)[64], const PG8_LAS float* sLt) {
;     f32x4 cur[16];
; #pragma unroll
;     for (int i4 = 0; i4 < 16; ++i4) cur[i4] = *(const PG8_LAS f32x4*)(sLt + 4 * i4);
;     asm volatile("" ::: "memory");
; #pragma unroll
;     for (int j = 0; j < 63; ++j) {
;         const float xj = x[j];
; #pragma unroll
;         for (int i4 = (j + 1) / 4; i4 < 16; ++i4) {
;             if (4 * i4 + 0 > j) x[4 * i4 + 0] -= cur[i4][0] * xj;
;             if (4 * i4 + 1 > j) x[4 * i4 + 1] -= cur[i4][1] * xj;
;             if (4 * i4 + 2 > j) x[4 * i4 + 2] -= cur[i4][2] * xj;
;             if (4 * i4 + 3 > j) x[4 * i4 + 3] -= cur[i4][3] * xj;
;             if (j + 1 < 63 && i4 >= (j + 2) / 4) cur[i4] = *(const PG8_LAS f32x4*)(sLt + (j + 1) * 64 + 4 * i4); }
;         asm volatile("" ::: "memory");
;     }
	v_pk_fma_f32 v[52:53], v[238:239], v[44:45], v[52:53] op_sel:[0,0,0] op_sel_hi:[1,0,1] neg_lo:[1,0,0] neg_hi:[1,0,0]
	v_pk_fma_f32 v[54:55], v[240:241], v[44:45], v[54:55] op_sel:[0,0,0] op_sel_hi:[1,0,1] neg_lo:[1,0,0] neg_hi:[1,0,0]
	ds_read_b128 v[238:241], v251 offset:4448
	s_waitcnt lgkmcnt(13)
	v_pk_fma_f32 v[56:57], v[242:243], v[44:45], v[56:57] op_sel:[0,0,0] op_sel_hi:[1,0,1] neg_lo:[1,0,0] neg_hi:[1,0,0]
	v_pk_fma_f32 v[58:59], v[244:245], v[44:45], v[58:59] op_sel:[0,0,0] op_sel_hi:[1,0,1] neg_lo:[1,0,0] neg_hi:[1,0,0]
	ds_read_b128 v[242:245], v251 offset:4464
	s_waitcnt lgkmcnt(13)
	v_pk_fma_f32 v[60:61], v[246:247], v[44:45], v[60:61] op_sel:[0,0,0] op_sel_hi:[1,0,1] neg_lo:[1,0,0] neg_hi:[1,0,0]
	v_pk_fma_f32 v[62:63], v[248:249], v[44:45], v[62:63] op_sel:[0,0,0] op_sel_hi:[1,0,1] neg_lo:[1,0,0] neg_hi:[1,0,0]
	ds_read_b128 v[246:249], v251 offset:4480
	s_waitcnt lgkmcnt(13)
	v_pk_fma_f32 v[64:65], v[0:1], v[44:45], v[64:65] op_sel:[0,0,0] op_sel_hi:[1,0,1] neg_lo:[1,0,0] neg_hi:[1,0,0]
	v_pk_fma_f32 v[66:67], v[2:3], v[44:45], v[66:67] op_sel:[0,0,0] op_sel_hi:[1,0,1] neg_lo:[1,0,0] neg_hi:[1,0,0]
	ds_read_b128 v[0:3], v251 offset:4496
	s_waitcnt lgkmcnt(13)
	v_pk_fma_f32 v[68:69], v[4:5], v[44:45], v[68:69] op_sel:[0,0,0] op_sel_hi:[1,0,1] neg_lo:[1,0,0] neg_hi:[1,0,0]
	v_pk_fma_f32 v[70:71], v[6:7], v[44:45], v[70:71] op_sel:[0,0,0] op_sel_hi:[1,0,1] neg_lo:[1,0,0] neg_hi:[1,0,0]
	ds_read_b128 v[4:7], v251 offset:4512
	s_waitcnt lgkmcnt(13)
	v_pk_fma_f32 v[72:73], v[8:9], v[44:45], v[72:73] op_sel:[0,0,0] op_sel_hi:[1,0,1] neg_lo:[1,0,0] neg_hi:[1,0,0]
	v_pk_fma_f32 v[74:75], v[10:11], v[44:45], v[74:75] op_sel:[0,0,0] op_sel_hi:[1,0,1] neg_lo:[1,0,0] neg_hi:[1,0,0]
	ds_read_b128 v[8:11], v251 offset:4528
	s_waitcnt lgkmcnt(13)
	v_pk_fma_f32 v[76:77], v[12:13], v[44:45], v[76:77] op_sel:[0,0,0] op_sel_hi:[1,0,1] neg_lo:[1,0,0] neg_hi:[1,0,0]
	v_pk_fma_f32 v[78:79], v[14:15], v[44:45], v[78:79] op_sel:[0,0,0] op_sel_hi:[1,0,1] neg_lo:[1,0,0] neg_hi:[1,0,0]
	ds_read_b128 v[12:15], v251 offset:4544
	s_waitcnt lgkmcnt(13)
	v_pk_fma_f32 v[80:81], v[16:17], v[44:45], v[80:81] op_sel:[0,0,0] op_sel_hi:[1,0,1] neg_lo:[1,0,0] neg_hi:[1,0,0]
	v_pk_fma_f32 v[82:83], v[18:19], v[44:45], v[82:83] op_sel:[0,0,0] op_sel_hi:[1,0,1] neg_lo:[1,0,0] neg_hi:[1,0,0]
	ds_read_b128 v[16:19], v251 offset:4560
	s_waitcnt lgkmcnt(13)
	v_pk_fma_f32 v[84:85], v[20:21], v[44:45], v[84:85] op_sel:[0,0,0] op_sel_hi:[1,0,1] neg_lo:[1,0,0] neg_hi:[1,0,0]
	v_pk_fma_f32 v[86:87], v[22:23], v[44:45], v[86:87] op_sel:[0,0,0] op_sel_hi:[1,0,1] neg_lo:[1,0,0] neg_hi:[1,0,0]
	ds_read_b128 v[20:23], v251 offset:4576
	s_waitcnt lgkmcnt(13)
	v_pk_fma_f32 v[88:89], v[24:25], v[44:45], v[88:89] op_sel:[0,0,0] op_sel_hi:[1,0,1] neg_lo:[1,0,0] neg_hi:[1,0,0]
	v_pk_fma_f32 v[90:91], v[26:27], v[44:45], v[90:91] op_sel:[0,0,0] op_sel_hi:[1,0,1] neg_lo:[1,0,0] neg_hi:[1,0,0]
	ds_read_b128 v[24:27], v251 offset:4592
	s_waitcnt lgkmcnt(13)
	v_pk_fma_f32 v[92:93], v[28:29], v[44:45], v[92:93] op_sel:[0,0,0] op_sel_hi:[1,0,1] neg_lo:[1,0,0] neg_hi:[1,0,0]
	v_pk_fma_f32 v[94:95], v[30:31], v[44:45], v[94:95] op_sel:[0,0,0] op_sel_hi:[1,0,1] neg_lo:[1,0,0] neg_hi:[1,0,0]
	ds_read_b128 v[28:31], v251 offset:4656
	s_waitcnt lgkmcnt(13)
	v_pk_fma_f32 v[46:47], v[128:129], v[44:45], v[46:47] op_sel:[0,1,0] op_sel_hi:[1,1,1] neg_lo:[1,0,0] neg_hi:[1,0,0]
	ds_read_b128 v[126:129], v251 offset:4672
	s_waitcnt lgkmcnt(13)
	v_pk_fma_f32 v[48:49], v[230:231], v[44:45], v[48:49] op_sel:[0,1,0] op_sel_hi:[1,1,1] neg_lo:[1,0,0] neg_hi:[1,0,0]
	v_pk_fma_f32 v[50:51], v[232:233], v[44:45], v[50:51] op_sel:[0,1,0] op_sel_hi:[1,1,1] neg_lo:[1,0,0] neg_hi:[1,0,0]
	ds_read_b128 v[230:233], v251 offset:4688
	s_waitcnt lgkmcnt(13)
	v_pk_fma_f32 v[52:53], v[234:235], v[44:45], v[52:53] op_sel:[0,1,0] op_sel_hi:[1,1,1] neg_lo:[1,0,0] neg_hi:[1,0,0]
	v_pk_fma_f32 v[54:55], v[236:237], v[44:45], v[54:55] op_sel:[0,1,0] op_sel_hi:[1,1,1] neg_lo:[1,0,0] neg_hi:[1,0,0]
	ds_read_b128 v[234:237], v251 offset:4704
	s_waitcnt lgkmcnt(13)
	v_pk_fma_f32 v[56:57], v[238:239], v[44:45], v[56:57] op_sel:[0,1,0] op_sel_hi:[1,1,1] neg_lo:[1,0,0] neg_hi:[1,0,0]
	v_pk_fma_f32 v[58:59], v[240:241], v[44:45], v[58:59] op_sel:[0,1,0] op_sel_hi:[1,1,1] neg_lo:[1,0,0] neg_hi:[1,0,0]
	ds_read_b128 v[238:241], v251 offset:4720
	s_waitcnt lgkmcnt(13)
	v_pk_fma_f32 v[60:61], v[242:243], v[44:45], v[60:61] op_sel:[0,1,0] op_sel_hi:[1,1,1] neg_lo:[1,0,0] neg_hi:[1,0,0]
	v_pk_fma_f32 v[62:63], v[244:245], v[44:45], v[62:63] op_sel:[0,1,0] op_sel_hi:[1,1,1] neg_lo:[1,0,0] neg_hi:[1,0,0]
	ds_read_b128 v[242:245], v251 offset:4736
	s_waitcnt lgkmcnt(13)
	v_pk_fma_f32 v[64:65], v[246:247], v[44:45], v[64:65] op_sel:[0,1,0] op_sel_hi:[1,1,1] neg_lo:[1,0,0] neg_hi:[1,0,0]
	v_pk_fma_f32 v[66:67], v[248:249], v[44:45], v[66:67] op_sel:[0,1,0] op_sel_hi:[1,1,1] neg_lo:[1,0,0] neg_hi:[1,0,0]
	ds_read_b128 v[246:249], v251 offset:4752
	s_waitcnt lgkmcnt(13)
	v_pk_fma_f32 v[68:69], v[0:1], v[44:45], v[68:69] op_sel:[0,1,0] op_sel_hi:[1,1,1] neg_lo:[1,0,0] neg_hi:[1,0,0]
	v_pk_fma_f32 v[70:71], v[2:3], v[44:45], v[70:71] op_sel:[0,1,0] op_sel_hi:[1,1,1] neg_lo:[1,0,0] neg_hi:[1,0,0]
	ds_read_b128 v[0:3], v251 offset:4768
	s_waitcnt lgkmcnt(13)
	v_pk_fma_f32 v[72:73], v[4:5], v[44:45], v[72:73] op_sel:[0,1,0] op_sel_hi:[1,1,1] neg_lo:[1,0,0] neg_hi:[1,0,0]
	v_pk_fma_f32 v[74:75], v[6:7], v[44:45], v[74:75] op_sel:[0,1,0] op_sel_hi:[1,1,1] neg_lo:[1,0,0] neg_hi:[1,0,0]
	ds_read_b128 v[4:7], v251 offset:4784
	s_waitcnt lgkmcnt(13)
; #define PG8_LAS __attribute__((address_space(3)))
; __device__ __forceinline__ void solve64(float (&x)[64], const PG8_LAS float* sLt) {
;     f32x4 cur[16];
; #pragma unroll
;     for (int i4 = 0; i4 < 16; ++i4) cur[i4] = *(const PG8_LAS f32x4*)(sLt + 4 * i4);
;     asm volatile("" ::: "memory");
; #pragma unroll
;     for (int j = 0; j < 63; ++j) {
;         const float xj = x[j];
; #pragma unroll
;         for (int i4 = (j + 1) / 4; i4 < 16; ++i4) {
;             if (4 * i4 + 0 > j) x[4 * i4 + 0] -= cur[i4][0] * xj;
;             if (4 * i4 + 1 > j) x[4 * i4 + 1] -= cur[i4][1] * xj;
;             if (4 * i4 + 2 > j) x[4 * i4 + 2] -= cur[i4][2] * xj;
;             if (4 * i4 + 3 > j) x[4 * i4 + 3] -= cur[i4][3] * xj;
;             if (j + 1 < 63 && i4 >= (j + 2) / 4) cur[i4] = *(const PG8_LAS f32x4*)(sLt + (j + 1) * 64 + 4 * i4); }
;         asm volatile("" ::: "memory");
;     }
	v_pk_fma_f32 v[76:77], v[8:9], v[44:45], v[76:77] op_sel:[0,1,0] op_sel_hi:[1,1,1] neg_lo:[1,0,0] neg_hi:[1,0,0]
	v_pk_fma_f32 v[78:79], v[10:11], v[44:45], v[78:79] op_sel:[0,1,0] op_sel_hi:[1,1,1] neg_lo:[1,0,0] neg_hi:[1,0,0]
	ds_read_b128 v[8:11], v251 offset:4800
	s_waitcnt lgkmcnt(13)
	v_pk_fma_f32 v[80:81], v[12:13], v[44:45], v[80:81] op_sel:[0,1,0] op_sel_hi:[1,1,1] neg_lo:[1,0,0] neg_hi:[1,0,0]
	v_pk_fma_f32 v[82:83], v[14:15], v[44:45], v[82:83] op_sel:[0,1,0] op_sel_hi:[1,1,1] neg_lo:[1,0,0] neg_hi:[1,0,0]
	ds_read_b128 v[12:15], v251 offset:4816
	s_waitcnt lgkmcnt(13)
	v_pk_fma_f32 v[84:85], v[16:17], v[44:45], v[84:85] op_sel:[0,1,0] op_sel_hi:[1,1,1] neg_lo:[1,0,0] neg_hi:[1,0,0]
	v_pk_fma_f32 v[86:87], v[18:19], v[44:45], v[86:87] op_sel:[0,1,0] op_sel_hi:[1,1,1] neg_lo:[1,0,0] neg_hi:[1,0,0]
	ds_read_b128 v[16:19], v251 offset:4832
	s_waitcnt lgkmcnt(13)
	v_pk_fma_f32 v[88:89], v[20:21], v[44:45], v[88:89] op_sel:[0,1,0] op_sel_hi:[1,1,1] neg_lo:[1,0,0] neg_hi:[1,0,0]
	v_pk_fma_f32 v[90:91], v[22:23], v[44:45], v[90:91] op_sel:[0,1,0] op_sel_hi:[1,1,1] neg_lo:[1,0,0] neg_hi:[1,0,0]
	ds_read_b128 v[20:23], v251 offset:4848
	s_waitcnt lgkmcnt(13)
	v_pk_fma_f32 v[92:93], v[24:25], v[44:45], v[92:93] op_sel:[0,1,0] op_sel_hi:[1,1,1] neg_lo:[1,0,0] neg_hi:[1,0,0]
	v_pk_fma_f32 v[94:95], v[26:27], v[44:45], v[94:95] op_sel:[0,1,0] op_sel_hi:[1,1,1] neg_lo:[1,0,0] neg_hi:[1,0,0]
	ds_read_b128 v[24:27], v251 offset:4928
	s_waitcnt lgkmcnt(13)
	v_fma_f32 v47, -v31, v46, v47
	ds_read_b128 v[28:31], v251 offset:4944
	s_waitcnt lgkmcnt(13)
	v_pk_fma_f32 v[48:49], v[126:127], v[46:47], v[48:49] op_sel:[0,0,0] op_sel_hi:[1,0,1] neg_lo:[1,0,0] neg_hi:[1,0,0]
	v_pk_fma_f32 v[50:51], v[128:129], v[46:47], v[50:51] op_sel:[0,0,0] op_sel_hi:[1,0,1] neg_lo:[1,0,0] neg_hi:[1,0,0]
	ds_read_b128 v[126:129], v251 offset:4960
	s_waitcnt lgkmcnt(13)
	v_pk_fma_f32 v[52:53], v[230:231], v[46:47], v[52:53] op_sel:[0,0,0] op_sel_hi:[1,0,1] neg_lo:[1,0,0] neg_hi:[1,0,0]
	v_pk_fma_f32 v[54:55], v[232:233], v[46:47], v[54:55] op_sel:[0,0,0] op_sel_hi:[1,0,1] neg_lo:[1,0,0] neg_hi:[1,0,0]
	ds_read_b128 v[230:233], v251 offset:4976
	s_waitcnt lgkmcnt(13)
	v_pk_fma_f32 v[56:57], v[234:235], v[46:47], v[56:57] op_sel:[0,0,0] op_sel_hi:[1,0,1] neg_lo:[1,0,0] neg_hi:[1,0,0]
	v_pk_fma_f32 v[58:59], v[236:237], v[46:47], v[58:59] op_sel:[0,0,0] op_sel_hi:[1,0,1] neg_lo:[1,0,0] neg_hi:[1,0,0]
	ds_read_b128 v[234:237], v251 offset:4992
	s_waitcnt lgkmcnt(13)
	v_pk_fma_f32 v[60:61], v[238:239], v[46:47], v[60:61] op_sel:[0,0,0] op_sel_hi:[1,0,1] neg_lo:[1,0,0] neg_hi:[1,0,0]
	v_pk_fma_f32 v[62:63], v[240:241], v[46:47], v[62:63] op_sel:[0,0,0] op_sel_hi:[1,0,1] neg_lo:[1,0,0] neg_hi:[1,0,0]
	ds_read_b128 v[238:241], v251 offset:5008
	s_waitcnt lgkmcnt(13)
	v_pk_fma_f32 v[64:65], v[242:243], v[46:47], v[64:65] op_sel:[0,0,0] op_sel_hi:[1,0,1] neg_lo:[1,0,0] neg_hi:[1,0,0]
	v_pk_fma_f32 v[66:67], v[244:245], v[46:47], v[66:67] op_sel:[0,0,0] op_sel_hi:[1,0,1] neg_lo:[1,0,0] neg_hi:[1,0,0]
	ds_read_b128 v[242:245], v251 offset:5024
	s_waitcnt lgkmcnt(13)
	v_pk_fma_f32 v[68:69], v[246:247], v[46:47], v[68:69] op_sel:[0,0,0] op_sel_hi:[1,0,1] neg_lo:[1,0,0] neg_hi:[1,0,0]
	v_pk_fma_f32 v[70:71], v[248:249], v[46:47], v[70:71] op_sel:[0,0,0] op_sel_hi:[1,0,1] neg_lo:[1,0,0] neg_hi:[1,0,0]
	ds_read_b128 v[246:249], v251 offset:5040
	s_waitcnt lgkmcnt(13)
	v_pk_fma_f32 v[72:73], v[0:1], v[46:47], v[72:73] op_sel:[0,0,0] op_sel_hi:[1,0,1] neg_lo:[1,0,0] neg_hi:[1,0,0]
	v_pk_fma_f32 v[74:75], v[2:3], v[46:47], v[74:75] op_sel:[0,0,0] op_sel_hi:[1,0,1] neg_lo:[1,0,0] neg_hi:[1,0,0]
	ds_read_b128 v[0:3], v251 offset:5056
	s_waitcnt lgkmcnt(13)
	v_pk_fma_f32 v[76:77], v[4:5], v[46:47], v[76:77] op_sel:[0,0,0] op_sel_hi:[1,0,1] neg_lo:[1,0,0] neg_hi:[1,0,0]
	v_pk_fma_f32 v[78:79], v[6:7], v[46:47], v[78:79] op_sel:[0,0,0] op_sel_hi:[1,0,1] neg_lo:[1,0,0] neg_hi:[1,0,0]
	ds_read_b128 v[4:7], v251 offset:5072
	s_waitcnt lgkmcnt(13)
	v_pk_fma_f32 v[80:81], v[8:9], v[46:47], v[80:81] op_sel:[0,0,0] op_sel_hi:[1,0,1] neg_lo:[1,0,0] neg_hi:[1,0,0]
	v_pk_fma_f32 v[82:83], v[10:11], v[46:47], v[82:83] op_sel:[0,0,0] op_sel_hi:[1,0,1] neg_lo:[1,0,0] neg_hi:[1,0,0]
	ds_read_b128 v[8:11], v251 offset:5088
	s_waitcnt lgkmcnt(13)
	v_pk_fma_f32 v[84:85], v[12:13], v[46:47], v[84:85] op_sel:[0,0,0] op_sel_hi:[1,0,1] neg_lo:[1,0,0] neg_hi:[1,0,0]
	v_pk_fma_f32 v[86:87], v[14:15], v[46:47], v[86:87] op_sel:[0,0,0] op_sel_hi:[1,0,1] neg_lo:[1,0,0] neg_hi:[1,0,0]
	ds_read_b128 v[12:15], v251 offset:5104
	s_waitcnt lgkmcnt(13)
	v_pk_fma_f32 v[88:89], v[16:17], v[46:47], v[88:89] op_sel:[0,0,0] op_sel_hi:[1,0,1] neg_lo:[1,0,0] neg_hi:[1,0,0]
	v_pk_fma_f32 v[90:91], v[18:19], v[46:47], v[90:91] op_sel:[0,0,0] op_sel_hi:[1,0,1] neg_lo:[1,0,0] neg_hi:[1,0,0]
	ds_read_b128 v[16:19], v251 offset:5184
	s_waitcnt lgkmcnt(13)
	v_pk_fma_f32 v[92:93], v[20:21], v[46:47], v[92:93] op_sel:[0,0,0] op_sel_hi:[1,0,1] neg_lo:[1,0,0] neg_hi:[1,0,0]
	v_pk_fma_f32 v[94:95], v[22:23], v[46:47], v[94:95] op_sel:[0,0,0] op_sel_hi:[1,0,1] neg_lo:[1,0,0] neg_hi:[1,0,0]
	ds_read_b128 v[20:23], v251 offset:5200
	s_waitcnt lgkmcnt(13)
	v_pk_fma_f32 v[48:49], v[24:25], v[46:47], v[48:49] op_sel:[0,1,0] op_sel_hi:[1,1,1] neg_lo:[1,0,0] neg_hi:[1,0,0]
	v_pk_fma_f32 v[50:51], v[26:27], v[46:47], v[50:51] op_sel:[0,1,0] op_sel_hi:[1,1,1] neg_lo:[1,0,0] neg_hi:[1,0,0]
	ds_read_b128 v[24:27], v251 offset:5216
	s_waitcnt lgkmcnt(13)
	v_pk_fma_f32 v[52:53], v[28:29], v[46:47], v[52:53] op_sel:[0,1,0] op_sel_hi:[1,1,1] neg_lo:[1,0,0] neg_hi:[1,0,0]
	v_pk_fma_f32 v[54:55], v[30:31], v[46:47], v[54:55] op_sel:[0,1,0] op_sel_hi:[1,1,1] neg_lo:[1,0,0] neg_hi:[1,0,0]
	ds_read_b128 v[28:31], v251 offset:5232
	s_waitcnt lgkmcnt(13)
; #define PG8_LAS __attribute__((address_space(3)))
; __device__ __forceinline__ void solve64(float (&x)[64], const PG8_LAS float* sLt) {
;     f32x4 cur[16];
; #pragma unroll
;     for (int i4 = 0; i4 < 16; ++i4) cur[i4] = *(const PG8_LAS f32x4*)(sLt + 4 * i4);
;     asm volatile("" ::: "memory");
; #pragma unroll
;     for (int j = 0; j < 63; ++j) {
;         const float xj = x[j];
; #pragma unroll
;         for (int i4 = (j + 1) / 4; i4 < 16; ++i4) {
;             if (4 * i4 + 0 > j) x[4 * i4 + 0] -= cur[i4][0] * xj;
;             if (4 * i4 + 1 > j) x[4 * i4 + 1] -= cur[i4][1] * xj;
;             if (4 * i4 + 2 > j) x[4 * i4 + 2] -= cur[i4][2] * xj;
;             if (4 * i4 + 3 > j) x[4 * i4 + 3] -= cur[i4][3] * xj;
;             if (j + 1 < 63 && i4 >= (j + 2) / 4) cur[i4] = *(const PG8_LAS f32x4*)(sLt + (j + 1) * 64 + 4 * i4); }
;         asm volatile("" ::: "memory");
;     }
	v_pk_fma_f32 v[56:57], v[126:127], v[46:47], v[56:57] op_sel:[0,1,0] op_sel_hi:[1,1,1] neg_lo:[1,0,0] neg_hi:[1,0,0]
	v_pk_fma_f32 v[58:59], v[128:129], v[46:47], v[58:59] op_sel:[0,1,0] op_sel_hi:[1,1,1] neg_lo:[1,0,0] neg_hi:[1,0,0]
	ds_read_b128 v[126:129], v251 offset:5248
	s_waitcnt lgkmcnt(13)
	v_pk_fma_f32 v[60:61], v[230:231], v[46:47], v[60:61] op_sel:[0,1,0] op_sel_hi:[1,1,1] neg_lo:[1,0,0] neg_hi:[1,0,0]
	v_pk_fma_f32 v[62:63], v[232:233], v[46:47], v[62:63] op_sel:[0,1,0] op_sel_hi:[1,1,1] neg_lo:[1,0,0] neg_hi:[1,0,0]
	ds_read_b128 v[230:233], v251 offset:5264
	s_waitcnt lgkmcnt(13)
	v_pk_fma_f32 v[64:65], v[234:235], v[46:47], v[64:65] op_sel:[0,1,0] op_sel_hi:[1,1,1] neg_lo:[1,0,0] neg_hi:[1,0,0]
	v_pk_fma_f32 v[66:67], v[236:237], v[46:47], v[66:67] op_sel:[0,1,0] op_sel_hi:[1,1,1] neg_lo:[1,0,0] neg_hi:[1,0,0]
	ds_read_b128 v[234:237], v251 offset:5280
	s_waitcnt lgkmcnt(13)
	v_pk_fma_f32 v[68:69], v[238:239], v[46:47], v[68:69] op_sel:[0,1,0] op_sel_hi:[1,1,1] neg_lo:[1,0,0] neg_hi:[1,0,0]
	v_pk_fma_f32 v[70:71], v[240:241], v[46:47], v[70:71] op_sel:[0,1,0] op_sel_hi:[1,1,1] neg_lo:[1,0,0] neg_hi:[1,0,0]
	ds_read_b128 v[238:241], v251 offset:5296
	s_waitcnt lgkmcnt(13)
	v_pk_fma_f32 v[72:73], v[242:243], v[46:47], v[72:73] op_sel:[0,1,0] op_sel_hi:[1,1,1] neg_lo:[1,0,0] neg_hi:[1,0,0]
	v_pk_fma_f32 v[74:75], v[244:245], v[46:47], v[74:75] op_sel:[0,1,0] op_sel_hi:[1,1,1] neg_lo:[1,0,0] neg_hi:[1,0,0]
	ds_read_b128 v[242:245], v251 offset:5312
	s_waitcnt lgkmcnt(13)
	v_pk_fma_f32 v[76:77], v[246:247], v[46:47], v[76:77] op_sel:[0,1,0] op_sel_hi:[1,1,1] neg_lo:[1,0,0] neg_hi:[1,0,0]
	v_pk_fma_f32 v[78:79], v[248:249], v[46:47], v[78:79] op_sel:[0,1,0] op_sel_hi:[1,1,1] neg_lo:[1,0,0] neg_hi:[1,0,0]
	ds_read_b128 v[246:249], v251 offset:5328
	s_waitcnt lgkmcnt(13)
	v_pk_fma_f32 v[80:81], v[0:1], v[46:47], v[80:81] op_sel:[0,1,0] op_sel_hi:[1,1,1] neg_lo:[1,0,0] neg_hi:[1,0,0]
	v_pk_fma_f32 v[82:83], v[2:3], v[46:47], v[82:83] op_sel:[0,1,0] op_sel_hi:[1,1,1] neg_lo:[1,0,0] neg_hi:[1,0,0]
	ds_read_b128 v[0:3], v251 offset:5344
	s_waitcnt lgkmcnt(13)
	v_pk_fma_f32 v[84:85], v[4:5], v[46:47], v[84:85] op_sel:[0,1,0] op_sel_hi:[1,1,1] neg_lo:[1,0,0] neg_hi:[1,0,0]
	v_pk_fma_f32 v[86:87], v[6:7], v[46:47], v[86:87] op_sel:[0,1,0] op_sel_hi:[1,1,1] neg_lo:[1,0,0] neg_hi:[1,0,0]
	ds_read_b128 v[4:7], v251 offset:5360
	s_waitcnt lgkmcnt(13)
	v_pk_fma_f32 v[88:89], v[8:9], v[46:47], v[88:89] op_sel:[0,1,0] op_sel_hi:[1,1,1] neg_lo:[1,0,0] neg_hi:[1,0,0]
	v_pk_fma_f32 v[90:91], v[10:11], v[46:47], v[90:91] op_sel:[0,1,0] op_sel_hi:[1,1,1] neg_lo:[1,0,0] neg_hi:[1,0,0]
	ds_read_b128 v[8:11], v251 offset:5440
	s_waitcnt lgkmcnt(13)
	v_pk_fma_f32 v[92:93], v[12:13], v[46:47], v[92:93] op_sel:[0,1,0] op_sel_hi:[1,1,1] neg_lo:[1,0,0] neg_hi:[1,0,0]
	v_pk_fma_f32 v[94:95], v[14:15], v[46:47], v[94:95] op_sel:[0,1,0] op_sel_hi:[1,1,1] neg_lo:[1,0,0] neg_hi:[1,0,0]
	ds_read_b128 v[12:15], v251 offset:5456
	s_waitcnt lgkmcnt(13)
	v_fma_f32 v49, -v17, v48, v49
	v_pk_fma_f32 v[50:51], v[18:19], v[48:49], v[50:51] op_sel:[0,0,0] op_sel_hi:[1,0,1] neg_lo:[1,0,0] neg_hi:[1,0,0]
	ds_read_b128 v[16:19], v251 offset:5472
	s_waitcnt lgkmcnt(13)
	v_pk_fma_f32 v[52:53], v[20:21], v[48:49], v[52:53] op_sel:[0,0,0] op_sel_hi:[1,0,1] neg_lo:[1,0,0] neg_hi:[1,0,0]
	v_pk_fma_f32 v[54:55], v[22:23], v[48:49], v[54:55] op_sel:[0,0,0] op_sel_hi:[1,0,1] neg_lo:[1,0,0] neg_hi:[1,0,0]
	ds_read_b128 v[20:23], v251 offset:5488
	s_waitcnt lgkmcnt(13)
	v_pk_fma_f32 v[56:57], v[24:25], v[48:49], v[56:57] op_sel:[0,0,0] op_sel_hi:[1,0,1] neg_lo:[1,0,0] neg_hi:[1,0,0]
	v_pk_fma_f32 v[58:59], v[26:27], v[48:49], v[58:59] op_sel:[0,0,0] op_sel_hi:[1,0,1] neg_lo:[1,0,0] neg_hi:[1,0,0]
	ds_read_b128 v[24:27], v251 offset:5504
	s_waitcnt lgkmcnt(13)
	v_pk_fma_f32 v[60:61], v[28:29], v[48:49], v[60:61] op_sel:[0,0,0] op_sel_hi:[1,0,1] neg_lo:[1,0,0] neg_hi:[1,0,0]
	v_pk_fma_f32 v[62:63], v[30:31], v[48:49], v[62:63] op_sel:[0,0,0] op_sel_hi:[1,0,1] neg_lo:[1,0,0] neg_hi:[1,0,0]
	ds_read_b128 v[28:31], v251 offset:5520
	s_waitcnt lgkmcnt(13)
	v_pk_fma_f32 v[64:65], v[126:127], v[48:49], v[64:65] op_sel:[0,0,0] op_sel_hi:[1,0,1] neg_lo:[1,0,0] neg_hi:[1,0,0]
	v_pk_fma_f32 v[66:67], v[128:129], v[48:49], v[66:67] op_sel:[0,0,0] op_sel_hi:[1,0,1] neg_lo:[1,0,0] neg_hi:[1,0,0]
	ds_read_b128 v[126:129], v251 offset:5536
	s_waitcnt lgkmcnt(13)
	v_pk_fma_f32 v[68:69], v[230:231], v[48:49], v[68:69] op_sel:[0,0,0] op_sel_hi:[1,0,1] neg_lo:[1,0,0] neg_hi:[1,0,0]
	v_pk_fma_f32 v[70:71], v[232:233], v[48:49], v[70:71] op_sel:[0,0,0] op_sel_hi:[1,0,1] neg_lo:[1,0,0] neg_hi:[1,0,0]
	ds_read_b128 v[230:233], v251 offset:5552
	s_waitcnt lgkmcnt(13)
	v_pk_fma_f32 v[72:73], v[234:235], v[48:49], v[72:73] op_sel:[0,0,0] op_sel_hi:[1,0,1] neg_lo:[1,0,0] neg_hi:[1,0,0]
	v_pk_fma_f32 v[74:75], v[236:237], v[48:49], v[74:75] op_sel:[0,0,0] op_sel_hi:[1,0,1] neg_lo:[1,0,0] neg_hi:[1,0,0]
	ds_read_b128 v[234:237], v251 offset:5568
	s_waitcnt lgkmcnt(13)
	v_pk_fma_f32 v[76:77], v[238:239], v[48:49], v[76:77] op_sel:[0,0,0] op_sel_hi:[1,0,1] neg_lo:[1,0,0] neg_hi:[1,0,0]
	v_pk_fma_f32 v[78:79], v[240:241], v[48:49], v[78:79] op_sel:[0,0,0] op_sel_hi:[1,0,1] neg_lo:[1,0,0] neg_hi:[1,0,0]
	ds_read_b128 v[238:241], v251 offset:5584
	s_waitcnt lgkmcnt(13)
	v_pk_fma_f32 v[80:81], v[242:243], v[48:49], v[80:81] op_sel:[0,0,0] op_sel_hi:[1,0,1] neg_lo:[1,0,0] neg_hi:[1,0,0]
	v_pk_fma_f32 v[82:83], v[244:245], v[48:49], v[82:83] op_sel:[0,0,0] op_sel_hi:[1,0,1] neg_lo:[1,0,0] neg_hi:[1,0,0]
	ds_read_b128 v[242:245], v251 offset:5600
	s_waitcnt lgkmcnt(13)
; #define PG8_LAS __attribute__((address_space(3)))
; __device__ __forceinline__ void solve64(float (&x)[64], const PG8_LAS float* sLt) {
;     f32x4 cur[16];
; #pragma unroll
;     for (int i4 = 0; i4 < 16; ++i4) cur[i4] = *(const PG8_LAS f32x4*)(sLt + 4 * i4);
;     asm volatile("" ::: "memory");
; #pragma unroll
;     for (int j = 0; j < 63; ++j) {
;         const float xj = x[j];
; #pragma unroll
;         for (int i4 = (j + 1) / 4; i4 < 16; ++i4) {
;             if (4 * i4 + 0 > j) x[4 * i4 + 0] -= cur[i4][0] * xj;
;             if (4 * i4 + 1 > j) x[4 * i4 + 1] -= cur[i4][1] * xj;
;             if (4 * i4 + 2 > j) x[4 * i4 + 2] -= cur[i4][2] * xj;
;             if (4 * i4 + 3 > j) x[4 * i4 + 3] -= cur[i4][3] * xj;
;             if (j + 1 < 63 && i4 >= (j + 2) / 4) cur[i4] = *(const PG8_LAS f32x4*)(sLt + (j + 1) * 64 + 4 * i4); }
;         asm volatile("" ::: "memory");
;     }
	v_pk_fma_f32 v[84:85], v[246:247], v[48:49], v[84:85] op_sel:[0,0,0] op_sel_hi:[1,0,1] neg_lo:[1,0,0] neg_hi:[1,0,0]
	v_pk_fma_f32 v[86:87], v[248:249], v[48:49], v[86:87] op_sel:[0,0,0] op_sel_hi:[1,0,1] neg_lo:[1,0,0] neg_hi:[1,0,0]
	ds_read_b128 v[246:249], v251 offset:5616
	s_waitcnt lgkmcnt(13)
	v_pk_fma_f32 v[88:89], v[0:1], v[48:49], v[88:89] op_sel:[0,0,0] op_sel_hi:[1,0,1] neg_lo:[1,0,0] neg_hi:[1,0,0]
	v_pk_fma_f32 v[90:91], v[2:3], v[48:49], v[90:91] op_sel:[0,0,0] op_sel_hi:[1,0,1] neg_lo:[1,0,0] neg_hi:[1,0,0]
	ds_read_b128 v[0:3], v251 offset:5696
	s_waitcnt lgkmcnt(13)
	v_pk_fma_f32 v[92:93], v[4:5], v[48:49], v[92:93] op_sel:[0,0,0] op_sel_hi:[1,0,1] neg_lo:[1,0,0] neg_hi:[1,0,0]
	v_pk_fma_f32 v[94:95], v[6:7], v[48:49], v[94:95] op_sel:[0,0,0] op_sel_hi:[1,0,1] neg_lo:[1,0,0] neg_hi:[1,0,0]
	ds_read_b128 v[4:7], v251 offset:5712
	s_waitcnt lgkmcnt(13)
	v_pk_fma_f32 v[50:51], v[10:11], v[48:49], v[50:51] op_sel:[0,1,0] op_sel_hi:[1,1,1] neg_lo:[1,0,0] neg_hi:[1,0,0]
	ds_read_b128 v[8:11], v251 offset:5728
	s_waitcnt lgkmcnt(13)
	v_pk_fma_f32 v[52:53], v[12:13], v[48:49], v[52:53] op_sel:[0,1,0] op_sel_hi:[1,1,1] neg_lo:[1,0,0] neg_hi:[1,0,0]
	v_pk_fma_f32 v[54:55], v[14:15], v[48:49], v[54:55] op_sel:[0,1,0] op_sel_hi:[1,1,1] neg_lo:[1,0,0] neg_hi:[1,0,0]
	ds_read_b128 v[12:15], v251 offset:5744
	s_waitcnt lgkmcnt(13)
	v_pk_fma_f32 v[56:57], v[16:17], v[48:49], v[56:57] op_sel:[0,1,0] op_sel_hi:[1,1,1] neg_lo:[1,0,0] neg_hi:[1,0,0]
	v_pk_fma_f32 v[58:59], v[18:19], v[48:49], v[58:59] op_sel:[0,1,0] op_sel_hi:[1,1,1] neg_lo:[1,0,0] neg_hi:[1,0,0]
	ds_read_b128 v[16:19], v251 offset:5760
	s_waitcnt lgkmcnt(13)
	v_pk_fma_f32 v[60:61], v[20:21], v[48:49], v[60:61] op_sel:[0,1,0] op_sel_hi:[1,1,1] neg_lo:[1,0,0] neg_hi:[1,0,0]
	v_pk_fma_f32 v[62:63], v[22:23], v[48:49], v[62:63] op_sel:[0,1,0] op_sel_hi:[1,1,1] neg_lo:[1,0,0] neg_hi:[1,0,0]
	ds_read_b128 v[20:23], v251 offset:5776
	s_waitcnt lgkmcnt(13)
	v_pk_fma_f32 v[64:65], v[24:25], v[48:49], v[64:65] op_sel:[0,1,0] op_sel_hi:[1,1,1] neg_lo:[1,0,0] neg_hi:[1,0,0]
	v_pk_fma_f32 v[66:67], v[26:27], v[48:49], v[66:67] op_sel:[0,1,0] op_sel_hi:[1,1,1] neg_lo:[1,0,0] neg_hi:[1,0,0]
	ds_read_b128 v[24:27], v251 offset:5792
	s_waitcnt lgkmcnt(13)
	v_pk_fma_f32 v[68:69], v[28:29], v[48:49], v[68:69] op_sel:[0,1,0] op_sel_hi:[1,1,1] neg_lo:[1,0,0] neg_hi:[1,0,0]
	v_pk_fma_f32 v[70:71], v[30:31], v[48:49], v[70:71] op_sel:[0,1,0] op_sel_hi:[1,1,1] neg_lo:[1,0,0] neg_hi:[1,0,0]
	ds_read_b128 v[28:31], v251 offset:5808
	s_waitcnt lgkmcnt(13)
	v_pk_fma_f32 v[72:73], v[126:127], v[48:49], v[72:73] op_sel:[0,1,0] op_sel_hi:[1,1,1] neg_lo:[1,0,0] neg_hi:[1,0,0]
	v_pk_fma_f32 v[74:75], v[128:129], v[48:49], v[74:75] op_sel:[0,1,0] op_sel_hi:[1,1,1] neg_lo:[1,0,0] neg_hi:[1,0,0]
	ds_read_b128 v[126:129], v251 offset:5824
	s_waitcnt lgkmcnt(13)
	v_pk_fma_f32 v[76:77], v[230:231], v[48:49], v[76:77] op_sel:[0,1,0] op_sel_hi:[1,1,1] neg_lo:[1,0,0] neg_hi:[1,0,0]
	v_pk_fma_f32 v[78:79], v[232:233], v[48:49], v[78:79] op_sel:[0,1,0] op_sel_hi:[1,1,1] neg_lo:[1,0,0] neg_hi:[1,0,0]
	ds_read_b128 v[230:233], v251 offset:5840
	s_waitcnt lgkmcnt(13)
	v_pk_fma_f32 v[80:81], v[234:235], v[48:49], v[80:81] op_sel:[0,1,0] op_sel_hi:[1,1,1] neg_lo:[1,0,0] neg_hi:[1,0,0]
	v_pk_fma_f32 v[82:83], v[236:237], v[48:49], v[82:83] op_sel:[0,1,0] op_sel_hi:[1,1,1] neg_lo:[1,0,0] neg_hi:[1,0,0]
	ds_read_b128 v[234:237], v251 offset:5856
	s_waitcnt lgkmcnt(13)
	v_pk_fma_f32 v[84:85], v[238:239], v[48:49], v[84:85] op_sel:[0,1,0] op_sel_hi:[1,1,1] neg_lo:[1,0,0] neg_hi:[1,0,0]
	v_pk_fma_f32 v[86:87], v[240:241], v[48:49], v[86:87] op_sel:[0,1,0] op_sel_hi:[1,1,1] neg_lo:[1,0,0] neg_hi:[1,0,0]
	ds_read_b128 v[238:241], v251 offset:5872
	s_waitcnt lgkmcnt(13)
	v_pk_fma_f32 v[88:89], v[242:243], v[48:49], v[88:89] op_sel:[0,1,0] op_sel_hi:[1,1,1] neg_lo:[1,0,0] neg_hi:[1,0,0]
	v_pk_fma_f32 v[90:91], v[244:245], v[48:49], v[90:91] op_sel:[0,1,0] op_sel_hi:[1,1,1] neg_lo:[1,0,0] neg_hi:[1,0,0]
	ds_read_b128 v[242:245], v251 offset:5968
	s_waitcnt lgkmcnt(13)
	v_pk_fma_f32 v[92:93], v[246:247], v[48:49], v[92:93] op_sel:[0,1,0] op_sel_hi:[1,1,1] neg_lo:[1,0,0] neg_hi:[1,0,0]
	v_pk_fma_f32 v[94:95], v[248:249], v[48:49], v[94:95] op_sel:[0,1,0] op_sel_hi:[1,1,1] neg_lo:[1,0,0] neg_hi:[1,0,0]
	ds_read_b128 v[246:249], v251 offset:5984
	s_waitcnt lgkmcnt(13)
	v_fma_f32 v51, -v3, v50, v51
	ds_read_b128 v[0:3], v251 offset:6000
	s_waitcnt lgkmcnt(13)
	v_pk_fma_f32 v[52:53], v[4:5], v[50:51], v[52:53] op_sel:[0,0,0] op_sel_hi:[1,0,1] neg_lo:[1,0,0] neg_hi:[1,0,0]
	v_pk_fma_f32 v[54:55], v[6:7], v[50:51], v[54:55] op_sel:[0,0,0] op_sel_hi:[1,0,1] neg_lo:[1,0,0] neg_hi:[1,0,0]
	ds_read_b128 v[4:7], v251 offset:6016
	s_waitcnt lgkmcnt(13)
	v_pk_fma_f32 v[56:57], v[8:9], v[50:51], v[56:57] op_sel:[0,0,0] op_sel_hi:[1,0,1] neg_lo:[1,0,0] neg_hi:[1,0,0]
	v_pk_fma_f32 v[58:59], v[10:11], v[50:51], v[58:59] op_sel:[0,0,0] op_sel_hi:[1,0,1] neg_lo:[1,0,0] neg_hi:[1,0,0]
	ds_read_b128 v[8:11], v251 offset:6032
	s_waitcnt lgkmcnt(13)
	v_pk_fma_f32 v[60:61], v[12:13], v[50:51], v[60:61] op_sel:[0,0,0] op_sel_hi:[1,0,1] neg_lo:[1,0,0] neg_hi:[1,0,0]
	v_pk_fma_f32 v[62:63], v[14:15], v[50:51], v[62:63] op_sel:[0,0,0] op_sel_hi:[1,0,1] neg_lo:[1,0,0] neg_hi:[1,0,0]
	ds_read_b128 v[12:15], v251 offset:6048
	s_waitcnt lgkmcnt(13)
	v_pk_fma_f32 v[64:65], v[16:17], v[50:51], v[64:65] op_sel:[0,0,0] op_sel_hi:[1,0,1] neg_lo:[1,0,0] neg_hi:[1,0,0]
	v_pk_fma_f32 v[66:67], v[18:19], v[50:51], v[66:67] op_sel:[0,0,0] op_sel_hi:[1,0,1] neg_lo:[1,0,0] neg_hi:[1,0,0]
	ds_read_b128 v[16:19], v251 offset:6064
	s_waitcnt lgkmcnt(13)
; #define PG8_LAS __attribute__((address_space(3)))
; __device__ __forceinline__ void solve64(float (&x)[64], const PG8_LAS float* sLt) {
;     f32x4 cur[16];
; #pragma unroll
;     for (int i4 = 0; i4 < 16; ++i4) cur[i4] = *(const PG8_LAS f32x4*)(sLt + 4 * i4);
;     asm volatile("" ::: "memory");
; #pragma unroll
;     for (int j = 0; j < 63; ++j) {
;         const float xj = x[j];
; #pragma unroll
;         for (int i4 = (j + 1) / 4; i4 < 16; ++i4) {
;             if (4 * i4 + 0 > j) x[4 * i4 + 0] -= cur[i4][0] * xj;
;             if (4 * i4 + 1 > j) x[4 * i4 + 1] -= cur[i4][1] * xj;
;             if (4 * i4 + 2 > j) x[4 * i4 + 2] -= cur[i4][2] * xj;
;             if (4 * i4 + 3 > j) x[4 * i4 + 3] -= cur[i4][3] * xj;
;             if (j + 1 < 63 && i4 >= (j + 2) / 4) cur[i4] = *(const PG8_LAS f32x4*)(sLt + (j + 1) * 64 + 4 * i4); }
;         asm volatile("" ::: "memory");
;     }
	v_pk_fma_f32 v[68:69], v[20:21], v[50:51], v[68:69] op_sel:[0,0,0] op_sel_hi:[1,0,1] neg_lo:[1,0,0] neg_hi:[1,0,0]
	v_pk_fma_f32 v[70:71], v[22:23], v[50:51], v[70:71] op_sel:[0,0,0] op_sel_hi:[1,0,1] neg_lo:[1,0,0] neg_hi:[1,0,0]
	ds_read_b128 v[20:23], v251 offset:6080
	s_waitcnt lgkmcnt(13)
	v_pk_fma_f32 v[72:73], v[24:25], v[50:51], v[72:73] op_sel:[0,0,0] op_sel_hi:[1,0,1] neg_lo:[1,0,0] neg_hi:[1,0,0]
	v_pk_fma_f32 v[74:75], v[26:27], v[50:51], v[74:75] op_sel:[0,0,0] op_sel_hi:[1,0,1] neg_lo:[1,0,0] neg_hi:[1,0,0]
	ds_read_b128 v[24:27], v251 offset:6096
	s_waitcnt lgkmcnt(13)
	v_pk_fma_f32 v[76:77], v[28:29], v[50:51], v[76:77] op_sel:[0,0,0] op_sel_hi:[1,0,1] neg_lo:[1,0,0] neg_hi:[1,0,0]
	v_pk_fma_f32 v[78:79], v[30:31], v[50:51], v[78:79] op_sel:[0,0,0] op_sel_hi:[1,0,1] neg_lo:[1,0,0] neg_hi:[1,0,0]
	ds_read_b128 v[28:31], v251 offset:6112
	s_waitcnt lgkmcnt(13)
	v_pk_fma_f32 v[80:81], v[126:127], v[50:51], v[80:81] op_sel:[0,0,0] op_sel_hi:[1,0,1] neg_lo:[1,0,0] neg_hi:[1,0,0]
	v_pk_fma_f32 v[82:83], v[128:129], v[50:51], v[82:83] op_sel:[0,0,0] op_sel_hi:[1,0,1] neg_lo:[1,0,0] neg_hi:[1,0,0]
	ds_read_b128 v[126:129], v251 offset:6128
	s_waitcnt lgkmcnt(13)
	v_pk_fma_f32 v[84:85], v[230:231], v[50:51], v[84:85] op_sel:[0,0,0] op_sel_hi:[1,0,1] neg_lo:[1,0,0] neg_hi:[1,0,0]
	v_pk_fma_f32 v[86:87], v[232:233], v[50:51], v[86:87] op_sel:[0,0,0] op_sel_hi:[1,0,1] neg_lo:[1,0,0] neg_hi:[1,0,0]
	ds_read_b128 v[230:233], v251 offset:6224
	s_waitcnt lgkmcnt(13)
	v_pk_fma_f32 v[88:89], v[234:235], v[50:51], v[88:89] op_sel:[0,0,0] op_sel_hi:[1,0,1] neg_lo:[1,0,0] neg_hi:[1,0,0]
	v_pk_fma_f32 v[90:91], v[236:237], v[50:51], v[90:91] op_sel:[0,0,0] op_sel_hi:[1,0,1] neg_lo:[1,0,0] neg_hi:[1,0,0]
	ds_read_b128 v[234:237], v251 offset:6240
	s_waitcnt lgkmcnt(13)
	v_pk_fma_f32 v[92:93], v[238:239], v[50:51], v[92:93] op_sel:[0,0,0] op_sel_hi:[1,0,1] neg_lo:[1,0,0] neg_hi:[1,0,0]
	v_pk_fma_f32 v[94:95], v[240:241], v[50:51], v[94:95] op_sel:[0,0,0] op_sel_hi:[1,0,1] neg_lo:[1,0,0] neg_hi:[1,0,0]
	ds_read_b128 v[238:241], v251 offset:6256
	s_waitcnt lgkmcnt(13)
	v_pk_fma_f32 v[52:53], v[242:243], v[50:51], v[52:53] op_sel:[0,1,0] op_sel_hi:[1,1,1] neg_lo:[1,0,0] neg_hi:[1,0,0]
	v_pk_fma_f32 v[54:55], v[244:245], v[50:51], v[54:55] op_sel:[0,1,0] op_sel_hi:[1,1,1] neg_lo:[1,0,0] neg_hi:[1,0,0]
	ds_read_b128 v[242:245], v251 offset:6272
	s_waitcnt lgkmcnt(13)
	v_pk_fma_f32 v[56:57], v[246:247], v[50:51], v[56:57] op_sel:[0,1,0] op_sel_hi:[1,1,1] neg_lo:[1,0,0] neg_hi:[1,0,0]
	v_pk_fma_f32 v[58:59], v[248:249], v[50:51], v[58:59] op_sel:[0,1,0] op_sel_hi:[1,1,1] neg_lo:[1,0,0] neg_hi:[1,0,0]
	ds_read_b128 v[246:249], v251 offset:6288
	s_waitcnt lgkmcnt(13)
	v_pk_fma_f32 v[60:61], v[0:1], v[50:51], v[60:61] op_sel:[0,1,0] op_sel_hi:[1,1,1] neg_lo:[1,0,0] neg_hi:[1,0,0]
	v_pk_fma_f32 v[62:63], v[2:3], v[50:51], v[62:63] op_sel:[0,1,0] op_sel_hi:[1,1,1] neg_lo:[1,0,0] neg_hi:[1,0,0]
	ds_read_b128 v[0:3], v251 offset:6304
	s_waitcnt lgkmcnt(13)
	v_pk_fma_f32 v[64:65], v[4:5], v[50:51], v[64:65] op_sel:[0,1,0] op_sel_hi:[1,1,1] neg_lo:[1,0,0] neg_hi:[1,0,0]
	v_pk_fma_f32 v[66:67], v[6:7], v[50:51], v[66:67] op_sel:[0,1,0] op_sel_hi:[1,1,1] neg_lo:[1,0,0] neg_hi:[1,0,0]
	ds_read_b128 v[4:7], v251 offset:6320
	s_waitcnt lgkmcnt(13)
	v_pk_fma_f32 v[68:69], v[8:9], v[50:51], v[68:69] op_sel:[0,1,0] op_sel_hi:[1,1,1] neg_lo:[1,0,0] neg_hi:[1,0,0]
	v_pk_fma_f32 v[70:71], v[10:11], v[50:51], v[70:71] op_sel:[0,1,0] op_sel_hi:[1,1,1] neg_lo:[1,0,0] neg_hi:[1,0,0]
	ds_read_b128 v[8:11], v251 offset:6336
	s_waitcnt lgkmcnt(13)
	v_pk_fma_f32 v[72:73], v[12:13], v[50:51], v[72:73] op_sel:[0,1,0] op_sel_hi:[1,1,1] neg_lo:[1,0,0] neg_hi:[1,0,0]
	v_pk_fma_f32 v[74:75], v[14:15], v[50:51], v[74:75] op_sel:[0,1,0] op_sel_hi:[1,1,1] neg_lo:[1,0,0] neg_hi:[1,0,0]
	ds_read_b128 v[12:15], v251 offset:6352
	s_waitcnt lgkmcnt(13)
	v_pk_fma_f32 v[76:77], v[16:17], v[50:51], v[76:77] op_sel:[0,1,0] op_sel_hi:[1,1,1] neg_lo:[1,0,0] neg_hi:[1,0,0]
	v_pk_fma_f32 v[78:79], v[18:19], v[50:51], v[78:79] op_sel:[0,1,0] op_sel_hi:[1,1,1] neg_lo:[1,0,0] neg_hi:[1,0,0]
	ds_read_b128 v[16:19], v251 offset:6368
	s_waitcnt lgkmcnt(13)
	v_pk_fma_f32 v[80:81], v[20:21], v[50:51], v[80:81] op_sel:[0,1,0] op_sel_hi:[1,1,1] neg_lo:[1,0,0] neg_hi:[1,0,0]
	v_pk_fma_f32 v[82:83], v[22:23], v[50:51], v[82:83] op_sel:[0,1,0] op_sel_hi:[1,1,1] neg_lo:[1,0,0] neg_hi:[1,0,0]
	ds_read_b128 v[20:23], v251 offset:6384
	s_waitcnt lgkmcnt(13)
	v_pk_fma_f32 v[84:85], v[24:25], v[50:51], v[84:85] op_sel:[0,1,0] op_sel_hi:[1,1,1] neg_lo:[1,0,0] neg_hi:[1,0,0]
	v_pk_fma_f32 v[86:87], v[26:27], v[50:51], v[86:87] op_sel:[0,1,0] op_sel_hi:[1,1,1] neg_lo:[1,0,0] neg_hi:[1,0,0]
	ds_read_b128 v[24:27], v251 offset:6480
	s_waitcnt lgkmcnt(13)
	v_pk_fma_f32 v[88:89], v[28:29], v[50:51], v[88:89] op_sel:[0,1,0] op_sel_hi:[1,1,1] neg_lo:[1,0,0] neg_hi:[1,0,0]
	v_pk_fma_f32 v[90:91], v[30:31], v[50:51], v[90:91] op_sel:[0,1,0] op_sel_hi:[1,1,1] neg_lo:[1,0,0] neg_hi:[1,0,0]
	ds_read_b128 v[28:31], v251 offset:6496
	s_waitcnt lgkmcnt(13)
	v_pk_fma_f32 v[92:93], v[126:127], v[50:51], v[92:93] op_sel:[0,1,0] op_sel_hi:[1,1,1] neg_lo:[1,0,0] neg_hi:[1,0,0]
	v_pk_fma_f32 v[94:95], v[128:129], v[50:51], v[94:95] op_sel:[0,1,0] op_sel_hi:[1,1,1] neg_lo:[1,0,0] neg_hi:[1,0,0]
	ds_read_b128 v[126:129], v251 offset:6512
	s_waitcnt lgkmcnt(13)
	v_fma_f32 v53, -v231, v52, v53
	v_pk_fma_f32 v[54:55], v[232:233], v[52:53], v[54:55] op_sel:[0,0,0] op_sel_hi:[1,0,1] neg_lo:[1,0,0] neg_hi:[1,0,0]
	ds_read_b128 v[230:233], v251 offset:6528
	s_waitcnt lgkmcnt(13)
; #define PG8_LAS __attribute__((address_space(3)))
; __device__ __forceinline__ void solve64(float (&x)[64], const PG8_LAS float* sLt) {
;     f32x4 cur[16];
; #pragma unroll
;     for (int i4 = 0; i4 < 16; ++i4) cur[i4] = *(const PG8_LAS f32x4*)(sLt + 4 * i4);
;     asm volatile("" ::: "memory");
; #pragma unroll
;     for (int j = 0; j < 63; ++j) {
;         const float xj = x[j];
; #pragma unroll
;         for (int i4 = (j + 1) / 4; i4 < 16; ++i4) {
;             if (4 * i4 + 0 > j) x[4 * i4 + 0] -= cur[i4][0] * xj;
;             if (4 * i4 + 1 > j) x[4 * i4 + 1] -= cur[i4][1] * xj;
;             if (4 * i4 + 2 > j) x[4 * i4 + 2] -= cur[i4][2] * xj;
;             if (4 * i4 + 3 > j) x[4 * i4 + 3] -= cur[i4][3] * xj;
;             if (j + 1 < 63 && i4 >= (j + 2) / 4) cur[i4] = *(const PG8_LAS f32x4*)(sLt + (j + 1) * 64 + 4 * i4); }
;         asm volatile("" ::: "memory");
;     }
	v_pk_fma_f32 v[56:57], v[234:235], v[52:53], v[56:57] op_sel:[0,0,0] op_sel_hi:[1,0,1] neg_lo:[1,0,0] neg_hi:[1,0,0]
	v_pk_fma_f32 v[58:59], v[236:237], v[52:53], v[58:59] op_sel:[0,0,0] op_sel_hi:[1,0,1] neg_lo:[1,0,0] neg_hi:[1,0,0]
	ds_read_b128 v[234:237], v251 offset:6544
	s_waitcnt lgkmcnt(13)
	v_pk_fma_f32 v[60:61], v[238:239], v[52:53], v[60:61] op_sel:[0,0,0] op_sel_hi:[1,0,1] neg_lo:[1,0,0] neg_hi:[1,0,0]
	v_pk_fma_f32 v[62:63], v[240:241], v[52:53], v[62:63] op_sel:[0,0,0] op_sel_hi:[1,0,1] neg_lo:[1,0,0] neg_hi:[1,0,0]
	ds_read_b128 v[238:241], v251 offset:6560
	s_waitcnt lgkmcnt(13)
	v_pk_fma_f32 v[64:65], v[242:243], v[52:53], v[64:65] op_sel:[0,0,0] op_sel_hi:[1,0,1] neg_lo:[1,0,0] neg_hi:[1,0,0]
	v_pk_fma_f32 v[66:67], v[244:245], v[52:53], v[66:67] op_sel:[0,0,0] op_sel_hi:[1,0,1] neg_lo:[1,0,0] neg_hi:[1,0,0]
	ds_read_b128 v[242:245], v251 offset:6576
	s_waitcnt lgkmcnt(13)
	v_pk_fma_f32 v[68:69], v[246:247], v[52:53], v[68:69] op_sel:[0,0,0] op_sel_hi:[1,0,1] neg_lo:[1,0,0] neg_hi:[1,0,0]
	v_pk_fma_f32 v[70:71], v[248:249], v[52:53], v[70:71] op_sel:[0,0,0] op_sel_hi:[1,0,1] neg_lo:[1,0,0] neg_hi:[1,0,0]
	ds_read_b128 v[246:249], v251 offset:6592
	s_waitcnt lgkmcnt(13)
	v_pk_fma_f32 v[72:73], v[0:1], v[52:53], v[72:73] op_sel:[0,0,0] op_sel_hi:[1,0,1] neg_lo:[1,0,0] neg_hi:[1,0,0]
	v_pk_fma_f32 v[74:75], v[2:3], v[52:53], v[74:75] op_sel:[0,0,0] op_sel_hi:[1,0,1] neg_lo:[1,0,0] neg_hi:[1,0,0]
	ds_read_b128 v[0:3], v251 offset:6608
	s_waitcnt lgkmcnt(13)
	v_pk_fma_f32 v[76:77], v[4:5], v[52:53], v[76:77] op_sel:[0,0,0] op_sel_hi:[1,0,1] neg_lo:[1,0,0] neg_hi:[1,0,0]
	v_pk_fma_f32 v[78:79], v[6:7], v[52:53], v[78:79] op_sel:[0,0,0] op_sel_hi:[1,0,1] neg_lo:[1,0,0] neg_hi:[1,0,0]
	ds_read_b128 v[4:7], v251 offset:6624
	s_waitcnt lgkmcnt(13)
	v_pk_fma_f32 v[80:81], v[8:9], v[52:53], v[80:81] op_sel:[0,0,0] op_sel_hi:[1,0,1] neg_lo:[1,0,0] neg_hi:[1,0,0]
	v_pk_fma_f32 v[82:83], v[10:11], v[52:53], v[82:83] op_sel:[0,0,0] op_sel_hi:[1,0,1] neg_lo:[1,0,0] neg_hi:[1,0,0]
	ds_read_b128 v[8:11], v251 offset:6640
	s_waitcnt lgkmcnt(13)
	v_pk_fma_f32 v[84:85], v[12:13], v[52:53], v[84:85] op_sel:[0,0,0] op_sel_hi:[1,0,1] neg_lo:[1,0,0] neg_hi:[1,0,0]
	v_pk_fma_f32 v[86:87], v[14:15], v[52:53], v[86:87] op_sel:[0,0,0] op_sel_hi:[1,0,1] neg_lo:[1,0,0] neg_hi:[1,0,0]
	ds_read_b128 v[12:15], v251 offset:6736
	s_waitcnt lgkmcnt(13)
	v_pk_fma_f32 v[88:89], v[16:17], v[52:53], v[88:89] op_sel:[0,0,0] op_sel_hi:[1,0,1] neg_lo:[1,0,0] neg_hi:[1,0,0]
	v_pk_fma_f32 v[90:91], v[18:19], v[52:53], v[90:91] op_sel:[0,0,0] op_sel_hi:[1,0,1] neg_lo:[1,0,0] neg_hi:[1,0,0]
	ds_read_b128 v[16:19], v251 offset:6752
	s_waitcnt lgkmcnt(13)
	v_pk_fma_f32 v[92:93], v[20:21], v[52:53], v[92:93] op_sel:[0,0,0] op_sel_hi:[1,0,1] neg_lo:[1,0,0] neg_hi:[1,0,0]
	v_pk_fma_f32 v[94:95], v[22:23], v[52:53], v[94:95] op_sel:[0,0,0] op_sel_hi:[1,0,1] neg_lo:[1,0,0] neg_hi:[1,0,0]
	ds_read_b128 v[20:23], v251 offset:6768
	s_waitcnt lgkmcnt(13)
	v_pk_fma_f32 v[54:55], v[26:27], v[52:53], v[54:55] op_sel:[0,1,0] op_sel_hi:[1,1,1] neg_lo:[1,0,0] neg_hi:[1,0,0]
	ds_read_b128 v[24:27], v251 offset:6784
	s_waitcnt lgkmcnt(13)
	v_pk_fma_f32 v[56:57], v[28:29], v[52:53], v[56:57] op_sel:[0,1,0] op_sel_hi:[1,1,1] neg_lo:[1,0,0] neg_hi:[1,0,0]
	v_pk_fma_f32 v[58:59], v[30:31], v[52:53], v[58:59] op_sel:[0,1,0] op_sel_hi:[1,1,1] neg_lo:[1,0,0] neg_hi:[1,0,0]
	ds_read_b128 v[28:31], v251 offset:6800
	s_waitcnt lgkmcnt(13)
	v_pk_fma_f32 v[60:61], v[126:127], v[52:53], v[60:61] op_sel:[0,1,0] op_sel_hi:[1,1,1] neg_lo:[1,0,0] neg_hi:[1,0,0]
	v_pk_fma_f32 v[62:63], v[128:129], v[52:53], v[62:63] op_sel:[0,1,0] op_sel_hi:[1,1,1] neg_lo:[1,0,0] neg_hi:[1,0,0]
	ds_read_b128 v[126:129], v251 offset:6816
	s_waitcnt lgkmcnt(13)
	v_pk_fma_f32 v[64:65], v[230:231], v[52:53], v[64:65] op_sel:[0,1,0] op_sel_hi:[1,1,1] neg_lo:[1,0,0] neg_hi:[1,0,0]
	v_pk_fma_f32 v[66:67], v[232:233], v[52:53], v[66:67] op_sel:[0,1,0] op_sel_hi:[1,1,1] neg_lo:[1,0,0] neg_hi:[1,0,0]
	ds_read_b128 v[230:233], v251 offset:6832
	s_waitcnt lgkmcnt(13)
	v_pk_fma_f32 v[68:69], v[234:235], v[52:53], v[68:69] op_sel:[0,1,0] op_sel_hi:[1,1,1] neg_lo:[1,0,0] neg_hi:[1,0,0]
	v_pk_fma_f32 v[70:71], v[236:237], v[52:53], v[70:71] op_sel:[0,1,0] op_sel_hi:[1,1,1] neg_lo:[1,0,0] neg_hi:[1,0,0]
	ds_read_b128 v[234:237], v251 offset:6848
	s_waitcnt lgkmcnt(13)
	v_pk_fma_f32 v[72:73], v[238:239], v[52:53], v[72:73] op_sel:[0,1,0] op_sel_hi:[1,1,1] neg_lo:[1,0,0] neg_hi:[1,0,0]
	v_pk_fma_f32 v[74:75], v[240:241], v[52:53], v[74:75] op_sel:[0,1,0] op_sel_hi:[1,1,1] neg_lo:[1,0,0] neg_hi:[1,0,0]
	ds_read_b128 v[238:241], v251 offset:6864
	s_waitcnt lgkmcnt(13)
	v_pk_fma_f32 v[76:77], v[242:243], v[52:53], v[76:77] op_sel:[0,1,0] op_sel_hi:[1,1,1] neg_lo:[1,0,0] neg_hi:[1,0,0]
	v_pk_fma_f32 v[78:79], v[244:245], v[52:53], v[78:79] op_sel:[0,1,0] op_sel_hi:[1,1,1] neg_lo:[1,0,0] neg_hi:[1,0,0]
	ds_read_b128 v[242:245], v251 offset:6880
	s_waitcnt lgkmcnt(13)
	v_pk_fma_f32 v[80:81], v[246:247], v[52:53], v[80:81] op_sel:[0,1,0] op_sel_hi:[1,1,1] neg_lo:[1,0,0] neg_hi:[1,0,0]
	v_pk_fma_f32 v[82:83], v[248:249], v[52:53], v[82:83] op_sel:[0,1,0] op_sel_hi:[1,1,1] neg_lo:[1,0,0] neg_hi:[1,0,0]
	ds_read_b128 v[246:249], v251 offset:6896
	s_waitcnt lgkmcnt(13)
	v_pk_fma_f32 v[84:85], v[0:1], v[52:53], v[84:85] op_sel:[0,1,0] op_sel_hi:[1,1,1] neg_lo:[1,0,0] neg_hi:[1,0,0]
	v_pk_fma_f32 v[86:87], v[2:3], v[52:53], v[86:87] op_sel:[0,1,0] op_sel_hi:[1,1,1] neg_lo:[1,0,0] neg_hi:[1,0,0]
	ds_read_b128 v[0:3], v251 offset:7008
	s_waitcnt lgkmcnt(13)
; #define PG8_LAS __attribute__((address_space(3)))
; __device__ __forceinline__ void solve64(float (&x)[64], const PG8_LAS float* sLt) {
;     f32x4 cur[16];
; #pragma unroll
;     for (int i4 = 0; i4 < 16; ++i4) cur[i4] = *(const PG8_LAS f32x4*)(sLt + 4 * i4);
;     asm volatile("" ::: "memory");
; #pragma unroll
;     for (int j = 0; j < 63; ++j) {
;         const float xj = x[j];
; #pragma unroll
;         for (int i4 = (j + 1) / 4; i4 < 16; ++i4) {
;             if (4 * i4 + 0 > j) x[4 * i4 + 0] -= cur[i4][0] * xj;
;             if (4 * i4 + 1 > j) x[4 * i4 + 1] -= cur[i4][1] * xj;
;             if (4 * i4 + 2 > j) x[4 * i4 + 2] -= cur[i4][2] * xj;
;             if (4 * i4 + 3 > j) x[4 * i4 + 3] -= cur[i4][3] * xj;
;             if (j + 1 < 63 && i4 >= (j + 2) / 4) cur[i4] = *(const PG8_LAS f32x4*)(sLt + (j + 1) * 64 + 4 * i4); }
;         asm volatile("" ::: "memory");
;     }
; }
	v_pk_fma_f32 v[88:89], v[4:5], v[52:53], v[88:89] op_sel:[0,1,0] op_sel_hi:[1,1,1] neg_lo:[1,0,0] neg_hi:[1,0,0]
	v_pk_fma_f32 v[90:91], v[6:7], v[52:53], v[90:91] op_sel:[0,1,0] op_sel_hi:[1,1,1] neg_lo:[1,0,0] neg_hi:[1,0,0]
	ds_read_b128 v[4:7], v251 offset:7024
	s_waitcnt lgkmcnt(13)
	v_pk_fma_f32 v[92:93], v[8:9], v[52:53], v[92:93] op_sel:[0,1,0] op_sel_hi:[1,1,1] neg_lo:[1,0,0] neg_hi:[1,0,0]
	v_pk_fma_f32 v[94:95], v[10:11], v[52:53], v[94:95] op_sel:[0,1,0] op_sel_hi:[1,1,1] neg_lo:[1,0,0] neg_hi:[1,0,0]
	ds_read_b128 v[8:11], v251 offset:7040
	s_waitcnt lgkmcnt(13)
	v_fma_f32 v55, -v15, v54, v55
	ds_read_b128 v[12:15], v251 offset:7056
	s_waitcnt lgkmcnt(13)
	v_pk_fma_f32 v[56:57], v[16:17], v[54:55], v[56:57] op_sel:[0,0,0] op_sel_hi:[1,0,1] neg_lo:[1,0,0] neg_hi:[1,0,0]
	v_pk_fma_f32 v[58:59], v[18:19], v[54:55], v[58:59] op_sel:[0,0,0] op_sel_hi:[1,0,1] neg_lo:[1,0,0] neg_hi:[1,0,0]
	ds_read_b128 v[16:19], v251 offset:7072
	s_waitcnt lgkmcnt(13)
	v_pk_fma_f32 v[60:61], v[20:21], v[54:55], v[60:61] op_sel:[0,0,0] op_sel_hi:[1,0,1] neg_lo:[1,0,0] neg_hi:[1,0,0]
	v_pk_fma_f32 v[62:63], v[22:23], v[54:55], v[62:63] op_sel:[0,0,0] op_sel_hi:[1,0,1] neg_lo:[1,0,0] neg_hi:[1,0,0]
	ds_read_b128 v[20:23], v251 offset:7088
	s_waitcnt lgkmcnt(13)
	v_pk_fma_f32 v[64:65], v[24:25], v[54:55], v[64:65] op_sel:[0,0,0] op_sel_hi:[1,0,1] neg_lo:[1,0,0] neg_hi:[1,0,0]
	v_pk_fma_f32 v[66:67], v[26:27], v[54:55], v[66:67] op_sel:[0,0,0] op_sel_hi:[1,0,1] neg_lo:[1,0,0] neg_hi:[1,0,0]
	ds_read_b128 v[24:27], v251 offset:7104
	s_waitcnt lgkmcnt(13)
	v_pk_fma_f32 v[68:69], v[28:29], v[54:55], v[68:69] op_sel:[0,0,0] op_sel_hi:[1,0,1] neg_lo:[1,0,0] neg_hi:[1,0,0]
	v_pk_fma_f32 v[70:71], v[30:31], v[54:55], v[70:71] op_sel:[0,0,0] op_sel_hi:[1,0,1] neg_lo:[1,0,0] neg_hi:[1,0,0]
	ds_read_b128 v[28:31], v251 offset:7120
	s_waitcnt lgkmcnt(13)
	v_pk_fma_f32 v[72:73], v[126:127], v[54:55], v[72:73] op_sel:[0,0,0] op_sel_hi:[1,0,1] neg_lo:[1,0,0] neg_hi:[1,0,0]
	v_pk_fma_f32 v[74:75], v[128:129], v[54:55], v[74:75] op_sel:[0,0,0] op_sel_hi:[1,0,1] neg_lo:[1,0,0] neg_hi:[1,0,0]
	ds_read_b128 v[126:129], v251 offset:7136
	s_waitcnt lgkmcnt(13)
	v_pk_fma_f32 v[76:77], v[230:231], v[54:55], v[76:77] op_sel:[0,0,0] op_sel_hi:[1,0,1] neg_lo:[1,0,0] neg_hi:[1,0,0]
	v_pk_fma_f32 v[78:79], v[232:233], v[54:55], v[78:79] op_sel:[0,0,0] op_sel_hi:[1,0,1] neg_lo:[1,0,0] neg_hi:[1,0,0]
	ds_read_b128 v[230:233], v251 offset:7152
	s_waitcnt lgkmcnt(13)
	v_pk_fma_f32 v[80:81], v[234:235], v[54:55], v[80:81] op_sel:[0,0,0] op_sel_hi:[1,0,1] neg_lo:[1,0,0] neg_hi:[1,0,0]
	v_pk_fma_f32 v[82:83], v[236:237], v[54:55], v[82:83] op_sel:[0,0,0] op_sel_hi:[1,0,1] neg_lo:[1,0,0] neg_hi:[1,0,0]
	ds_read_b128 v[234:237], v251 offset:7264
	s_waitcnt lgkmcnt(13)
	v_pk_fma_f32 v[84:85], v[238:239], v[54:55], v[84:85] op_sel:[0,0,0] op_sel_hi:[1,0,1] neg_lo:[1,0,0] neg_hi:[1,0,0]
	v_pk_fma_f32 v[86:87], v[240:241], v[54:55], v[86:87] op_sel:[0,0,0] op_sel_hi:[1,0,1] neg_lo:[1,0,0] neg_hi:[1,0,0]
	ds_read_b128 v[238:241], v251 offset:7280
	s_waitcnt lgkmcnt(13)
	v_pk_fma_f32 v[88:89], v[242:243], v[54:55], v[88:89] op_sel:[0,0,0] op_sel_hi:[1,0,1] neg_lo:[1,0,0] neg_hi:[1,0,0]
	v_pk_fma_f32 v[90:91], v[244:245], v[54:55], v[90:91] op_sel:[0,0,0] op_sel_hi:[1,0,1] neg_lo:[1,0,0] neg_hi:[1,0,0]
	ds_read_b128 v[242:245], v251 offset:7296
	s_waitcnt lgkmcnt(13)
	v_pk_fma_f32 v[92:93], v[246:247], v[54:55], v[92:93] op_sel:[0,0,0] op_sel_hi:[1,0,1] neg_lo:[1,0,0] neg_hi:[1,0,0]
	v_pk_fma_f32 v[94:95], v[248:249], v[54:55], v[94:95] op_sel:[0,0,0] op_sel_hi:[1,0,1] neg_lo:[1,0,0] neg_hi:[1,0,0]
	ds_read_b128 v[246:249], v251 offset:7312
	s_waitcnt lgkmcnt(13)
	v_pk_fma_f32 v[56:57], v[0:1], v[54:55], v[56:57] op_sel:[0,1,0] op_sel_hi:[1,1,1] neg_lo:[1,0,0] neg_hi:[1,0,0]
	v_pk_fma_f32 v[58:59], v[2:3], v[54:55], v[58:59] op_sel:[0,1,0] op_sel_hi:[1,1,1] neg_lo:[1,0,0] neg_hi:[1,0,0]
	ds_read_b128 v[0:3], v251 offset:7328
	s_waitcnt lgkmcnt(13)
	v_pk_fma_f32 v[60:61], v[4:5], v[54:55], v[60:61] op_sel:[0,1,0] op_sel_hi:[1,1,1] neg_lo:[1,0,0] neg_hi:[1,0,0]
	v_pk_fma_f32 v[62:63], v[6:7], v[54:55], v[62:63] op_sel:[0,1,0] op_sel_hi:[1,1,1] neg_lo:[1,0,0] neg_hi:[1,0,0]
	ds_read_b128 v[4:7], v251 offset:7344
	s_waitcnt lgkmcnt(13)
	v_pk_fma_f32 v[64:65], v[8:9], v[54:55], v[64:65] op_sel:[0,1,0] op_sel_hi:[1,1,1] neg_lo:[1,0,0] neg_hi:[1,0,0]
	v_pk_fma_f32 v[66:67], v[10:11], v[54:55], v[66:67] op_sel:[0,1,0] op_sel_hi:[1,1,1] neg_lo:[1,0,0] neg_hi:[1,0,0]
	ds_read_b128 v[8:11], v251 offset:7360
	s_waitcnt lgkmcnt(13)
	v_pk_fma_f32 v[68:69], v[12:13], v[54:55], v[68:69] op_sel:[0,1,0] op_sel_hi:[1,1,1] neg_lo:[1,0,0] neg_hi:[1,0,0]
	v_pk_fma_f32 v[70:71], v[14:15], v[54:55], v[70:71] op_sel:[0,1,0] op_sel_hi:[1,1,1] neg_lo:[1,0,0] neg_hi:[1,0,0]
	ds_read_b128 v[12:15], v251 offset:7376
	s_waitcnt lgkmcnt(13)
	v_pk_fma_f32 v[72:73], v[16:17], v[54:55], v[72:73] op_sel:[0,1,0] op_sel_hi:[1,1,1] neg_lo:[1,0,0] neg_hi:[1,0,0]
	v_pk_fma_f32 v[74:75], v[18:19], v[54:55], v[74:75] op_sel:[0,1,0] op_sel_hi:[1,1,1] neg_lo:[1,0,0] neg_hi:[1,0,0]
	ds_read_b128 v[16:19], v251 offset:7392
	s_waitcnt lgkmcnt(13)
	v_pk_fma_f32 v[76:77], v[20:21], v[54:55], v[76:77] op_sel:[0,1,0] op_sel_hi:[1,1,1] neg_lo:[1,0,0] neg_hi:[1,0,0]
	v_pk_fma_f32 v[78:79], v[22:23], v[54:55], v[78:79] op_sel:[0,1,0] op_sel_hi:[1,1,1] neg_lo:[1,0,0] neg_hi:[1,0,0]
	ds_read_b128 v[20:23], v251 offset:7408
	s_waitcnt lgkmcnt(13)
	v_pk_fma_f32 v[80:81], v[24:25], v[54:55], v[80:81] op_sel:[0,1,0] op_sel_hi:[1,1,1] neg_lo:[1,0,0] neg_hi:[1,0,0]
	v_pk_fma_f32 v[82:83], v[26:27], v[54:55], v[82:83] op_sel:[0,1,0] op_sel_hi:[1,1,1] neg_lo:[1,0,0] neg_hi:[1,0,0]
	ds_read_b128 v[24:27], v251 offset:7520
	s_waitcnt lgkmcnt(13)
; #define PG8_LAS __attribute__((address_space(3)))
; __device__ __forceinline__ void solve64(float (&x)[64], const PG8_LAS float* sLt) {
;     f32x4 cur[16];
; #pragma unroll
;     for (int i4 = 0; i4 < 16; ++i4) cur[i4] = *(const PG8_LAS f32x4*)(sLt + 4 * i4);
;     asm volatile("" ::: "memory");
; #pragma unroll
;     for (int j = 0; j < 63; ++j) {
;         const float xj = x[j];
; #pragma unroll
;         for (int i4 = (j + 1) / 4; i4 < 16; ++i4) {
;             if (4 * i4 + 0 > j) x[4 * i4 + 0] -= cur[i4][0] * xj;
;             if (4 * i4 + 1 > j) x[4 * i4 + 1] -= cur[i4][1] * xj;
;             if (4 * i4 + 2 > j) x[4 * i4 + 2] -= cur[i4][2] * xj;
;             if (4 * i4 + 3 > j) x[4 * i4 + 3] -= cur[i4][3] * xj;
;             if (j + 1 < 63 && i4 >= (j + 2) / 4) cur[i4] = *(const PG8_LAS f32x4*)(sLt + (j + 1) * 64 + 4 * i4); }
;         asm volatile("" ::: "memory");
;     }
; }
	v_pk_fma_f32 v[84:85], v[28:29], v[54:55], v[84:85] op_sel:[0,1,0] op_sel_hi:[1,1,1] neg_lo:[1,0,0] neg_hi:[1,0,0]
	v_pk_fma_f32 v[86:87], v[30:31], v[54:55], v[86:87] op_sel:[0,1,0] op_sel_hi:[1,1,1] neg_lo:[1,0,0] neg_hi:[1,0,0]
	ds_read_b128 v[28:31], v251 offset:7536
	s_waitcnt lgkmcnt(13)
	v_pk_fma_f32 v[88:89], v[126:127], v[54:55], v[88:89] op_sel:[0,1,0] op_sel_hi:[1,1,1] neg_lo:[1,0,0] neg_hi:[1,0,0]
	v_pk_fma_f32 v[90:91], v[128:129], v[54:55], v[90:91] op_sel:[0,1,0] op_sel_hi:[1,1,1] neg_lo:[1,0,0] neg_hi:[1,0,0]
	ds_read_b128 v[126:129], v251 offset:7552
	s_waitcnt lgkmcnt(13)
	v_pk_fma_f32 v[92:93], v[230:231], v[54:55], v[92:93] op_sel:[0,1,0] op_sel_hi:[1,1,1] neg_lo:[1,0,0] neg_hi:[1,0,0]
	v_pk_fma_f32 v[94:95], v[232:233], v[54:55], v[94:95] op_sel:[0,1,0] op_sel_hi:[1,1,1] neg_lo:[1,0,0] neg_hi:[1,0,0]
	ds_read_b128 v[230:233], v251 offset:7568
	s_waitcnt lgkmcnt(13)
	v_fma_f32 v57, -v235, v56, v57
	v_pk_fma_f32 v[58:59], v[236:237], v[56:57], v[58:59] op_sel:[0,0,0] op_sel_hi:[1,0,1] neg_lo:[1,0,0] neg_hi:[1,0,0]
	ds_read_b128 v[234:237], v251 offset:7584
	s_waitcnt lgkmcnt(13)
	v_pk_fma_f32 v[60:61], v[238:239], v[56:57], v[60:61] op_sel:[0,0,0] op_sel_hi:[1,0,1] neg_lo:[1,0,0] neg_hi:[1,0,0]
	v_pk_fma_f32 v[62:63], v[240:241], v[56:57], v[62:63] op_sel:[0,0,0] op_sel_hi:[1,0,1] neg_lo:[1,0,0] neg_hi:[1,0,0]
	ds_read_b128 v[238:241], v251 offset:7600
	s_waitcnt lgkmcnt(13)
	v_pk_fma_f32 v[64:65], v[242:243], v[56:57], v[64:65] op_sel:[0,0,0] op_sel_hi:[1,0,1] neg_lo:[1,0,0] neg_hi:[1,0,0]
	v_pk_fma_f32 v[66:67], v[244:245], v[56:57], v[66:67] op_sel:[0,0,0] op_sel_hi:[1,0,1] neg_lo:[1,0,0] neg_hi:[1,0,0]
	ds_read_b128 v[242:245], v251 offset:7616
	s_waitcnt lgkmcnt(13)
	v_pk_fma_f32 v[68:69], v[246:247], v[56:57], v[68:69] op_sel:[0,0,0] op_sel_hi:[1,0,1] neg_lo:[1,0,0] neg_hi:[1,0,0]
	v_pk_fma_f32 v[70:71], v[248:249], v[56:57], v[70:71] op_sel:[0,0,0] op_sel_hi:[1,0,1] neg_lo:[1,0,0] neg_hi:[1,0,0]
	ds_read_b128 v[246:249], v251 offset:7632
	s_waitcnt lgkmcnt(13)
	v_pk_fma_f32 v[72:73], v[0:1], v[56:57], v[72:73] op_sel:[0,0,0] op_sel_hi:[1,0,1] neg_lo:[1,0,0] neg_hi:[1,0,0]
	v_pk_fma_f32 v[74:75], v[2:3], v[56:57], v[74:75] op_sel:[0,0,0] op_sel_hi:[1,0,1] neg_lo:[1,0,0] neg_hi:[1,0,0]
	ds_read_b128 v[0:3], v251 offset:7648
	s_waitcnt lgkmcnt(13)
	v_pk_fma_f32 v[76:77], v[4:5], v[56:57], v[76:77] op_sel:[0,0,0] op_sel_hi:[1,0,1] neg_lo:[1,0,0] neg_hi:[1,0,0]
	v_pk_fma_f32 v[78:79], v[6:7], v[56:57], v[78:79] op_sel:[0,0,0] op_sel_hi:[1,0,1] neg_lo:[1,0,0] neg_hi:[1,0,0]
	ds_read_b128 v[4:7], v251 offset:7664
	s_waitcnt lgkmcnt(13)
	v_pk_fma_f32 v[80:81], v[8:9], v[56:57], v[80:81] op_sel:[0,0,0] op_sel_hi:[1,0,1] neg_lo:[1,0,0] neg_hi:[1,0,0]
	v_pk_fma_f32 v[82:83], v[10:11], v[56:57], v[82:83] op_sel:[0,0,0] op_sel_hi:[1,0,1] neg_lo:[1,0,0] neg_hi:[1,0,0]
	ds_read_b128 v[8:11], v251 offset:7776
	s_waitcnt lgkmcnt(13)
	v_pk_fma_f32 v[84:85], v[12:13], v[56:57], v[84:85] op_sel:[0,0,0] op_sel_hi:[1,0,1] neg_lo:[1,0,0] neg_hi:[1,0,0]
	v_pk_fma_f32 v[86:87], v[14:15], v[56:57], v[86:87] op_sel:[0,0,0] op_sel_hi:[1,0,1] neg_lo:[1,0,0] neg_hi:[1,0,0]
	ds_read_b128 v[12:15], v251 offset:7792
	s_waitcnt lgkmcnt(13)
	v_pk_fma_f32 v[88:89], v[16:17], v[56:57], v[88:89] op_sel:[0,0,0] op_sel_hi:[1,0,1] neg_lo:[1,0,0] neg_hi:[1,0,0]
	v_pk_fma_f32 v[90:91], v[18:19], v[56:57], v[90:91] op_sel:[0,0,0] op_sel_hi:[1,0,1] neg_lo:[1,0,0] neg_hi:[1,0,0]
	ds_read_b128 v[16:19], v251 offset:7808
	s_waitcnt lgkmcnt(13)
	v_pk_fma_f32 v[92:93], v[20:21], v[56:57], v[92:93] op_sel:[0,0,0] op_sel_hi:[1,0,1] neg_lo:[1,0,0] neg_hi:[1,0,0]
	v_pk_fma_f32 v[94:95], v[22:23], v[56:57], v[94:95] op_sel:[0,0,0] op_sel_hi:[1,0,1] neg_lo:[1,0,0] neg_hi:[1,0,0]
	ds_read_b128 v[20:23], v251 offset:7824
	s_waitcnt lgkmcnt(13)
	v_pk_fma_f32 v[58:59], v[26:27], v[56:57], v[58:59] op_sel:[0,1,0] op_sel_hi:[1,1,1] neg_lo:[1,0,0] neg_hi:[1,0,0]
	ds_read_b128 v[24:27], v251 offset:7840
	s_waitcnt lgkmcnt(13)
	v_pk_fma_f32 v[60:61], v[28:29], v[56:57], v[60:61] op_sel:[0,1,0] op_sel_hi:[1,1,1] neg_lo:[1,0,0] neg_hi:[1,0,0]
	v_pk_fma_f32 v[62:63], v[30:31], v[56:57], v[62:63] op_sel:[0,1,0] op_sel_hi:[1,1,1] neg_lo:[1,0,0] neg_hi:[1,0,0]
	ds_read_b128 v[28:31], v251 offset:7856
	s_waitcnt lgkmcnt(13)
	v_pk_fma_f32 v[64:65], v[126:127], v[56:57], v[64:65] op_sel:[0,1,0] op_sel_hi:[1,1,1] neg_lo:[1,0,0] neg_hi:[1,0,0]
	v_pk_fma_f32 v[66:67], v[128:129], v[56:57], v[66:67] op_sel:[0,1,0] op_sel_hi:[1,1,1] neg_lo:[1,0,0] neg_hi:[1,0,0]
	ds_read_b128 v[126:129], v251 offset:7872
	s_waitcnt lgkmcnt(13)
	v_pk_fma_f32 v[68:69], v[230:231], v[56:57], v[68:69] op_sel:[0,1,0] op_sel_hi:[1,1,1] neg_lo:[1,0,0] neg_hi:[1,0,0]
	v_pk_fma_f32 v[70:71], v[232:233], v[56:57], v[70:71] op_sel:[0,1,0] op_sel_hi:[1,1,1] neg_lo:[1,0,0] neg_hi:[1,0,0]
	ds_read_b128 v[230:233], v251 offset:7888
	s_waitcnt lgkmcnt(13)
	v_pk_fma_f32 v[72:73], v[234:235], v[56:57], v[72:73] op_sel:[0,1,0] op_sel_hi:[1,1,1] neg_lo:[1,0,0] neg_hi:[1,0,0]
	v_pk_fma_f32 v[74:75], v[236:237], v[56:57], v[74:75] op_sel:[0,1,0] op_sel_hi:[1,1,1] neg_lo:[1,0,0] neg_hi:[1,0,0]
	ds_read_b128 v[234:237], v251 offset:7904
	s_waitcnt lgkmcnt(13)
	v_pk_fma_f32 v[76:77], v[238:239], v[56:57], v[76:77] op_sel:[0,1,0] op_sel_hi:[1,1,1] neg_lo:[1,0,0] neg_hi:[1,0,0]
	v_pk_fma_f32 v[78:79], v[240:241], v[56:57], v[78:79] op_sel:[0,1,0] op_sel_hi:[1,1,1] neg_lo:[1,0,0] neg_hi:[1,0,0]
	ds_read_b128 v[238:241], v251 offset:7920
	s_waitcnt lgkmcnt(13)
	v_pk_fma_f32 v[80:81], v[242:243], v[56:57], v[80:81] op_sel:[0,1,0] op_sel_hi:[1,1,1] neg_lo:[1,0,0] neg_hi:[1,0,0]
	v_pk_fma_f32 v[82:83], v[244:245], v[56:57], v[82:83] op_sel:[0,1,0] op_sel_hi:[1,1,1] neg_lo:[1,0,0] neg_hi:[1,0,0]
	ds_read_b128 v[242:245], v251 offset:8048
	s_waitcnt lgkmcnt(13)
; #define PG8_LAS __attribute__((address_space(3)))
; __device__ __forceinline__ void solve64(float (&x)[64], const PG8_LAS float* sLt) {
;     f32x4 cur[16];
; #pragma unroll
;     for (int i4 = 0; i4 < 16; ++i4) cur[i4] = *(const PG8_LAS f32x4*)(sLt + 4 * i4);
;     asm volatile("" ::: "memory");
; #pragma unroll
;     for (int j = 0; j < 63; ++j) {
;         const float xj = x[j];
; #pragma unroll
;         for (int i4 = (j + 1) / 4; i4 < 16; ++i4) {
;             if (4 * i4 + 0 > j) x[4 * i4 + 0] -= cur[i4][0] * xj;
;             if (4 * i4 + 1 > j) x[4 * i4 + 1] -= cur[i4][1] * xj;
;             if (4 * i4 + 2 > j) x[4 * i4 + 2] -= cur[i4][2] * xj;
;             if (4 * i4 + 3 > j) x[4 * i4 + 3] -= cur[i4][3] * xj;
;             if (j + 1 < 63 && i4 >= (j + 2) / 4) cur[i4] = *(const PG8_LAS f32x4*)(sLt + (j + 1) * 64 + 4 * i4); }
;         asm volatile("" ::: "memory");
;     }
; }
	v_pk_fma_f32 v[84:85], v[246:247], v[56:57], v[84:85] op_sel:[0,1,0] op_sel_hi:[1,1,1] neg_lo:[1,0,0] neg_hi:[1,0,0]
	v_pk_fma_f32 v[86:87], v[248:249], v[56:57], v[86:87] op_sel:[0,1,0] op_sel_hi:[1,1,1] neg_lo:[1,0,0] neg_hi:[1,0,0]
	ds_read_b128 v[246:249], v251 offset:8064
	s_waitcnt lgkmcnt(13)
	v_pk_fma_f32 v[88:89], v[0:1], v[56:57], v[88:89] op_sel:[0,1,0] op_sel_hi:[1,1,1] neg_lo:[1,0,0] neg_hi:[1,0,0]
	v_pk_fma_f32 v[90:91], v[2:3], v[56:57], v[90:91] op_sel:[0,1,0] op_sel_hi:[1,1,1] neg_lo:[1,0,0] neg_hi:[1,0,0]
	ds_read_b128 v[0:3], v251 offset:8080
	s_waitcnt lgkmcnt(13)
	v_pk_fma_f32 v[92:93], v[4:5], v[56:57], v[92:93] op_sel:[0,1,0] op_sel_hi:[1,1,1] neg_lo:[1,0,0] neg_hi:[1,0,0]
	v_pk_fma_f32 v[94:95], v[6:7], v[56:57], v[94:95] op_sel:[0,1,0] op_sel_hi:[1,1,1] neg_lo:[1,0,0] neg_hi:[1,0,0]
	ds_read_b128 v[4:7], v251 offset:8096
	s_waitcnt lgkmcnt(13)
	v_fma_f32 v59, -v11, v58, v59
	ds_read_b128 v[8:11], v251 offset:8112
	s_waitcnt lgkmcnt(13)
	v_pk_fma_f32 v[60:61], v[12:13], v[58:59], v[60:61] op_sel:[0,0,0] op_sel_hi:[1,0,1] neg_lo:[1,0,0] neg_hi:[1,0,0]
	v_pk_fma_f32 v[62:63], v[14:15], v[58:59], v[62:63] op_sel:[0,0,0] op_sel_hi:[1,0,1] neg_lo:[1,0,0] neg_hi:[1,0,0]
	ds_read_b128 v[12:15], v251 offset:8128
	s_waitcnt lgkmcnt(13)
	v_pk_fma_f32 v[64:65], v[16:17], v[58:59], v[64:65] op_sel:[0,0,0] op_sel_hi:[1,0,1] neg_lo:[1,0,0] neg_hi:[1,0,0]
	v_pk_fma_f32 v[66:67], v[18:19], v[58:59], v[66:67] op_sel:[0,0,0] op_sel_hi:[1,0,1] neg_lo:[1,0,0] neg_hi:[1,0,0]
	ds_read_b128 v[16:19], v251 offset:8144
	s_waitcnt lgkmcnt(13)
	v_pk_fma_f32 v[68:69], v[20:21], v[58:59], v[68:69] op_sel:[0,0,0] op_sel_hi:[1,0,1] neg_lo:[1,0,0] neg_hi:[1,0,0]
	v_pk_fma_f32 v[70:71], v[22:23], v[58:59], v[70:71] op_sel:[0,0,0] op_sel_hi:[1,0,1] neg_lo:[1,0,0] neg_hi:[1,0,0]
	ds_read_b128 v[20:23], v251 offset:8160
	s_waitcnt lgkmcnt(13)
	v_pk_fma_f32 v[72:73], v[24:25], v[58:59], v[72:73] op_sel:[0,0,0] op_sel_hi:[1,0,1] neg_lo:[1,0,0] neg_hi:[1,0,0]
	v_pk_fma_f32 v[74:75], v[26:27], v[58:59], v[74:75] op_sel:[0,0,0] op_sel_hi:[1,0,1] neg_lo:[1,0,0] neg_hi:[1,0,0]
	ds_read_b128 v[24:27], v251 offset:8176
	s_waitcnt lgkmcnt(13)
	v_pk_fma_f32 v[76:77], v[28:29], v[58:59], v[76:77] op_sel:[0,0,0] op_sel_hi:[1,0,1] neg_lo:[1,0,0] neg_hi:[1,0,0]
	v_pk_fma_f32 v[78:79], v[30:31], v[58:59], v[78:79] op_sel:[0,0,0] op_sel_hi:[1,0,1] neg_lo:[1,0,0] neg_hi:[1,0,0]
	ds_read_b128 v[28:31], v251 offset:8304
	s_waitcnt lgkmcnt(13)
	v_pk_fma_f32 v[80:81], v[126:127], v[58:59], v[80:81] op_sel:[0,0,0] op_sel_hi:[1,0,1] neg_lo:[1,0,0] neg_hi:[1,0,0]
	v_pk_fma_f32 v[82:83], v[128:129], v[58:59], v[82:83] op_sel:[0,0,0] op_sel_hi:[1,0,1] neg_lo:[1,0,0] neg_hi:[1,0,0]
	ds_read_b128 v[126:129], v251 offset:8320
	s_waitcnt lgkmcnt(13)
	v_pk_fma_f32 v[84:85], v[230:231], v[58:59], v[84:85] op_sel:[0,0,0] op_sel_hi:[1,0,1] neg_lo:[1,0,0] neg_hi:[1,0,0]
	v_pk_fma_f32 v[86:87], v[232:233], v[58:59], v[86:87] op_sel:[0,0,0] op_sel_hi:[1,0,1] neg_lo:[1,0,0] neg_hi:[1,0,0]
	ds_read_b128 v[230:233], v251 offset:8336
	s_waitcnt lgkmcnt(13)
	v_pk_fma_f32 v[88:89], v[234:235], v[58:59], v[88:89] op_sel:[0,0,0] op_sel_hi:[1,0,1] neg_lo:[1,0,0] neg_hi:[1,0,0]
	v_pk_fma_f32 v[90:91], v[236:237], v[58:59], v[90:91] op_sel:[0,0,0] op_sel_hi:[1,0,1] neg_lo:[1,0,0] neg_hi:[1,0,0]
	ds_read_b128 v[234:237], v251 offset:8352
	s_waitcnt lgkmcnt(13)
	v_pk_fma_f32 v[92:93], v[238:239], v[58:59], v[92:93] op_sel:[0,0,0] op_sel_hi:[1,0,1] neg_lo:[1,0,0] neg_hi:[1,0,0]
	v_pk_fma_f32 v[94:95], v[240:241], v[58:59], v[94:95] op_sel:[0,0,0] op_sel_hi:[1,0,1] neg_lo:[1,0,0] neg_hi:[1,0,0]
	ds_read_b128 v[238:241], v251 offset:8368
	s_waitcnt lgkmcnt(13)
	v_pk_fma_f32 v[60:61], v[242:243], v[58:59], v[60:61] op_sel:[0,1,0] op_sel_hi:[1,1,1] neg_lo:[1,0,0] neg_hi:[1,0,0]
	v_pk_fma_f32 v[62:63], v[244:245], v[58:59], v[62:63] op_sel:[0,1,0] op_sel_hi:[1,1,1] neg_lo:[1,0,0] neg_hi:[1,0,0]
	ds_read_b128 v[242:245], v251 offset:8384
	s_waitcnt lgkmcnt(13)
	v_pk_fma_f32 v[64:65], v[246:247], v[58:59], v[64:65] op_sel:[0,1,0] op_sel_hi:[1,1,1] neg_lo:[1,0,0] neg_hi:[1,0,0]
	v_pk_fma_f32 v[66:67], v[248:249], v[58:59], v[66:67] op_sel:[0,1,0] op_sel_hi:[1,1,1] neg_lo:[1,0,0] neg_hi:[1,0,0]
	ds_read_b128 v[246:249], v251 offset:8400
	s_waitcnt lgkmcnt(13)
	v_pk_fma_f32 v[68:69], v[0:1], v[58:59], v[68:69] op_sel:[0,1,0] op_sel_hi:[1,1,1] neg_lo:[1,0,0] neg_hi:[1,0,0]
	v_pk_fma_f32 v[70:71], v[2:3], v[58:59], v[70:71] op_sel:[0,1,0] op_sel_hi:[1,1,1] neg_lo:[1,0,0] neg_hi:[1,0,0]
	ds_read_b128 v[0:3], v251 offset:8416
	s_waitcnt lgkmcnt(13)
	v_pk_fma_f32 v[72:73], v[4:5], v[58:59], v[72:73] op_sel:[0,1,0] op_sel_hi:[1,1,1] neg_lo:[1,0,0] neg_hi:[1,0,0]
	v_pk_fma_f32 v[74:75], v[6:7], v[58:59], v[74:75] op_sel:[0,1,0] op_sel_hi:[1,1,1] neg_lo:[1,0,0] neg_hi:[1,0,0]
	ds_read_b128 v[4:7], v251 offset:8432
	s_waitcnt lgkmcnt(13)
	v_pk_fma_f32 v[76:77], v[8:9], v[58:59], v[76:77] op_sel:[0,1,0] op_sel_hi:[1,1,1] neg_lo:[1,0,0] neg_hi:[1,0,0]
	v_pk_fma_f32 v[78:79], v[10:11], v[58:59], v[78:79] op_sel:[0,1,0] op_sel_hi:[1,1,1] neg_lo:[1,0,0] neg_hi:[1,0,0]
	ds_read_b128 v[8:11], v251 offset:8560
	s_waitcnt lgkmcnt(13)
	v_pk_fma_f32 v[80:81], v[12:13], v[58:59], v[80:81] op_sel:[0,1,0] op_sel_hi:[1,1,1] neg_lo:[1,0,0] neg_hi:[1,0,0]
	v_pk_fma_f32 v[82:83], v[14:15], v[58:59], v[82:83] op_sel:[0,1,0] op_sel_hi:[1,1,1] neg_lo:[1,0,0] neg_hi:[1,0,0]
	ds_read_b128 v[12:15], v251 offset:8576
	s_waitcnt lgkmcnt(13)
	v_pk_fma_f32 v[84:85], v[16:17], v[58:59], v[84:85] op_sel:[0,1,0] op_sel_hi:[1,1,1] neg_lo:[1,0,0] neg_hi:[1,0,0]
	v_pk_fma_f32 v[86:87], v[18:19], v[58:59], v[86:87] op_sel:[0,1,0] op_sel_hi:[1,1,1] neg_lo:[1,0,0] neg_hi:[1,0,0]
	ds_read_b128 v[16:19], v251 offset:8592
	s_waitcnt lgkmcnt(13)
; #define PG8_LAS __attribute__((address_space(3)))
; __device__ __forceinline__ void solve64(float (&x)[64], const PG8_LAS float* sLt) {
;     f32x4 cur[16];
; #pragma unroll
;     for (int i4 = 0; i4 < 16; ++i4) cur[i4] = *(const PG8_LAS f32x4*)(sLt + 4 * i4);
;     asm volatile("" ::: "memory");
; #pragma unroll
;     for (int j = 0; j < 63; ++j) {
;         const float xj = x[j];
; #pragma unroll
;         for (int i4 = (j + 1) / 4; i4 < 16; ++i4) {
;             if (4 * i4 + 0 > j) x[4 * i4 + 0] -= cur[i4][0] * xj;
;             if (4 * i4 + 1 > j) x[4 * i4 + 1] -= cur[i4][1] * xj;
;             if (4 * i4 + 2 > j) x[4 * i4 + 2] -= cur[i4][2] * xj;
;             if (4 * i4 + 3 > j) x[4 * i4 + 3] -= cur[i4][3] * xj;
;             if (j + 1 < 63 && i4 >= (j + 2) / 4) cur[i4] = *(const PG8_LAS f32x4*)(sLt + (j + 1) * 64 + 4 * i4); }
;         asm volatile("" ::: "memory");
;     }
; }
	v_pk_fma_f32 v[88:89], v[20:21], v[58:59], v[88:89] op_sel:[0,1,0] op_sel_hi:[1,1,1] neg_lo:[1,0,0] neg_hi:[1,0,0]
	v_pk_fma_f32 v[90:91], v[22:23], v[58:59], v[90:91] op_sel:[0,1,0] op_sel_hi:[1,1,1] neg_lo:[1,0,0] neg_hi:[1,0,0]
	ds_read_b128 v[20:23], v251 offset:8608
	s_waitcnt lgkmcnt(13)
	v_pk_fma_f32 v[92:93], v[24:25], v[58:59], v[92:93] op_sel:[0,1,0] op_sel_hi:[1,1,1] neg_lo:[1,0,0] neg_hi:[1,0,0]
	v_pk_fma_f32 v[94:95], v[26:27], v[58:59], v[94:95] op_sel:[0,1,0] op_sel_hi:[1,1,1] neg_lo:[1,0,0] neg_hi:[1,0,0]
	ds_read_b128 v[24:27], v251 offset:8624
	s_waitcnt lgkmcnt(13)
	v_fma_f32 v61, -v29, v60, v61
	v_pk_fma_f32 v[62:63], v[30:31], v[60:61], v[62:63] op_sel:[0,0,0] op_sel_hi:[1,0,1] neg_lo:[1,0,0] neg_hi:[1,0,0]
	ds_read_b128 v[28:31], v251 offset:8640
	s_waitcnt lgkmcnt(13)
	v_pk_fma_f32 v[64:65], v[126:127], v[60:61], v[64:65] op_sel:[0,0,0] op_sel_hi:[1,0,1] neg_lo:[1,0,0] neg_hi:[1,0,0]
	v_pk_fma_f32 v[66:67], v[128:129], v[60:61], v[66:67] op_sel:[0,0,0] op_sel_hi:[1,0,1] neg_lo:[1,0,0] neg_hi:[1,0,0]
	ds_read_b128 v[126:129], v251 offset:8656
	s_waitcnt lgkmcnt(13)
	v_pk_fma_f32 v[68:69], v[230:231], v[60:61], v[68:69] op_sel:[0,0,0] op_sel_hi:[1,0,1] neg_lo:[1,0,0] neg_hi:[1,0,0]
	v_pk_fma_f32 v[70:71], v[232:233], v[60:61], v[70:71] op_sel:[0,0,0] op_sel_hi:[1,0,1] neg_lo:[1,0,0] neg_hi:[1,0,0]
	ds_read_b128 v[230:233], v251 offset:8672
	s_waitcnt lgkmcnt(13)
	v_pk_fma_f32 v[72:73], v[234:235], v[60:61], v[72:73] op_sel:[0,0,0] op_sel_hi:[1,0,1] neg_lo:[1,0,0] neg_hi:[1,0,0]
	v_pk_fma_f32 v[74:75], v[236:237], v[60:61], v[74:75] op_sel:[0,0,0] op_sel_hi:[1,0,1] neg_lo:[1,0,0] neg_hi:[1,0,0]
	ds_read_b128 v[234:237], v251 offset:8688
	s_waitcnt lgkmcnt(13)
	v_pk_fma_f32 v[76:77], v[238:239], v[60:61], v[76:77] op_sel:[0,0,0] op_sel_hi:[1,0,1] neg_lo:[1,0,0] neg_hi:[1,0,0]
	v_pk_fma_f32 v[78:79], v[240:241], v[60:61], v[78:79] op_sel:[0,0,0] op_sel_hi:[1,0,1] neg_lo:[1,0,0] neg_hi:[1,0,0]
	ds_read_b128 v[238:241], v251 offset:8816
	s_waitcnt lgkmcnt(13)
	v_pk_fma_f32 v[80:81], v[242:243], v[60:61], v[80:81] op_sel:[0,0,0] op_sel_hi:[1,0,1] neg_lo:[1,0,0] neg_hi:[1,0,0]
	v_pk_fma_f32 v[82:83], v[244:245], v[60:61], v[82:83] op_sel:[0,0,0] op_sel_hi:[1,0,1] neg_lo:[1,0,0] neg_hi:[1,0,0]
	ds_read_b128 v[242:245], v251 offset:8832
	s_waitcnt lgkmcnt(13)
	v_pk_fma_f32 v[84:85], v[246:247], v[60:61], v[84:85] op_sel:[0,0,0] op_sel_hi:[1,0,1] neg_lo:[1,0,0] neg_hi:[1,0,0]
	v_pk_fma_f32 v[86:87], v[248:249], v[60:61], v[86:87] op_sel:[0,0,0] op_sel_hi:[1,0,1] neg_lo:[1,0,0] neg_hi:[1,0,0]
	ds_read_b128 v[246:249], v251 offset:8848
	s_waitcnt lgkmcnt(13)
	v_pk_fma_f32 v[88:89], v[0:1], v[60:61], v[88:89] op_sel:[0,0,0] op_sel_hi:[1,0,1] neg_lo:[1,0,0] neg_hi:[1,0,0]
	v_pk_fma_f32 v[90:91], v[2:3], v[60:61], v[90:91] op_sel:[0,0,0] op_sel_hi:[1,0,1] neg_lo:[1,0,0] neg_hi:[1,0,0]
	ds_read_b128 v[0:3], v251 offset:8864
	s_waitcnt lgkmcnt(13)
	v_pk_fma_f32 v[92:93], v[4:5], v[60:61], v[92:93] op_sel:[0,0,0] op_sel_hi:[1,0,1] neg_lo:[1,0,0] neg_hi:[1,0,0]
	v_pk_fma_f32 v[94:95], v[6:7], v[60:61], v[94:95] op_sel:[0,0,0] op_sel_hi:[1,0,1] neg_lo:[1,0,0] neg_hi:[1,0,0]
	ds_read_b128 v[4:7], v251 offset:8880
	s_waitcnt lgkmcnt(13)
	v_pk_fma_f32 v[62:63], v[10:11], v[60:61], v[62:63] op_sel:[0,1,0] op_sel_hi:[1,1,1] neg_lo:[1,0,0] neg_hi:[1,0,0]
	ds_read_b128 v[8:11], v251 offset:8896
	s_waitcnt lgkmcnt(13)
	v_pk_fma_f32 v[64:65], v[12:13], v[60:61], v[64:65] op_sel:[0,1,0] op_sel_hi:[1,1,1] neg_lo:[1,0,0] neg_hi:[1,0,0]
	v_pk_fma_f32 v[66:67], v[14:15], v[60:61], v[66:67] op_sel:[0,1,0] op_sel_hi:[1,1,1] neg_lo:[1,0,0] neg_hi:[1,0,0]
	ds_read_b128 v[12:15], v251 offset:8912
	s_waitcnt lgkmcnt(13)
	v_pk_fma_f32 v[68:69], v[16:17], v[60:61], v[68:69] op_sel:[0,1,0] op_sel_hi:[1,1,1] neg_lo:[1,0,0] neg_hi:[1,0,0]
	v_pk_fma_f32 v[70:71], v[18:19], v[60:61], v[70:71] op_sel:[0,1,0] op_sel_hi:[1,1,1] neg_lo:[1,0,0] neg_hi:[1,0,0]
	ds_read_b128 v[16:19], v251 offset:8928
	s_waitcnt lgkmcnt(13)
	v_pk_fma_f32 v[72:73], v[20:21], v[60:61], v[72:73] op_sel:[0,1,0] op_sel_hi:[1,1,1] neg_lo:[1,0,0] neg_hi:[1,0,0]
	v_pk_fma_f32 v[74:75], v[22:23], v[60:61], v[74:75] op_sel:[0,1,0] op_sel_hi:[1,1,1] neg_lo:[1,0,0] neg_hi:[1,0,0]
	ds_read_b128 v[20:23], v251 offset:8944
	s_waitcnt lgkmcnt(13)
	v_pk_fma_f32 v[76:77], v[24:25], v[60:61], v[76:77] op_sel:[0,1,0] op_sel_hi:[1,1,1] neg_lo:[1,0,0] neg_hi:[1,0,0]
	v_pk_fma_f32 v[78:79], v[26:27], v[60:61], v[78:79] op_sel:[0,1,0] op_sel_hi:[1,1,1] neg_lo:[1,0,0] neg_hi:[1,0,0]
	ds_read_b128 v[24:27], v251 offset:9088
	s_waitcnt lgkmcnt(13)
	v_pk_fma_f32 v[80:81], v[28:29], v[60:61], v[80:81] op_sel:[0,1,0] op_sel_hi:[1,1,1] neg_lo:[1,0,0] neg_hi:[1,0,0]
	v_pk_fma_f32 v[82:83], v[30:31], v[60:61], v[82:83] op_sel:[0,1,0] op_sel_hi:[1,1,1] neg_lo:[1,0,0] neg_hi:[1,0,0]
	ds_read_b128 v[28:31], v251 offset:9104
	s_waitcnt lgkmcnt(13)
	v_pk_fma_f32 v[84:85], v[126:127], v[60:61], v[84:85] op_sel:[0,1,0] op_sel_hi:[1,1,1] neg_lo:[1,0,0] neg_hi:[1,0,0]
	v_pk_fma_f32 v[86:87], v[128:129], v[60:61], v[86:87] op_sel:[0,1,0] op_sel_hi:[1,1,1] neg_lo:[1,0,0] neg_hi:[1,0,0]
	ds_read_b128 v[126:129], v251 offset:9120
	s_waitcnt lgkmcnt(13)
	v_pk_fma_f32 v[88:89], v[230:231], v[60:61], v[88:89] op_sel:[0,1,0] op_sel_hi:[1,1,1] neg_lo:[1,0,0] neg_hi:[1,0,0]
	v_pk_fma_f32 v[90:91], v[232:233], v[60:61], v[90:91] op_sel:[0,1,0] op_sel_hi:[1,1,1] neg_lo:[1,0,0] neg_hi:[1,0,0]
	ds_read_b128 v[230:233], v251 offset:9136
	s_waitcnt lgkmcnt(13)
	v_pk_fma_f32 v[92:93], v[234:235], v[60:61], v[92:93] op_sel:[0,1,0] op_sel_hi:[1,1,1] neg_lo:[1,0,0] neg_hi:[1,0,0]
	v_pk_fma_f32 v[94:95], v[236:237], v[60:61], v[94:95] op_sel:[0,1,0] op_sel_hi:[1,1,1] neg_lo:[1,0,0] neg_hi:[1,0,0]
	ds_read_b128 v[234:237], v251 offset:9152
	s_waitcnt lgkmcnt(13)
; #define PG8_LAS __attribute__((address_space(3)))
; __device__ __forceinline__ void solve64(float (&x)[64], const PG8_LAS float* sLt) {
;     f32x4 cur[16];
; #pragma unroll
;     for (int i4 = 0; i4 < 16; ++i4) cur[i4] = *(const PG8_LAS f32x4*)(sLt + 4 * i4);
;     asm volatile("" ::: "memory");
; #pragma unroll
;     for (int j = 0; j < 63; ++j) {
;         const float xj = x[j];
; #pragma unroll
;         for (int i4 = (j + 1) / 4; i4 < 16; ++i4) {
;             if (4 * i4 + 0 > j) x[4 * i4 + 0] -= cur[i4][0] * xj;
;             if (4 * i4 + 1 > j) x[4 * i4 + 1] -= cur[i4][1] * xj;
;             if (4 * i4 + 2 > j) x[4 * i4 + 2] -= cur[i4][2] * xj;
;             if (4 * i4 + 3 > j) x[4 * i4 + 3] -= cur[i4][3] * xj;
;             if (j + 1 < 63 && i4 >= (j + 2) / 4) cur[i4] = *(const PG8_LAS f32x4*)(sLt + (j + 1) * 64 + 4 * i4); }
;         asm volatile("" ::: "memory");
;     }
; }
	v_fma_f32 v63, -v241, v62, v63
	ds_read_b128 v[238:241], v251 offset:9168
	s_waitcnt lgkmcnt(13)
	v_pk_fma_f32 v[64:65], v[242:243], v[62:63], v[64:65] op_sel:[0,0,0] op_sel_hi:[1,0,1] neg_lo:[1,0,0] neg_hi:[1,0,0]
	v_pk_fma_f32 v[66:67], v[244:245], v[62:63], v[66:67] op_sel:[0,0,0] op_sel_hi:[1,0,1] neg_lo:[1,0,0] neg_hi:[1,0,0]
	ds_read_b128 v[242:245], v251 offset:9184
	s_waitcnt lgkmcnt(13)
	v_pk_fma_f32 v[68:69], v[246:247], v[62:63], v[68:69] op_sel:[0,0,0] op_sel_hi:[1,0,1] neg_lo:[1,0,0] neg_hi:[1,0,0]
	v_pk_fma_f32 v[70:71], v[248:249], v[62:63], v[70:71] op_sel:[0,0,0] op_sel_hi:[1,0,1] neg_lo:[1,0,0] neg_hi:[1,0,0]
	ds_read_b128 v[246:249], v251 offset:9200
	s_waitcnt lgkmcnt(13)
	v_pk_fma_f32 v[72:73], v[0:1], v[62:63], v[72:73] op_sel:[0,0,0] op_sel_hi:[1,0,1] neg_lo:[1,0,0] neg_hi:[1,0,0]
	v_pk_fma_f32 v[74:75], v[2:3], v[62:63], v[74:75] op_sel:[0,0,0] op_sel_hi:[1,0,1] neg_lo:[1,0,0] neg_hi:[1,0,0]
	ds_read_b128 v[0:3], v251 offset:9344
	s_waitcnt lgkmcnt(13)
	v_pk_fma_f32 v[76:77], v[4:5], v[62:63], v[76:77] op_sel:[0,0,0] op_sel_hi:[1,0,1] neg_lo:[1,0,0] neg_hi:[1,0,0]
	v_pk_fma_f32 v[78:79], v[6:7], v[62:63], v[78:79] op_sel:[0,0,0] op_sel_hi:[1,0,1] neg_lo:[1,0,0] neg_hi:[1,0,0]
	ds_read_b128 v[4:7], v251 offset:9360
	s_waitcnt lgkmcnt(13)
	v_pk_fma_f32 v[80:81], v[8:9], v[62:63], v[80:81] op_sel:[0,0,0] op_sel_hi:[1,0,1] neg_lo:[1,0,0] neg_hi:[1,0,0]
	v_pk_fma_f32 v[82:83], v[10:11], v[62:63], v[82:83] op_sel:[0,0,0] op_sel_hi:[1,0,1] neg_lo:[1,0,0] neg_hi:[1,0,0]
	ds_read_b128 v[8:11], v251 offset:9376
	s_waitcnt lgkmcnt(13)
	v_pk_fma_f32 v[84:85], v[12:13], v[62:63], v[84:85] op_sel:[0,0,0] op_sel_hi:[1,0,1] neg_lo:[1,0,0] neg_hi:[1,0,0]
	v_pk_fma_f32 v[86:87], v[14:15], v[62:63], v[86:87] op_sel:[0,0,0] op_sel_hi:[1,0,1] neg_lo:[1,0,0] neg_hi:[1,0,0]
	ds_read_b128 v[12:15], v251 offset:9392
	s_waitcnt lgkmcnt(13)
	v_pk_fma_f32 v[88:89], v[16:17], v[62:63], v[88:89] op_sel:[0,0,0] op_sel_hi:[1,0,1] neg_lo:[1,0,0] neg_hi:[1,0,0]
	v_pk_fma_f32 v[90:91], v[18:19], v[62:63], v[90:91] op_sel:[0,0,0] op_sel_hi:[1,0,1] neg_lo:[1,0,0] neg_hi:[1,0,0]
	ds_read_b128 v[16:19], v251 offset:9408
	s_waitcnt lgkmcnt(13)
	v_pk_fma_f32 v[92:93], v[20:21], v[62:63], v[92:93] op_sel:[0,0,0] op_sel_hi:[1,0,1] neg_lo:[1,0,0] neg_hi:[1,0,0]
	v_pk_fma_f32 v[94:95], v[22:23], v[62:63], v[94:95] op_sel:[0,0,0] op_sel_hi:[1,0,1] neg_lo:[1,0,0] neg_hi:[1,0,0]
	ds_read_b128 v[20:23], v251 offset:9424
	s_waitcnt lgkmcnt(13)
	v_pk_fma_f32 v[64:65], v[24:25], v[62:63], v[64:65] op_sel:[0,1,0] op_sel_hi:[1,1,1] neg_lo:[1,0,0] neg_hi:[1,0,0]
	v_pk_fma_f32 v[66:67], v[26:27], v[62:63], v[66:67] op_sel:[0,1,0] op_sel_hi:[1,1,1] neg_lo:[1,0,0] neg_hi:[1,0,0]
	ds_read_b128 v[24:27], v251 offset:9440
	s_waitcnt lgkmcnt(13)
	v_pk_fma_f32 v[68:69], v[28:29], v[62:63], v[68:69] op_sel:[0,1,0] op_sel_hi:[1,1,1] neg_lo:[1,0,0] neg_hi:[1,0,0]
	v_pk_fma_f32 v[70:71], v[30:31], v[62:63], v[70:71] op_sel:[0,1,0] op_sel_hi:[1,1,1] neg_lo:[1,0,0] neg_hi:[1,0,0]
	ds_read_b128 v[28:31], v251 offset:9456
	s_waitcnt lgkmcnt(13)
	v_pk_fma_f32 v[72:73], v[126:127], v[62:63], v[72:73] op_sel:[0,1,0] op_sel_hi:[1,1,1] neg_lo:[1,0,0] neg_hi:[1,0,0]
	v_pk_fma_f32 v[74:75], v[128:129], v[62:63], v[74:75] op_sel:[0,1,0] op_sel_hi:[1,1,1] neg_lo:[1,0,0] neg_hi:[1,0,0]
	ds_read_b128 v[126:129], v251 offset:9600
	s_waitcnt lgkmcnt(13)
	v_pk_fma_f32 v[76:77], v[230:231], v[62:63], v[76:77] op_sel:[0,1,0] op_sel_hi:[1,1,1] neg_lo:[1,0,0] neg_hi:[1,0,0]
	v_pk_fma_f32 v[78:79], v[232:233], v[62:63], v[78:79] op_sel:[0,1,0] op_sel_hi:[1,1,1] neg_lo:[1,0,0] neg_hi:[1,0,0]
	ds_read_b128 v[230:233], v251 offset:9616
	s_waitcnt lgkmcnt(13)
	v_pk_fma_f32 v[80:81], v[234:235], v[62:63], v[80:81] op_sel:[0,1,0] op_sel_hi:[1,1,1] neg_lo:[1,0,0] neg_hi:[1,0,0]
	v_pk_fma_f32 v[82:83], v[236:237], v[62:63], v[82:83] op_sel:[0,1,0] op_sel_hi:[1,1,1] neg_lo:[1,0,0] neg_hi:[1,0,0]
	ds_read_b128 v[234:237], v251 offset:9632
	s_waitcnt lgkmcnt(13)
	v_pk_fma_f32 v[84:85], v[238:239], v[62:63], v[84:85] op_sel:[0,1,0] op_sel_hi:[1,1,1] neg_lo:[1,0,0] neg_hi:[1,0,0]
	v_pk_fma_f32 v[86:87], v[240:241], v[62:63], v[86:87] op_sel:[0,1,0] op_sel_hi:[1,1,1] neg_lo:[1,0,0] neg_hi:[1,0,0]
	ds_read_b128 v[238:241], v251 offset:9648
	s_waitcnt lgkmcnt(13)
	v_pk_fma_f32 v[88:89], v[242:243], v[62:63], v[88:89] op_sel:[0,1,0] op_sel_hi:[1,1,1] neg_lo:[1,0,0] neg_hi:[1,0,0]
	v_pk_fma_f32 v[90:91], v[244:245], v[62:63], v[90:91] op_sel:[0,1,0] op_sel_hi:[1,1,1] neg_lo:[1,0,0] neg_hi:[1,0,0]
	ds_read_b128 v[242:245], v251 offset:9664
	s_waitcnt lgkmcnt(13)
	v_pk_fma_f32 v[92:93], v[246:247], v[62:63], v[92:93] op_sel:[0,1,0] op_sel_hi:[1,1,1] neg_lo:[1,0,0] neg_hi:[1,0,0]
	v_pk_fma_f32 v[94:95], v[248:249], v[62:63], v[94:95] op_sel:[0,1,0] op_sel_hi:[1,1,1] neg_lo:[1,0,0] neg_hi:[1,0,0]
	ds_read_b128 v[246:249], v251 offset:9680
	s_waitcnt lgkmcnt(13)
	v_fma_f32 v65, -v1, v64, v65
	v_pk_fma_f32 v[66:67], v[2:3], v[64:65], v[66:67] op_sel:[0,0,0] op_sel_hi:[1,0,1] neg_lo:[1,0,0] neg_hi:[1,0,0]
	ds_read_b128 v[0:3], v251 offset:9696
	s_waitcnt lgkmcnt(13)
	v_pk_fma_f32 v[68:69], v[4:5], v[64:65], v[68:69] op_sel:[0,0,0] op_sel_hi:[1,0,1] neg_lo:[1,0,0] neg_hi:[1,0,0]
	v_pk_fma_f32 v[70:71], v[6:7], v[64:65], v[70:71] op_sel:[0,0,0] op_sel_hi:[1,0,1] neg_lo:[1,0,0] neg_hi:[1,0,0]
	ds_read_b128 v[4:7], v251 offset:9712
	s_waitcnt lgkmcnt(13)
	v_pk_fma_f32 v[72:73], v[8:9], v[64:65], v[72:73] op_sel:[0,0,0] op_sel_hi:[1,0,1] neg_lo:[1,0,0] neg_hi:[1,0,0]
	v_pk_fma_f32 v[74:75], v[10:11], v[64:65], v[74:75] op_sel:[0,0,0] op_sel_hi:[1,0,1] neg_lo:[1,0,0] neg_hi:[1,0,0]
	ds_read_b128 v[8:11], v251 offset:9856
	s_waitcnt lgkmcnt(13)
; #define PG8_LAS __attribute__((address_space(3)))
; __device__ __forceinline__ void solve64(float (&x)[64], const PG8_LAS float* sLt) {
;     f32x4 cur[16];
; #pragma unroll
;     for (int i4 = 0; i4 < 16; ++i4) cur[i4] = *(const PG8_LAS f32x4*)(sLt + 4 * i4);
;     asm volatile("" ::: "memory");
; #pragma unroll
;     for (int j = 0; j < 63; ++j) {
;         const float xj = x[j];
; #pragma unroll
;         for (int i4 = (j + 1) / 4; i4 < 16; ++i4) {
;             if (4 * i4 + 0 > j) x[4 * i4 + 0] -= cur[i4][0] * xj;
;             if (4 * i4 + 1 > j) x[4 * i4 + 1] -= cur[i4][1] * xj;
;             if (4 * i4 + 2 > j) x[4 * i4 + 2] -= cur[i4][2] * xj;
;             if (4 * i4 + 3 > j) x[4 * i4 + 3] -= cur[i4][3] * xj;
;             if (j + 1 < 63 && i4 >= (j + 2) / 4) cur[i4] = *(const PG8_LAS f32x4*)(sLt + (j + 1) * 64 + 4 * i4); }
;         asm volatile("" ::: "memory");
;     }
; }
	v_pk_fma_f32 v[76:77], v[12:13], v[64:65], v[76:77] op_sel:[0,0,0] op_sel_hi:[1,0,1] neg_lo:[1,0,0] neg_hi:[1,0,0]
	v_pk_fma_f32 v[78:79], v[14:15], v[64:65], v[78:79] op_sel:[0,0,0] op_sel_hi:[1,0,1] neg_lo:[1,0,0] neg_hi:[1,0,0]
	ds_read_b128 v[12:15], v251 offset:9872
	s_waitcnt lgkmcnt(13)
	v_pk_fma_f32 v[80:81], v[16:17], v[64:65], v[80:81] op_sel:[0,0,0] op_sel_hi:[1,0,1] neg_lo:[1,0,0] neg_hi:[1,0,0]
	v_pk_fma_f32 v[82:83], v[18:19], v[64:65], v[82:83] op_sel:[0,0,0] op_sel_hi:[1,0,1] neg_lo:[1,0,0] neg_hi:[1,0,0]
	ds_read_b128 v[16:19], v251 offset:9888
	s_waitcnt lgkmcnt(13)
	v_pk_fma_f32 v[84:85], v[20:21], v[64:65], v[84:85] op_sel:[0,0,0] op_sel_hi:[1,0,1] neg_lo:[1,0,0] neg_hi:[1,0,0]
	v_pk_fma_f32 v[86:87], v[22:23], v[64:65], v[86:87] op_sel:[0,0,0] op_sel_hi:[1,0,1] neg_lo:[1,0,0] neg_hi:[1,0,0]
	ds_read_b128 v[20:23], v251 offset:9904
	s_waitcnt lgkmcnt(13)
	v_pk_fma_f32 v[88:89], v[24:25], v[64:65], v[88:89] op_sel:[0,0,0] op_sel_hi:[1,0,1] neg_lo:[1,0,0] neg_hi:[1,0,0]
	v_pk_fma_f32 v[90:91], v[26:27], v[64:65], v[90:91] op_sel:[0,0,0] op_sel_hi:[1,0,1] neg_lo:[1,0,0] neg_hi:[1,0,0]
	ds_read_b128 v[24:27], v251 offset:9920
	s_waitcnt lgkmcnt(13)
	v_pk_fma_f32 v[92:93], v[28:29], v[64:65], v[92:93] op_sel:[0,0,0] op_sel_hi:[1,0,1] neg_lo:[1,0,0] neg_hi:[1,0,0]
	v_pk_fma_f32 v[94:95], v[30:31], v[64:65], v[94:95] op_sel:[0,0,0] op_sel_hi:[1,0,1] neg_lo:[1,0,0] neg_hi:[1,0,0]
	ds_read_b128 v[28:31], v251 offset:9936
	s_waitcnt lgkmcnt(13)
	v_pk_fma_f32 v[66:67], v[128:129], v[64:65], v[66:67] op_sel:[0,1,0] op_sel_hi:[1,1,1] neg_lo:[1,0,0] neg_hi:[1,0,0]
	ds_read_b128 v[126:129], v251 offset:9952
	s_waitcnt lgkmcnt(13)
	v_pk_fma_f32 v[68:69], v[230:231], v[64:65], v[68:69] op_sel:[0,1,0] op_sel_hi:[1,1,1] neg_lo:[1,0,0] neg_hi:[1,0,0]
	v_pk_fma_f32 v[70:71], v[232:233], v[64:65], v[70:71] op_sel:[0,1,0] op_sel_hi:[1,1,1] neg_lo:[1,0,0] neg_hi:[1,0,0]
	ds_read_b128 v[230:233], v251 offset:9968
	s_waitcnt lgkmcnt(13)
	v_pk_fma_f32 v[72:73], v[234:235], v[64:65], v[72:73] op_sel:[0,1,0] op_sel_hi:[1,1,1] neg_lo:[1,0,0] neg_hi:[1,0,0]
	v_pk_fma_f32 v[74:75], v[236:237], v[64:65], v[74:75] op_sel:[0,1,0] op_sel_hi:[1,1,1] neg_lo:[1,0,0] neg_hi:[1,0,0]
	ds_read_b128 v[234:237], v251 offset:10128
	s_waitcnt lgkmcnt(13)
	v_pk_fma_f32 v[76:77], v[238:239], v[64:65], v[76:77] op_sel:[0,1,0] op_sel_hi:[1,1,1] neg_lo:[1,0,0] neg_hi:[1,0,0]
	v_pk_fma_f32 v[78:79], v[240:241], v[64:65], v[78:79] op_sel:[0,1,0] op_sel_hi:[1,1,1] neg_lo:[1,0,0] neg_hi:[1,0,0]
	ds_read_b128 v[238:241], v251 offset:10144
	s_waitcnt lgkmcnt(13)
	v_pk_fma_f32 v[80:81], v[242:243], v[64:65], v[80:81] op_sel:[0,1,0] op_sel_hi:[1,1,1] neg_lo:[1,0,0] neg_hi:[1,0,0]
	v_pk_fma_f32 v[82:83], v[244:245], v[64:65], v[82:83] op_sel:[0,1,0] op_sel_hi:[1,1,1] neg_lo:[1,0,0] neg_hi:[1,0,0]
	ds_read_b128 v[242:245], v251 offset:10160
	s_waitcnt lgkmcnt(13)
	v_pk_fma_f32 v[84:85], v[246:247], v[64:65], v[84:85] op_sel:[0,1,0] op_sel_hi:[1,1,1] neg_lo:[1,0,0] neg_hi:[1,0,0]
	v_pk_fma_f32 v[86:87], v[248:249], v[64:65], v[86:87] op_sel:[0,1,0] op_sel_hi:[1,1,1] neg_lo:[1,0,0] neg_hi:[1,0,0]
	ds_read_b128 v[246:249], v251 offset:10176
	s_waitcnt lgkmcnt(13)
	v_pk_fma_f32 v[88:89], v[0:1], v[64:65], v[88:89] op_sel:[0,1,0] op_sel_hi:[1,1,1] neg_lo:[1,0,0] neg_hi:[1,0,0]
	v_pk_fma_f32 v[90:91], v[2:3], v[64:65], v[90:91] op_sel:[0,1,0] op_sel_hi:[1,1,1] neg_lo:[1,0,0] neg_hi:[1,0,0]
	ds_read_b128 v[0:3], v251 offset:10192
	s_waitcnt lgkmcnt(13)
	v_pk_fma_f32 v[92:93], v[4:5], v[64:65], v[92:93] op_sel:[0,1,0] op_sel_hi:[1,1,1] neg_lo:[1,0,0] neg_hi:[1,0,0]
	v_pk_fma_f32 v[94:95], v[6:7], v[64:65], v[94:95] op_sel:[0,1,0] op_sel_hi:[1,1,1] neg_lo:[1,0,0] neg_hi:[1,0,0]
	ds_read_b128 v[4:7], v251 offset:10208
	s_waitcnt lgkmcnt(13)
	v_fma_f32 v67, -v11, v66, v67
	ds_read_b128 v[8:11], v251 offset:10224
	s_waitcnt lgkmcnt(13)
	v_pk_fma_f32 v[68:69], v[12:13], v[66:67], v[68:69] op_sel:[0,0,0] op_sel_hi:[1,0,1] neg_lo:[1,0,0] neg_hi:[1,0,0]
	v_pk_fma_f32 v[70:71], v[14:15], v[66:67], v[70:71] op_sel:[0,0,0] op_sel_hi:[1,0,1] neg_lo:[1,0,0] neg_hi:[1,0,0]
	ds_read_b128 v[12:15], v251 offset:10384
	s_waitcnt lgkmcnt(13)
	v_pk_fma_f32 v[72:73], v[16:17], v[66:67], v[72:73] op_sel:[0,0,0] op_sel_hi:[1,0,1] neg_lo:[1,0,0] neg_hi:[1,0,0]
	v_pk_fma_f32 v[74:75], v[18:19], v[66:67], v[74:75] op_sel:[0,0,0] op_sel_hi:[1,0,1] neg_lo:[1,0,0] neg_hi:[1,0,0]
	ds_read_b128 v[16:19], v251 offset:10400
	s_waitcnt lgkmcnt(13)
	v_pk_fma_f32 v[76:77], v[20:21], v[66:67], v[76:77] op_sel:[0,0,0] op_sel_hi:[1,0,1] neg_lo:[1,0,0] neg_hi:[1,0,0]
	v_pk_fma_f32 v[78:79], v[22:23], v[66:67], v[78:79] op_sel:[0,0,0] op_sel_hi:[1,0,1] neg_lo:[1,0,0] neg_hi:[1,0,0]
	ds_read_b128 v[20:23], v251 offset:10416
	s_waitcnt lgkmcnt(13)
	v_pk_fma_f32 v[80:81], v[24:25], v[66:67], v[80:81] op_sel:[0,0,0] op_sel_hi:[1,0,1] neg_lo:[1,0,0] neg_hi:[1,0,0]
	v_pk_fma_f32 v[82:83], v[26:27], v[66:67], v[82:83] op_sel:[0,0,0] op_sel_hi:[1,0,1] neg_lo:[1,0,0] neg_hi:[1,0,0]
	ds_read_b128 v[24:27], v251 offset:10432
	s_waitcnt lgkmcnt(13)
	v_pk_fma_f32 v[84:85], v[28:29], v[66:67], v[84:85] op_sel:[0,0,0] op_sel_hi:[1,0,1] neg_lo:[1,0,0] neg_hi:[1,0,0]
	v_pk_fma_f32 v[86:87], v[30:31], v[66:67], v[86:87] op_sel:[0,0,0] op_sel_hi:[1,0,1] neg_lo:[1,0,0] neg_hi:[1,0,0]
	ds_read_b128 v[28:31], v251 offset:10448
	s_waitcnt lgkmcnt(13)
	v_pk_fma_f32 v[88:89], v[126:127], v[66:67], v[88:89] op_sel:[0,0,0] op_sel_hi:[1,0,1] neg_lo:[1,0,0] neg_hi:[1,0,0]
	v_pk_fma_f32 v[90:91], v[128:129], v[66:67], v[90:91] op_sel:[0,0,0] op_sel_hi:[1,0,1] neg_lo:[1,0,0] neg_hi:[1,0,0]
	ds_read_b128 v[126:129], v251 offset:10464
	s_waitcnt lgkmcnt(13)
; #define PG8_LAS __attribute__((address_space(3)))
; __device__ __forceinline__ void solve64(float (&x)[64], const PG8_LAS float* sLt) {
;     f32x4 cur[16];
; #pragma unroll
;     for (int i4 = 0; i4 < 16; ++i4) cur[i4] = *(const PG8_LAS f32x4*)(sLt + 4 * i4);
;     asm volatile("" ::: "memory");
; #pragma unroll
;     for (int j = 0; j < 63; ++j) {
;         const float xj = x[j];
; #pragma unroll
;         for (int i4 = (j + 1) / 4; i4 < 16; ++i4) {
;             if (4 * i4 + 0 > j) x[4 * i4 + 0] -= cur[i4][0] * xj;
;             if (4 * i4 + 1 > j) x[4 * i4 + 1] -= cur[i4][1] * xj;
;             if (4 * i4 + 2 > j) x[4 * i4 + 2] -= cur[i4][2] * xj;
;             if (4 * i4 + 3 > j) x[4 * i4 + 3] -= cur[i4][3] * xj;
;             if (j + 1 < 63 && i4 >= (j + 2) / 4) cur[i4] = *(const PG8_LAS f32x4*)(sLt + (j + 1) * 64 + 4 * i4); }
;         asm volatile("" ::: "memory");
;     }
; }
	v_pk_fma_f32 v[92:93], v[230:231], v[66:67], v[92:93] op_sel:[0,0,0] op_sel_hi:[1,0,1] neg_lo:[1,0,0] neg_hi:[1,0,0]
	v_pk_fma_f32 v[94:95], v[232:233], v[66:67], v[94:95] op_sel:[0,0,0] op_sel_hi:[1,0,1] neg_lo:[1,0,0] neg_hi:[1,0,0]
	ds_read_b128 v[230:233], v251 offset:10480
	s_waitcnt lgkmcnt(13)
	v_pk_fma_f32 v[68:69], v[234:235], v[66:67], v[68:69] op_sel:[0,1,0] op_sel_hi:[1,1,1] neg_lo:[1,0,0] neg_hi:[1,0,0]
	v_pk_fma_f32 v[70:71], v[236:237], v[66:67], v[70:71] op_sel:[0,1,0] op_sel_hi:[1,1,1] neg_lo:[1,0,0] neg_hi:[1,0,0]
	ds_read_b128 v[234:237], v251 offset:10640
	s_waitcnt lgkmcnt(13)
	v_pk_fma_f32 v[72:73], v[238:239], v[66:67], v[72:73] op_sel:[0,1,0] op_sel_hi:[1,1,1] neg_lo:[1,0,0] neg_hi:[1,0,0]
	v_pk_fma_f32 v[74:75], v[240:241], v[66:67], v[74:75] op_sel:[0,1,0] op_sel_hi:[1,1,1] neg_lo:[1,0,0] neg_hi:[1,0,0]
	ds_read_b128 v[238:241], v251 offset:10656
	s_waitcnt lgkmcnt(13)
	v_pk_fma_f32 v[76:77], v[242:243], v[66:67], v[76:77] op_sel:[0,1,0] op_sel_hi:[1,1,1] neg_lo:[1,0,0] neg_hi:[1,0,0]
	v_pk_fma_f32 v[78:79], v[244:245], v[66:67], v[78:79] op_sel:[0,1,0] op_sel_hi:[1,1,1] neg_lo:[1,0,0] neg_hi:[1,0,0]
	ds_read_b128 v[242:245], v251 offset:10672
	s_waitcnt lgkmcnt(13)
	v_pk_fma_f32 v[80:81], v[246:247], v[66:67], v[80:81] op_sel:[0,1,0] op_sel_hi:[1,1,1] neg_lo:[1,0,0] neg_hi:[1,0,0]
	v_pk_fma_f32 v[82:83], v[248:249], v[66:67], v[82:83] op_sel:[0,1,0] op_sel_hi:[1,1,1] neg_lo:[1,0,0] neg_hi:[1,0,0]
	ds_read_b128 v[246:249], v251 offset:10688
	s_waitcnt lgkmcnt(13)
	v_pk_fma_f32 v[84:85], v[0:1], v[66:67], v[84:85] op_sel:[0,1,0] op_sel_hi:[1,1,1] neg_lo:[1,0,0] neg_hi:[1,0,0]
	v_pk_fma_f32 v[86:87], v[2:3], v[66:67], v[86:87] op_sel:[0,1,0] op_sel_hi:[1,1,1] neg_lo:[1,0,0] neg_hi:[1,0,0]
	ds_read_b128 v[0:3], v251 offset:10704
	s_waitcnt lgkmcnt(13)
	v_pk_fma_f32 v[88:89], v[4:5], v[66:67], v[88:89] op_sel:[0,1,0] op_sel_hi:[1,1,1] neg_lo:[1,0,0] neg_hi:[1,0,0]
	v_pk_fma_f32 v[90:91], v[6:7], v[66:67], v[90:91] op_sel:[0,1,0] op_sel_hi:[1,1,1] neg_lo:[1,0,0] neg_hi:[1,0,0]
	ds_read_b128 v[4:7], v251 offset:10720
	s_waitcnt lgkmcnt(13)
	v_pk_fma_f32 v[92:93], v[8:9], v[66:67], v[92:93] op_sel:[0,1,0] op_sel_hi:[1,1,1] neg_lo:[1,0,0] neg_hi:[1,0,0]
	v_pk_fma_f32 v[94:95], v[10:11], v[66:67], v[94:95] op_sel:[0,1,0] op_sel_hi:[1,1,1] neg_lo:[1,0,0] neg_hi:[1,0,0]
	ds_read_b128 v[8:11], v251 offset:10736
	s_waitcnt lgkmcnt(13)
	v_fma_f32 v69, -v13, v68, v69
	v_pk_fma_f32 v[70:71], v[14:15], v[68:69], v[70:71] op_sel:[0,0,0] op_sel_hi:[1,0,1] neg_lo:[1,0,0] neg_hi:[1,0,0]
	ds_read_b128 v[12:15], v251 offset:10896
	s_waitcnt lgkmcnt(13)
	v_pk_fma_f32 v[72:73], v[16:17], v[68:69], v[72:73] op_sel:[0,0,0] op_sel_hi:[1,0,1] neg_lo:[1,0,0] neg_hi:[1,0,0]
	v_pk_fma_f32 v[74:75], v[18:19], v[68:69], v[74:75] op_sel:[0,0,0] op_sel_hi:[1,0,1] neg_lo:[1,0,0] neg_hi:[1,0,0]
	ds_read_b128 v[16:19], v251 offset:10912
	s_waitcnt lgkmcnt(13)
	v_pk_fma_f32 v[76:77], v[20:21], v[68:69], v[76:77] op_sel:[0,0,0] op_sel_hi:[1,0,1] neg_lo:[1,0,0] neg_hi:[1,0,0]
	v_pk_fma_f32 v[78:79], v[22:23], v[68:69], v[78:79] op_sel:[0,0,0] op_sel_hi:[1,0,1] neg_lo:[1,0,0] neg_hi:[1,0,0]
	ds_read_b128 v[20:23], v251 offset:10928
	s_waitcnt lgkmcnt(13)
	v_pk_fma_f32 v[80:81], v[24:25], v[68:69], v[80:81] op_sel:[0,0,0] op_sel_hi:[1,0,1] neg_lo:[1,0,0] neg_hi:[1,0,0]
	v_pk_fma_f32 v[82:83], v[26:27], v[68:69], v[82:83] op_sel:[0,0,0] op_sel_hi:[1,0,1] neg_lo:[1,0,0] neg_hi:[1,0,0]
	ds_read_b128 v[24:27], v251 offset:10944
	s_waitcnt lgkmcnt(13)
	v_pk_fma_f32 v[84:85], v[28:29], v[68:69], v[84:85] op_sel:[0,0,0] op_sel_hi:[1,0,1] neg_lo:[1,0,0] neg_hi:[1,0,0]
	v_pk_fma_f32 v[86:87], v[30:31], v[68:69], v[86:87] op_sel:[0,0,0] op_sel_hi:[1,0,1] neg_lo:[1,0,0] neg_hi:[1,0,0]
	ds_read_b128 v[28:31], v251 offset:10960
	s_waitcnt lgkmcnt(13)
	v_pk_fma_f32 v[88:89], v[126:127], v[68:69], v[88:89] op_sel:[0,0,0] op_sel_hi:[1,0,1] neg_lo:[1,0,0] neg_hi:[1,0,0]
	v_pk_fma_f32 v[90:91], v[128:129], v[68:69], v[90:91] op_sel:[0,0,0] op_sel_hi:[1,0,1] neg_lo:[1,0,0] neg_hi:[1,0,0]
	ds_read_b128 v[126:129], v251 offset:10976
	s_waitcnt lgkmcnt(13)
	v_pk_fma_f32 v[92:93], v[230:231], v[68:69], v[92:93] op_sel:[0,0,0] op_sel_hi:[1,0,1] neg_lo:[1,0,0] neg_hi:[1,0,0]
	v_pk_fma_f32 v[94:95], v[232:233], v[68:69], v[94:95] op_sel:[0,0,0] op_sel_hi:[1,0,1] neg_lo:[1,0,0] neg_hi:[1,0,0]
	ds_read_b128 v[230:233], v251 offset:10992
	s_waitcnt lgkmcnt(13)
	v_pk_fma_f32 v[70:71], v[236:237], v[68:69], v[70:71] op_sel:[0,1,0] op_sel_hi:[1,1,1] neg_lo:[1,0,0] neg_hi:[1,0,0]
	ds_read_b128 v[234:237], v251 offset:11168
	s_waitcnt lgkmcnt(13)
	v_pk_fma_f32 v[72:73], v[238:239], v[68:69], v[72:73] op_sel:[0,1,0] op_sel_hi:[1,1,1] neg_lo:[1,0,0] neg_hi:[1,0,0]
	v_pk_fma_f32 v[74:75], v[240:241], v[68:69], v[74:75] op_sel:[0,1,0] op_sel_hi:[1,1,1] neg_lo:[1,0,0] neg_hi:[1,0,0]
	ds_read_b128 v[238:241], v251 offset:11184
	s_waitcnt lgkmcnt(13)
	v_pk_fma_f32 v[76:77], v[242:243], v[68:69], v[76:77] op_sel:[0,1,0] op_sel_hi:[1,1,1] neg_lo:[1,0,0] neg_hi:[1,0,0]
	v_pk_fma_f32 v[78:79], v[244:245], v[68:69], v[78:79] op_sel:[0,1,0] op_sel_hi:[1,1,1] neg_lo:[1,0,0] neg_hi:[1,0,0]
	ds_read_b128 v[242:245], v251 offset:11200
	s_waitcnt lgkmcnt(13)
	v_pk_fma_f32 v[80:81], v[246:247], v[68:69], v[80:81] op_sel:[0,1,0] op_sel_hi:[1,1,1] neg_lo:[1,0,0] neg_hi:[1,0,0]
	v_pk_fma_f32 v[82:83], v[248:249], v[68:69], v[82:83] op_sel:[0,1,0] op_sel_hi:[1,1,1] neg_lo:[1,0,0] neg_hi:[1,0,0]
	ds_read_b128 v[246:249], v251 offset:11216
	s_waitcnt lgkmcnt(13)
	v_pk_fma_f32 v[84:85], v[0:1], v[68:69], v[84:85] op_sel:[0,1,0] op_sel_hi:[1,1,1] neg_lo:[1,0,0] neg_hi:[1,0,0]
	v_pk_fma_f32 v[86:87], v[2:3], v[68:69], v[86:87] op_sel:[0,1,0] op_sel_hi:[1,1,1] neg_lo:[1,0,0] neg_hi:[1,0,0]
	ds_read_b128 v[0:3], v251 offset:11232
	s_waitcnt lgkmcnt(13)
; #define PG8_LAS __attribute__((address_space(3)))
; __device__ __forceinline__ void solve64(float (&x)[64], const PG8_LAS float* sLt) {
;     f32x4 cur[16];
; #pragma unroll
;     for (int i4 = 0; i4 < 16; ++i4) cur[i4] = *(const PG8_LAS f32x4*)(sLt + 4 * i4);
;     asm volatile("" ::: "memory");
; #pragma unroll
;     for (int j = 0; j < 63; ++j) {
;         const float xj = x[j];
; #pragma unroll
;         for (int i4 = (j + 1) / 4; i4 < 16; ++i4) {
;             if (4 * i4 + 0 > j) x[4 * i4 + 0] -= cur[i4][0] * xj;
;             if (4 * i4 + 1 > j) x[4 * i4 + 1] -= cur[i4][1] * xj;
;             if (4 * i4 + 2 > j) x[4 * i4 + 2] -= cur[i4][2] * xj;
;             if (4 * i4 + 3 > j) x[4 * i4 + 3] -= cur[i4][3] * xj;
;             if (j + 1 < 63 && i4 >= (j + 2) / 4) cur[i4] = *(const PG8_LAS f32x4*)(sLt + (j + 1) * 64 + 4 * i4); }
;         asm volatile("" ::: "memory");
;     }
; }
	v_pk_fma_f32 v[88:89], v[4:5], v[68:69], v[88:89] op_sel:[0,1,0] op_sel_hi:[1,1,1] neg_lo:[1,0,0] neg_hi:[1,0,0]
	v_pk_fma_f32 v[90:91], v[6:7], v[68:69], v[90:91] op_sel:[0,1,0] op_sel_hi:[1,1,1] neg_lo:[1,0,0] neg_hi:[1,0,0]
	ds_read_b128 v[4:7], v251 offset:11248
	s_waitcnt lgkmcnt(13)
	v_pk_fma_f32 v[92:93], v[8:9], v[68:69], v[92:93] op_sel:[0,1,0] op_sel_hi:[1,1,1] neg_lo:[1,0,0] neg_hi:[1,0,0]
	v_pk_fma_f32 v[94:95], v[10:11], v[68:69], v[94:95] op_sel:[0,1,0] op_sel_hi:[1,1,1] neg_lo:[1,0,0] neg_hi:[1,0,0]
	ds_read_b128 v[8:11], v251 offset:11424
	s_waitcnt lgkmcnt(13)
	v_fma_f32 v71, -v15, v70, v71
	ds_read_b128 v[12:15], v251 offset:11440
	s_waitcnt lgkmcnt(13)
	v_pk_fma_f32 v[72:73], v[16:17], v[70:71], v[72:73] op_sel:[0,0,0] op_sel_hi:[1,0,1] neg_lo:[1,0,0] neg_hi:[1,0,0]
	v_pk_fma_f32 v[74:75], v[18:19], v[70:71], v[74:75] op_sel:[0,0,0] op_sel_hi:[1,0,1] neg_lo:[1,0,0] neg_hi:[1,0,0]
	ds_read_b128 v[16:19], v251 offset:11456
	s_waitcnt lgkmcnt(13)
	v_pk_fma_f32 v[76:77], v[20:21], v[70:71], v[76:77] op_sel:[0,0,0] op_sel_hi:[1,0,1] neg_lo:[1,0,0] neg_hi:[1,0,0]
	v_pk_fma_f32 v[78:79], v[22:23], v[70:71], v[78:79] op_sel:[0,0,0] op_sel_hi:[1,0,1] neg_lo:[1,0,0] neg_hi:[1,0,0]
	ds_read_b128 v[20:23], v251 offset:11472
	s_waitcnt lgkmcnt(13)
	v_pk_fma_f32 v[80:81], v[24:25], v[70:71], v[80:81] op_sel:[0,0,0] op_sel_hi:[1,0,1] neg_lo:[1,0,0] neg_hi:[1,0,0]
	v_pk_fma_f32 v[82:83], v[26:27], v[70:71], v[82:83] op_sel:[0,0,0] op_sel_hi:[1,0,1] neg_lo:[1,0,0] neg_hi:[1,0,0]
	ds_read_b128 v[24:27], v251 offset:11488
	s_waitcnt lgkmcnt(13)
	v_pk_fma_f32 v[84:85], v[28:29], v[70:71], v[84:85] op_sel:[0,0,0] op_sel_hi:[1,0,1] neg_lo:[1,0,0] neg_hi:[1,0,0]
	v_pk_fma_f32 v[86:87], v[30:31], v[70:71], v[86:87] op_sel:[0,0,0] op_sel_hi:[1,0,1] neg_lo:[1,0,0] neg_hi:[1,0,0]
	ds_read_b128 v[28:31], v251 offset:11504
	s_waitcnt lgkmcnt(13)
	v_pk_fma_f32 v[88:89], v[126:127], v[70:71], v[88:89] op_sel:[0,0,0] op_sel_hi:[1,0,1] neg_lo:[1,0,0] neg_hi:[1,0,0]
	v_pk_fma_f32 v[90:91], v[128:129], v[70:71], v[90:91] op_sel:[0,0,0] op_sel_hi:[1,0,1] neg_lo:[1,0,0] neg_hi:[1,0,0]
	ds_read_b128 v[126:129], v251 offset:11680
	s_waitcnt lgkmcnt(13)
	v_pk_fma_f32 v[92:93], v[230:231], v[70:71], v[92:93] op_sel:[0,0,0] op_sel_hi:[1,0,1] neg_lo:[1,0,0] neg_hi:[1,0,0]
	v_pk_fma_f32 v[94:95], v[232:233], v[70:71], v[94:95] op_sel:[0,0,0] op_sel_hi:[1,0,1] neg_lo:[1,0,0] neg_hi:[1,0,0]
	ds_read_b128 v[230:233], v251 offset:11696
	s_waitcnt lgkmcnt(13)
	v_pk_fma_f32 v[72:73], v[234:235], v[70:71], v[72:73] op_sel:[0,1,0] op_sel_hi:[1,1,1] neg_lo:[1,0,0] neg_hi:[1,0,0]
	v_pk_fma_f32 v[74:75], v[236:237], v[70:71], v[74:75] op_sel:[0,1,0] op_sel_hi:[1,1,1] neg_lo:[1,0,0] neg_hi:[1,0,0]
	ds_read_b128 v[234:237], v251 offset:11712
	s_waitcnt lgkmcnt(13)
	v_pk_fma_f32 v[76:77], v[238:239], v[70:71], v[76:77] op_sel:[0,1,0] op_sel_hi:[1,1,1] neg_lo:[1,0,0] neg_hi:[1,0,0]
	v_pk_fma_f32 v[78:79], v[240:241], v[70:71], v[78:79] op_sel:[0,1,0] op_sel_hi:[1,1,1] neg_lo:[1,0,0] neg_hi:[1,0,0]
	ds_read_b128 v[238:241], v251 offset:11728
	s_waitcnt lgkmcnt(13)
	v_pk_fma_f32 v[80:81], v[242:243], v[70:71], v[80:81] op_sel:[0,1,0] op_sel_hi:[1,1,1] neg_lo:[1,0,0] neg_hi:[1,0,0]
	v_pk_fma_f32 v[82:83], v[244:245], v[70:71], v[82:83] op_sel:[0,1,0] op_sel_hi:[1,1,1] neg_lo:[1,0,0] neg_hi:[1,0,0]
	ds_read_b128 v[242:245], v251 offset:11744
	s_waitcnt lgkmcnt(13)
	v_pk_fma_f32 v[84:85], v[246:247], v[70:71], v[84:85] op_sel:[0,1,0] op_sel_hi:[1,1,1] neg_lo:[1,0,0] neg_hi:[1,0,0]
	v_pk_fma_f32 v[86:87], v[248:249], v[70:71], v[86:87] op_sel:[0,1,0] op_sel_hi:[1,1,1] neg_lo:[1,0,0] neg_hi:[1,0,0]
	ds_read_b128 v[246:249], v251 offset:11760
	s_waitcnt lgkmcnt(13)
	v_pk_fma_f32 v[88:89], v[0:1], v[70:71], v[88:89] op_sel:[0,1,0] op_sel_hi:[1,1,1] neg_lo:[1,0,0] neg_hi:[1,0,0]
	v_pk_fma_f32 v[90:91], v[2:3], v[70:71], v[90:91] op_sel:[0,1,0] op_sel_hi:[1,1,1] neg_lo:[1,0,0] neg_hi:[1,0,0]
	ds_read_b128 v[0:3], v251 offset:11936
	s_waitcnt lgkmcnt(13)
	v_pk_fma_f32 v[92:93], v[4:5], v[70:71], v[92:93] op_sel:[0,1,0] op_sel_hi:[1,1,1] neg_lo:[1,0,0] neg_hi:[1,0,0]
	v_pk_fma_f32 v[94:95], v[6:7], v[70:71], v[94:95] op_sel:[0,1,0] op_sel_hi:[1,1,1] neg_lo:[1,0,0] neg_hi:[1,0,0]
	ds_read_b128 v[4:7], v251 offset:11952
	s_waitcnt lgkmcnt(13)
	v_fma_f32 v73, -v9, v72, v73
	v_pk_fma_f32 v[74:75], v[10:11], v[72:73], v[74:75] op_sel:[0,0,0] op_sel_hi:[1,0,1] neg_lo:[1,0,0] neg_hi:[1,0,0]
	ds_read_b128 v[8:11], v251 offset:11968
	s_waitcnt lgkmcnt(13)
	v_pk_fma_f32 v[76:77], v[12:13], v[72:73], v[76:77] op_sel:[0,0,0] op_sel_hi:[1,0,1] neg_lo:[1,0,0] neg_hi:[1,0,0]
	v_pk_fma_f32 v[78:79], v[14:15], v[72:73], v[78:79] op_sel:[0,0,0] op_sel_hi:[1,0,1] neg_lo:[1,0,0] neg_hi:[1,0,0]
	ds_read_b128 v[12:15], v251 offset:11984
	s_waitcnt lgkmcnt(13)
	v_pk_fma_f32 v[80:81], v[16:17], v[72:73], v[80:81] op_sel:[0,0,0] op_sel_hi:[1,0,1] neg_lo:[1,0,0] neg_hi:[1,0,0]
	v_pk_fma_f32 v[82:83], v[18:19], v[72:73], v[82:83] op_sel:[0,0,0] op_sel_hi:[1,0,1] neg_lo:[1,0,0] neg_hi:[1,0,0]
	ds_read_b128 v[16:19], v251 offset:12000
	s_waitcnt lgkmcnt(13)
	v_pk_fma_f32 v[84:85], v[20:21], v[72:73], v[84:85] op_sel:[0,0,0] op_sel_hi:[1,0,1] neg_lo:[1,0,0] neg_hi:[1,0,0]
	v_pk_fma_f32 v[86:87], v[22:23], v[72:73], v[86:87] op_sel:[0,0,0] op_sel_hi:[1,0,1] neg_lo:[1,0,0] neg_hi:[1,0,0]
	ds_read_b128 v[20:23], v251 offset:12016
	s_waitcnt lgkmcnt(13)
	v_pk_fma_f32 v[88:89], v[24:25], v[72:73], v[88:89] op_sel:[0,0,0] op_sel_hi:[1,0,1] neg_lo:[1,0,0] neg_hi:[1,0,0]
	v_pk_fma_f32 v[90:91], v[26:27], v[72:73], v[90:91] op_sel:[0,0,0] op_sel_hi:[1,0,1] neg_lo:[1,0,0] neg_hi:[1,0,0]
	ds_read_b128 v[24:27], v251 offset:12208
	s_waitcnt lgkmcnt(13)
; #define PG8_LAS __attribute__((address_space(3)))
; __device__ __forceinline__ void solve64(float (&x)[64], const PG8_LAS float* sLt) {
;     f32x4 cur[16];
; #pragma unroll
;     for (int i4 = 0; i4 < 16; ++i4) cur[i4] = *(const PG8_LAS f32x4*)(sLt + 4 * i4);
;     asm volatile("" ::: "memory");
; #pragma unroll
;     for (int j = 0; j < 63; ++j) {
;         const float xj = x[j];
; #pragma unroll
;         for (int i4 = (j + 1) / 4; i4 < 16; ++i4) {
;             if (4 * i4 + 0 > j) x[4 * i4 + 0] -= cur[i4][0] * xj;
;             if (4 * i4 + 1 > j) x[4 * i4 + 1] -= cur[i4][1] * xj;
;             if (4 * i4 + 2 > j) x[4 * i4 + 2] -= cur[i4][2] * xj;
;             if (4 * i4 + 3 > j) x[4 * i4 + 3] -= cur[i4][3] * xj;
;             if (j + 1 < 63 && i4 >= (j + 2) / 4) cur[i4] = *(const PG8_LAS f32x4*)(sLt + (j + 1) * 64 + 4 * i4); }
;         asm volatile("" ::: "memory");
;     }
; }
	v_pk_fma_f32 v[92:93], v[28:29], v[72:73], v[92:93] op_sel:[0,0,0] op_sel_hi:[1,0,1] neg_lo:[1,0,0] neg_hi:[1,0,0]
	v_pk_fma_f32 v[94:95], v[30:31], v[72:73], v[94:95] op_sel:[0,0,0] op_sel_hi:[1,0,1] neg_lo:[1,0,0] neg_hi:[1,0,0]
	ds_read_b128 v[28:31], v251 offset:12224
	s_waitcnt lgkmcnt(13)
	v_pk_fma_f32 v[74:75], v[128:129], v[72:73], v[74:75] op_sel:[0,1,0] op_sel_hi:[1,1,1] neg_lo:[1,0,0] neg_hi:[1,0,0]
	ds_read_b128 v[126:129], v251 offset:12240
	s_waitcnt lgkmcnt(13)
	v_pk_fma_f32 v[76:77], v[230:231], v[72:73], v[76:77] op_sel:[0,1,0] op_sel_hi:[1,1,1] neg_lo:[1,0,0] neg_hi:[1,0,0]
	v_pk_fma_f32 v[78:79], v[232:233], v[72:73], v[78:79] op_sel:[0,1,0] op_sel_hi:[1,1,1] neg_lo:[1,0,0] neg_hi:[1,0,0]
	ds_read_b128 v[230:233], v251 offset:12256
	s_waitcnt lgkmcnt(13)
	v_pk_fma_f32 v[80:81], v[234:235], v[72:73], v[80:81] op_sel:[0,1,0] op_sel_hi:[1,1,1] neg_lo:[1,0,0] neg_hi:[1,0,0]
	v_pk_fma_f32 v[82:83], v[236:237], v[72:73], v[82:83] op_sel:[0,1,0] op_sel_hi:[1,1,1] neg_lo:[1,0,0] neg_hi:[1,0,0]
	ds_read_b128 v[234:237], v251 offset:12272
	s_waitcnt lgkmcnt(13)
	v_pk_fma_f32 v[84:85], v[238:239], v[72:73], v[84:85] op_sel:[0,1,0] op_sel_hi:[1,1,1] neg_lo:[1,0,0] neg_hi:[1,0,0]
	v_pk_fma_f32 v[86:87], v[240:241], v[72:73], v[86:87] op_sel:[0,1,0] op_sel_hi:[1,1,1] neg_lo:[1,0,0] neg_hi:[1,0,0]
	ds_read_b128 v[238:241], v251 offset:12464
	s_waitcnt lgkmcnt(13)
	v_pk_fma_f32 v[88:89], v[242:243], v[72:73], v[88:89] op_sel:[0,1,0] op_sel_hi:[1,1,1] neg_lo:[1,0,0] neg_hi:[1,0,0]
	v_pk_fma_f32 v[90:91], v[244:245], v[72:73], v[90:91] op_sel:[0,1,0] op_sel_hi:[1,1,1] neg_lo:[1,0,0] neg_hi:[1,0,0]
	ds_read_b128 v[242:245], v251 offset:12480
	s_waitcnt lgkmcnt(13)
	v_pk_fma_f32 v[92:93], v[246:247], v[72:73], v[92:93] op_sel:[0,1,0] op_sel_hi:[1,1,1] neg_lo:[1,0,0] neg_hi:[1,0,0]
	v_pk_fma_f32 v[94:95], v[248:249], v[72:73], v[94:95] op_sel:[0,1,0] op_sel_hi:[1,1,1] neg_lo:[1,0,0] neg_hi:[1,0,0]
	ds_read_b128 v[246:249], v251 offset:12496
	s_waitcnt lgkmcnt(13)
	v_fma_f32 v75, -v3, v74, v75
	ds_read_b128 v[0:3], v251 offset:12512
	s_waitcnt lgkmcnt(13)
	v_pk_fma_f32 v[76:77], v[4:5], v[74:75], v[76:77] op_sel:[0,0,0] op_sel_hi:[1,0,1] neg_lo:[1,0,0] neg_hi:[1,0,0]
	v_pk_fma_f32 v[78:79], v[6:7], v[74:75], v[78:79] op_sel:[0,0,0] op_sel_hi:[1,0,1] neg_lo:[1,0,0] neg_hi:[1,0,0]
	ds_read_b128 v[4:7], v251 offset:12528
	s_waitcnt lgkmcnt(13)
	v_pk_fma_f32 v[80:81], v[8:9], v[74:75], v[80:81] op_sel:[0,0,0] op_sel_hi:[1,0,1] neg_lo:[1,0,0] neg_hi:[1,0,0]
	v_pk_fma_f32 v[82:83], v[10:11], v[74:75], v[82:83] op_sel:[0,0,0] op_sel_hi:[1,0,1] neg_lo:[1,0,0] neg_hi:[1,0,0]
	ds_read_b128 v[8:11], v251 offset:12720
	s_waitcnt lgkmcnt(13)
	v_pk_fma_f32 v[84:85], v[12:13], v[74:75], v[84:85] op_sel:[0,0,0] op_sel_hi:[1,0,1] neg_lo:[1,0,0] neg_hi:[1,0,0]
	v_pk_fma_f32 v[86:87], v[14:15], v[74:75], v[86:87] op_sel:[0,0,0] op_sel_hi:[1,0,1] neg_lo:[1,0,0] neg_hi:[1,0,0]
	ds_read_b128 v[12:15], v251 offset:12736
	s_waitcnt lgkmcnt(13)
	v_pk_fma_f32 v[88:89], v[16:17], v[74:75], v[88:89] op_sel:[0,0,0] op_sel_hi:[1,0,1] neg_lo:[1,0,0] neg_hi:[1,0,0]
	v_pk_fma_f32 v[90:91], v[18:19], v[74:75], v[90:91] op_sel:[0,0,0] op_sel_hi:[1,0,1] neg_lo:[1,0,0] neg_hi:[1,0,0]
	ds_read_b128 v[16:19], v251 offset:12752
	s_waitcnt lgkmcnt(13)
	v_pk_fma_f32 v[92:93], v[20:21], v[74:75], v[92:93] op_sel:[0,0,0] op_sel_hi:[1,0,1] neg_lo:[1,0,0] neg_hi:[1,0,0]
	v_pk_fma_f32 v[94:95], v[22:23], v[74:75], v[94:95] op_sel:[0,0,0] op_sel_hi:[1,0,1] neg_lo:[1,0,0] neg_hi:[1,0,0]
	ds_read_b128 v[20:23], v251 offset:12768
	s_waitcnt lgkmcnt(13)
	v_pk_fma_f32 v[76:77], v[24:25], v[74:75], v[76:77] op_sel:[0,1,0] op_sel_hi:[1,1,1] neg_lo:[1,0,0] neg_hi:[1,0,0]
	v_pk_fma_f32 v[78:79], v[26:27], v[74:75], v[78:79] op_sel:[0,1,0] op_sel_hi:[1,1,1] neg_lo:[1,0,0] neg_hi:[1,0,0]
	ds_read_b128 v[24:27], v251 offset:12784
	s_waitcnt lgkmcnt(13)
	v_pk_fma_f32 v[80:81], v[28:29], v[74:75], v[80:81] op_sel:[0,1,0] op_sel_hi:[1,1,1] neg_lo:[1,0,0] neg_hi:[1,0,0]
	v_pk_fma_f32 v[82:83], v[30:31], v[74:75], v[82:83] op_sel:[0,1,0] op_sel_hi:[1,1,1] neg_lo:[1,0,0] neg_hi:[1,0,0]
	ds_read_b128 v[28:31], v251 offset:12976
	s_waitcnt lgkmcnt(13)
	v_pk_fma_f32 v[84:85], v[126:127], v[74:75], v[84:85] op_sel:[0,1,0] op_sel_hi:[1,1,1] neg_lo:[1,0,0] neg_hi:[1,0,0]
	v_pk_fma_f32 v[86:87], v[128:129], v[74:75], v[86:87] op_sel:[0,1,0] op_sel_hi:[1,1,1] neg_lo:[1,0,0] neg_hi:[1,0,0]
	ds_read_b128 v[126:129], v251 offset:12992
	s_waitcnt lgkmcnt(13)
	v_pk_fma_f32 v[88:89], v[230:231], v[74:75], v[88:89] op_sel:[0,1,0] op_sel_hi:[1,1,1] neg_lo:[1,0,0] neg_hi:[1,0,0]
	v_pk_fma_f32 v[90:91], v[232:233], v[74:75], v[90:91] op_sel:[0,1,0] op_sel_hi:[1,1,1] neg_lo:[1,0,0] neg_hi:[1,0,0]
	ds_read_b128 v[230:233], v251 offset:13008
	s_waitcnt lgkmcnt(13)
	v_pk_fma_f32 v[92:93], v[234:235], v[74:75], v[92:93] op_sel:[0,1,0] op_sel_hi:[1,1,1] neg_lo:[1,0,0] neg_hi:[1,0,0]
	v_pk_fma_f32 v[94:95], v[236:237], v[74:75], v[94:95] op_sel:[0,1,0] op_sel_hi:[1,1,1] neg_lo:[1,0,0] neg_hi:[1,0,0]
	ds_read_b128 v[234:237], v251 offset:13024
	s_waitcnt lgkmcnt(13)
	v_fma_f32 v77, -v239, v76, v77
	v_pk_fma_f32 v[78:79], v[240:241], v[76:77], v[78:79] op_sel:[0,0,0] op_sel_hi:[1,0,1] neg_lo:[1,0,0] neg_hi:[1,0,0]
	ds_read_b128 v[238:241], v251 offset:13040
	s_waitcnt lgkmcnt(13)
	v_pk_fma_f32 v[80:81], v[242:243], v[76:77], v[80:81] op_sel:[0,0,0] op_sel_hi:[1,0,1] neg_lo:[1,0,0] neg_hi:[1,0,0]
	v_pk_fma_f32 v[82:83], v[244:245], v[76:77], v[82:83] op_sel:[0,0,0] op_sel_hi:[1,0,1] neg_lo:[1,0,0] neg_hi:[1,0,0]
	ds_read_b128 v[242:245], v251 offset:13248
	s_waitcnt lgkmcnt(13)
; #define PG8_LAS __attribute__((address_space(3)))
; __device__ __forceinline__ void solve64(float (&x)[64], const PG8_LAS float* sLt) {
;     f32x4 cur[16];
; #pragma unroll
;     for (int i4 = 0; i4 < 16; ++i4) cur[i4] = *(const PG8_LAS f32x4*)(sLt + 4 * i4);
;     asm volatile("" ::: "memory");
; #pragma unroll
;     for (int j = 0; j < 63; ++j) {
;         const float xj = x[j];
; #pragma unroll
;         for (int i4 = (j + 1) / 4; i4 < 16; ++i4) {
;             if (4 * i4 + 0 > j) x[4 * i4 + 0] -= cur[i4][0] * xj;
;             if (4 * i4 + 1 > j) x[4 * i4 + 1] -= cur[i4][1] * xj;
;             if (4 * i4 + 2 > j) x[4 * i4 + 2] -= cur[i4][2] * xj;
;             if (4 * i4 + 3 > j) x[4 * i4 + 3] -= cur[i4][3] * xj;
;             if (j + 1 < 63 && i4 >= (j + 2) / 4) cur[i4] = *(const PG8_LAS f32x4*)(sLt + (j + 1) * 64 + 4 * i4); }
;         asm volatile("" ::: "memory");
;     }
; }
	v_pk_fma_f32 v[84:85], v[246:247], v[76:77], v[84:85] op_sel:[0,0,0] op_sel_hi:[1,0,1] neg_lo:[1,0,0] neg_hi:[1,0,0]
	v_pk_fma_f32 v[86:87], v[248:249], v[76:77], v[86:87] op_sel:[0,0,0] op_sel_hi:[1,0,1] neg_lo:[1,0,0] neg_hi:[1,0,0]
	ds_read_b128 v[246:249], v251 offset:13264
	s_waitcnt lgkmcnt(13)
	v_pk_fma_f32 v[88:89], v[0:1], v[76:77], v[88:89] op_sel:[0,0,0] op_sel_hi:[1,0,1] neg_lo:[1,0,0] neg_hi:[1,0,0]
	v_pk_fma_f32 v[90:91], v[2:3], v[76:77], v[90:91] op_sel:[0,0,0] op_sel_hi:[1,0,1] neg_lo:[1,0,0] neg_hi:[1,0,0]
	ds_read_b128 v[0:3], v251 offset:13280
	s_waitcnt lgkmcnt(13)
	v_pk_fma_f32 v[92:93], v[4:5], v[76:77], v[92:93] op_sel:[0,0,0] op_sel_hi:[1,0,1] neg_lo:[1,0,0] neg_hi:[1,0,0]
	v_pk_fma_f32 v[94:95], v[6:7], v[76:77], v[94:95] op_sel:[0,0,0] op_sel_hi:[1,0,1] neg_lo:[1,0,0] neg_hi:[1,0,0]
	ds_read_b128 v[4:7], v251 offset:13296
	s_waitcnt lgkmcnt(13)
	v_pk_fma_f32 v[78:79], v[10:11], v[76:77], v[78:79] op_sel:[0,1,0] op_sel_hi:[1,1,1] neg_lo:[1,0,0] neg_hi:[1,0,0]
	ds_read_b128 v[8:11], v251 offset:13504
	s_waitcnt lgkmcnt(13)
	v_pk_fma_f32 v[80:81], v[12:13], v[76:77], v[80:81] op_sel:[0,1,0] op_sel_hi:[1,1,1] neg_lo:[1,0,0] neg_hi:[1,0,0]
	v_pk_fma_f32 v[82:83], v[14:15], v[76:77], v[82:83] op_sel:[0,1,0] op_sel_hi:[1,1,1] neg_lo:[1,0,0] neg_hi:[1,0,0]
	ds_read_b128 v[12:15], v251 offset:13520
	s_waitcnt lgkmcnt(13)
	v_pk_fma_f32 v[84:85], v[16:17], v[76:77], v[84:85] op_sel:[0,1,0] op_sel_hi:[1,1,1] neg_lo:[1,0,0] neg_hi:[1,0,0]
	v_pk_fma_f32 v[86:87], v[18:19], v[76:77], v[86:87] op_sel:[0,1,0] op_sel_hi:[1,1,1] neg_lo:[1,0,0] neg_hi:[1,0,0]
	ds_read_b128 v[16:19], v251 offset:13536
	s_waitcnt lgkmcnt(13)
	v_pk_fma_f32 v[88:89], v[20:21], v[76:77], v[88:89] op_sel:[0,1,0] op_sel_hi:[1,1,1] neg_lo:[1,0,0] neg_hi:[1,0,0]
	v_pk_fma_f32 v[90:91], v[22:23], v[76:77], v[90:91] op_sel:[0,1,0] op_sel_hi:[1,1,1] neg_lo:[1,0,0] neg_hi:[1,0,0]
	ds_read_b128 v[20:23], v251 offset:13552
	s_waitcnt lgkmcnt(13)
	v_pk_fma_f32 v[92:93], v[24:25], v[76:77], v[92:93] op_sel:[0,1,0] op_sel_hi:[1,1,1] neg_lo:[1,0,0] neg_hi:[1,0,0]
	v_pk_fma_f32 v[94:95], v[26:27], v[76:77], v[94:95] op_sel:[0,1,0] op_sel_hi:[1,1,1] neg_lo:[1,0,0] neg_hi:[1,0,0]
	ds_read_b128 v[24:27], v251 offset:13760
	s_waitcnt lgkmcnt(13)
	v_fma_f32 v79, -v31, v78, v79
	ds_read_b128 v[28:31], v251 offset:13776
	s_waitcnt lgkmcnt(13)
	v_pk_fma_f32 v[80:81], v[126:127], v[78:79], v[80:81] op_sel:[0,0,0] op_sel_hi:[1,0,1] neg_lo:[1,0,0] neg_hi:[1,0,0]
	v_pk_fma_f32 v[82:83], v[128:129], v[78:79], v[82:83] op_sel:[0,0,0] op_sel_hi:[1,0,1] neg_lo:[1,0,0] neg_hi:[1,0,0]
	ds_read_b128 v[126:129], v251 offset:13792
	s_waitcnt lgkmcnt(13)
	v_pk_fma_f32 v[84:85], v[230:231], v[78:79], v[84:85] op_sel:[0,0,0] op_sel_hi:[1,0,1] neg_lo:[1,0,0] neg_hi:[1,0,0]
	v_pk_fma_f32 v[86:87], v[232:233], v[78:79], v[86:87] op_sel:[0,0,0] op_sel_hi:[1,0,1] neg_lo:[1,0,0] neg_hi:[1,0,0]
	ds_read_b128 v[230:233], v251 offset:13808
	s_waitcnt lgkmcnt(13)
	v_pk_fma_f32 v[88:89], v[234:235], v[78:79], v[88:89] op_sel:[0,0,0] op_sel_hi:[1,0,1] neg_lo:[1,0,0] neg_hi:[1,0,0]
	v_pk_fma_f32 v[90:91], v[236:237], v[78:79], v[90:91] op_sel:[0,0,0] op_sel_hi:[1,0,1] neg_lo:[1,0,0] neg_hi:[1,0,0]
	ds_read_b128 v[234:237], v251 offset:14016
	s_waitcnt lgkmcnt(13)
	v_pk_fma_f32 v[92:93], v[238:239], v[78:79], v[92:93] op_sel:[0,0,0] op_sel_hi:[1,0,1] neg_lo:[1,0,0] neg_hi:[1,0,0]
	v_pk_fma_f32 v[94:95], v[240:241], v[78:79], v[94:95] op_sel:[0,0,0] op_sel_hi:[1,0,1] neg_lo:[1,0,0] neg_hi:[1,0,0]
	ds_read_b128 v[238:241], v251 offset:14032
	s_waitcnt lgkmcnt(13)
	v_pk_fma_f32 v[80:81], v[242:243], v[78:79], v[80:81] op_sel:[0,1,0] op_sel_hi:[1,1,1] neg_lo:[1,0,0] neg_hi:[1,0,0]
	v_pk_fma_f32 v[82:83], v[244:245], v[78:79], v[82:83] op_sel:[0,1,0] op_sel_hi:[1,1,1] neg_lo:[1,0,0] neg_hi:[1,0,0]
	ds_read_b128 v[242:245], v251 offset:14048
	s_waitcnt lgkmcnt(13)
	v_pk_fma_f32 v[84:85], v[246:247], v[78:79], v[84:85] op_sel:[0,1,0] op_sel_hi:[1,1,1] neg_lo:[1,0,0] neg_hi:[1,0,0]
	v_pk_fma_f32 v[86:87], v[248:249], v[78:79], v[86:87] op_sel:[0,1,0] op_sel_hi:[1,1,1] neg_lo:[1,0,0] neg_hi:[1,0,0]
	ds_read_b128 v[246:249], v251 offset:14064
	s_waitcnt lgkmcnt(13)
	v_pk_fma_f32 v[88:89], v[0:1], v[78:79], v[88:89] op_sel:[0,1,0] op_sel_hi:[1,1,1] neg_lo:[1,0,0] neg_hi:[1,0,0]
	v_pk_fma_f32 v[90:91], v[2:3], v[78:79], v[90:91] op_sel:[0,1,0] op_sel_hi:[1,1,1] neg_lo:[1,0,0] neg_hi:[1,0,0]
	ds_read_b128 v[0:3], v251 offset:14288
	s_waitcnt lgkmcnt(13)
	v_pk_fma_f32 v[92:93], v[4:5], v[78:79], v[92:93] op_sel:[0,1,0] op_sel_hi:[1,1,1] neg_lo:[1,0,0] neg_hi:[1,0,0]
	v_pk_fma_f32 v[94:95], v[6:7], v[78:79], v[94:95] op_sel:[0,1,0] op_sel_hi:[1,1,1] neg_lo:[1,0,0] neg_hi:[1,0,0]
	ds_read_b128 v[4:7], v251 offset:14304
	s_waitcnt lgkmcnt(13)
	v_fma_f32 v81, -v9, v80, v81
	v_pk_fma_f32 v[82:83], v[10:11], v[80:81], v[82:83] op_sel:[0,0,0] op_sel_hi:[1,0,1] neg_lo:[1,0,0] neg_hi:[1,0,0]
	ds_read_b128 v[8:11], v251 offset:14320
	s_waitcnt lgkmcnt(13)
	v_pk_fma_f32 v[84:85], v[12:13], v[80:81], v[84:85] op_sel:[0,0,0] op_sel_hi:[1,0,1] neg_lo:[1,0,0] neg_hi:[1,0,0]
	v_pk_fma_f32 v[86:87], v[14:15], v[80:81], v[86:87] op_sel:[0,0,0] op_sel_hi:[1,0,1] neg_lo:[1,0,0] neg_hi:[1,0,0]
	ds_read_b128 v[12:15], v251 offset:14544
	s_waitcnt lgkmcnt(13)
	v_pk_fma_f32 v[88:89], v[16:17], v[80:81], v[88:89] op_sel:[0,0,0] op_sel_hi:[1,0,1] neg_lo:[1,0,0] neg_hi:[1,0,0]
	v_pk_fma_f32 v[90:91], v[18:19], v[80:81], v[90:91] op_sel:[0,0,0] op_sel_hi:[1,0,1] neg_lo:[1,0,0] neg_hi:[1,0,0]
	ds_read_b128 v[16:19], v251 offset:14560
	s_waitcnt lgkmcnt(13)
; #define PG8_LAS __attribute__((address_space(3)))
; __device__ __forceinline__ void solve64(float (&x)[64], const PG8_LAS float* sLt) {
;     f32x4 cur[16];
; #pragma unroll
;     for (int i4 = 0; i4 < 16; ++i4) cur[i4] = *(const PG8_LAS f32x4*)(sLt + 4 * i4);
;     asm volatile("" ::: "memory");
; #pragma unroll
;     for (int j = 0; j < 63; ++j) {
;         const float xj = x[j];
; #pragma unroll
;         for (int i4 = (j + 1) / 4; i4 < 16; ++i4) {
;             if (4 * i4 + 0 > j) x[4 * i4 + 0] -= cur[i4][0] * xj;
;             if (4 * i4 + 1 > j) x[4 * i4 + 1] -= cur[i4][1] * xj;
;             if (4 * i4 + 2 > j) x[4 * i4 + 2] -= cur[i4][2] * xj;
;             if (4 * i4 + 3 > j) x[4 * i4 + 3] -= cur[i4][3] * xj;
;             if (j + 1 < 63 && i4 >= (j + 2) / 4) cur[i4] = *(const PG8_LAS f32x4*)(sLt + (j + 1) * 64 + 4 * i4); }
;         asm volatile("" ::: "memory");
;     }
; }
	v_pk_fma_f32 v[92:93], v[20:21], v[80:81], v[92:93] op_sel:[0,0,0] op_sel_hi:[1,0,1] neg_lo:[1,0,0] neg_hi:[1,0,0]
	v_pk_fma_f32 v[94:95], v[22:23], v[80:81], v[94:95] op_sel:[0,0,0] op_sel_hi:[1,0,1] neg_lo:[1,0,0] neg_hi:[1,0,0]
	ds_read_b128 v[20:23], v251 offset:14576
	s_waitcnt lgkmcnt(13)
	v_pk_fma_f32 v[82:83], v[26:27], v[80:81], v[82:83] op_sel:[0,1,0] op_sel_hi:[1,1,1] neg_lo:[1,0,0] neg_hi:[1,0,0]
	ds_read_b128 v[24:27], v251 offset:14800
	s_waitcnt lgkmcnt(13)
	v_pk_fma_f32 v[84:85], v[28:29], v[80:81], v[84:85] op_sel:[0,1,0] op_sel_hi:[1,1,1] neg_lo:[1,0,0] neg_hi:[1,0,0]
	v_pk_fma_f32 v[86:87], v[30:31], v[80:81], v[86:87] op_sel:[0,1,0] op_sel_hi:[1,1,1] neg_lo:[1,0,0] neg_hi:[1,0,0]
	ds_read_b128 v[28:31], v251 offset:14816
	s_waitcnt lgkmcnt(13)
	v_pk_fma_f32 v[88:89], v[126:127], v[80:81], v[88:89] op_sel:[0,1,0] op_sel_hi:[1,1,1] neg_lo:[1,0,0] neg_hi:[1,0,0]
	v_pk_fma_f32 v[90:91], v[128:129], v[80:81], v[90:91] op_sel:[0,1,0] op_sel_hi:[1,1,1] neg_lo:[1,0,0] neg_hi:[1,0,0]
	ds_read_b128 v[126:129], v251 offset:14832
	s_waitcnt lgkmcnt(13)
	v_pk_fma_f32 v[92:93], v[230:231], v[80:81], v[92:93] op_sel:[0,1,0] op_sel_hi:[1,1,1] neg_lo:[1,0,0] neg_hi:[1,0,0]
	v_pk_fma_f32 v[94:95], v[232:233], v[80:81], v[94:95] op_sel:[0,1,0] op_sel_hi:[1,1,1] neg_lo:[1,0,0] neg_hi:[1,0,0]
	ds_read_b128 v[230:233], v251 offset:15056
	s_waitcnt lgkmcnt(13)
	v_fma_f32 v83, -v237, v82, v83
	ds_read_b128 v[234:237], v251 offset:15072
	s_waitcnt lgkmcnt(13)
	v_pk_fma_f32 v[84:85], v[238:239], v[82:83], v[84:85] op_sel:[0,0,0] op_sel_hi:[1,0,1] neg_lo:[1,0,0] neg_hi:[1,0,0]
	v_pk_fma_f32 v[86:87], v[240:241], v[82:83], v[86:87] op_sel:[0,0,0] op_sel_hi:[1,0,1] neg_lo:[1,0,0] neg_hi:[1,0,0]
	ds_read_b128 v[238:241], v251 offset:15088
	s_waitcnt lgkmcnt(13)
	v_pk_fma_f32 v[88:89], v[242:243], v[82:83], v[88:89] op_sel:[0,0,0] op_sel_hi:[1,0,1] neg_lo:[1,0,0] neg_hi:[1,0,0]
	v_pk_fma_f32 v[90:91], v[244:245], v[82:83], v[90:91] op_sel:[0,0,0] op_sel_hi:[1,0,1] neg_lo:[1,0,0] neg_hi:[1,0,0]
	ds_read_b128 v[242:245], v251 offset:15328
	s_waitcnt lgkmcnt(13)
	v_pk_fma_f32 v[92:93], v[246:247], v[82:83], v[92:93] op_sel:[0,0,0] op_sel_hi:[1,0,1] neg_lo:[1,0,0] neg_hi:[1,0,0]
	v_pk_fma_f32 v[94:95], v[248:249], v[82:83], v[94:95] op_sel:[0,0,0] op_sel_hi:[1,0,1] neg_lo:[1,0,0] neg_hi:[1,0,0]
	ds_read_b128 v[246:249], v251 offset:15344
	s_waitcnt lgkmcnt(13)
	v_pk_fma_f32 v[84:85], v[0:1], v[82:83], v[84:85] op_sel:[0,1,0] op_sel_hi:[1,1,1] neg_lo:[1,0,0] neg_hi:[1,0,0]
	v_pk_fma_f32 v[86:87], v[2:3], v[82:83], v[86:87] op_sel:[0,1,0] op_sel_hi:[1,1,1] neg_lo:[1,0,0] neg_hi:[1,0,0]
	ds_read_b128 v[0:3], v251 offset:15584
	s_waitcnt lgkmcnt(13)
	v_pk_fma_f32 v[88:89], v[4:5], v[82:83], v[88:89] op_sel:[0,1,0] op_sel_hi:[1,1,1] neg_lo:[1,0,0] neg_hi:[1,0,0]
	v_pk_fma_f32 v[90:91], v[6:7], v[82:83], v[90:91] op_sel:[0,1,0] op_sel_hi:[1,1,1] neg_lo:[1,0,0] neg_hi:[1,0,0]
	ds_read_b128 v[4:7], v251 offset:15600
	s_waitcnt lgkmcnt(13)
	v_pk_fma_f32 v[92:93], v[8:9], v[82:83], v[92:93] op_sel:[0,1,0] op_sel_hi:[1,1,1] neg_lo:[1,0,0] neg_hi:[1,0,0]
	v_pk_fma_f32 v[94:95], v[10:11], v[82:83], v[94:95] op_sel:[0,1,0] op_sel_hi:[1,1,1] neg_lo:[1,0,0] neg_hi:[1,0,0]
	ds_read_b128 v[8:11], v251 offset:15840
	s_waitcnt lgkmcnt(13)
	v_fma_f32 v85, -v13, v84, v85
	v_pk_fma_f32 v[86:87], v[14:15], v[84:85], v[86:87] op_sel:[0,0,0] op_sel_hi:[1,0,1] neg_lo:[1,0,0] neg_hi:[1,0,0]
	ds_read_b128 v[12:15], v251 offset:15856
	s_waitcnt lgkmcnt(13)
	v_pk_fma_f32 v[88:89], v[16:17], v[84:85], v[88:89] op_sel:[0,0,0] op_sel_hi:[1,0,1] neg_lo:[1,0,0] neg_hi:[1,0,0]
	v_pk_fma_f32 v[90:91], v[18:19], v[84:85], v[90:91] op_sel:[0,0,0] op_sel_hi:[1,0,1] neg_lo:[1,0,0] neg_hi:[1,0,0]
	ds_read_b128 v[16:19], v251 offset:16096
	s_waitcnt lgkmcnt(13)
	v_pk_fma_f32 v[92:93], v[20:21], v[84:85], v[92:93] op_sel:[0,0,0] op_sel_hi:[1,0,1] neg_lo:[1,0,0] neg_hi:[1,0,0]
	v_pk_fma_f32 v[94:95], v[22:23], v[84:85], v[94:95] op_sel:[0,0,0] op_sel_hi:[1,0,1] neg_lo:[1,0,0] neg_hi:[1,0,0]
	ds_read_b128 v[20:23], v251 offset:16112
	s_waitcnt lgkmcnt(13)
	v_pk_fma_f32 v[86:87], v[26:27], v[84:85], v[86:87] op_sel:[0,1,0] op_sel_hi:[1,1,1] neg_lo:[1,0,0] neg_hi:[1,0,0]
	ds_read_b128 v[24:27], v251 offset:16368
	s_waitcnt lgkmcnt(13)
	v_pk_fma_f32 v[88:89], v[28:29], v[84:85], v[88:89] op_sel:[0,1,0] op_sel_hi:[1,1,1] neg_lo:[1,0,0] neg_hi:[1,0,0]
	v_pk_fma_f32 v[90:91], v[30:31], v[84:85], v[90:91] op_sel:[0,1,0] op_sel_hi:[1,1,1] neg_lo:[1,0,0] neg_hi:[1,0,0]
	ds_read_b128 v[28:31], v251 offset:16624
	s_waitcnt lgkmcnt(13)
	v_pk_fma_f32 v[92:93], v[126:127], v[84:85], v[92:93] op_sel:[0,1,0] op_sel_hi:[1,1,1] neg_lo:[1,0,0] neg_hi:[1,0,0]
	v_pk_fma_f32 v[94:95], v[128:129], v[84:85], v[94:95] op_sel:[0,1,0] op_sel_hi:[1,1,1] neg_lo:[1,0,0] neg_hi:[1,0,0]
	ds_read_b128 v[126:129], v251 offset:16880
	s_waitcnt lgkmcnt(13)
	v_fma_f32 v87, -v233, v86, v87
	ds_read_b128 v[230:233], v251 offset:17136
	s_waitcnt lgkmcnt(13)
	v_pk_fma_f32 v[88:89], v[234:235], v[86:87], v[88:89] op_sel:[0,0,0] op_sel_hi:[1,0,1] neg_lo:[1,0,0] neg_hi:[1,0,0]
	v_pk_fma_f32 v[90:91], v[236:237], v[86:87], v[90:91] op_sel:[0,0,0] op_sel_hi:[1,0,1] neg_lo:[1,0,0] neg_hi:[1,0,0]
	s_waitcnt lgkmcnt(12)
	v_pk_fma_f32 v[92:93], v[238:239], v[86:87], v[92:93] op_sel:[0,0,0] op_sel_hi:[1,0,1] neg_lo:[1,0,0] neg_hi:[1,0,0]
	v_pk_fma_f32 v[94:95], v[240:241], v[86:87], v[94:95] op_sel:[0,0,0] op_sel_hi:[1,0,1] neg_lo:[1,0,0] neg_hi:[1,0,0]
	s_waitcnt lgkmcnt(11)
	v_pk_fma_f32 v[88:89], v[242:243], v[86:87], v[88:89] op_sel:[0,1,0] op_sel_hi:[1,1,1] neg_lo:[1,0,0] neg_hi:[1,0,0]
	v_pk_fma_f32 v[90:91], v[244:245], v[86:87], v[90:91] op_sel:[0,1,0] op_sel_hi:[1,1,1] neg_lo:[1,0,0] neg_hi:[1,0,0]
	s_waitcnt lgkmcnt(10)
; #define PG8_LAS __attribute__((address_space(3)))
; __device__ __forceinline__ void solve64(float (&x)[64], const PG8_LAS float* sLt) {
;     ...
; #pragma unroll
;     for (int j = 0; j < 63; ++j) {
;         const float xj = x[j];
; #pragma unroll
;         for (int i4 = (j + 1) / 4; i4 < 16; ++i4) {
;             if (4 * i4 + 0 > j) x[4 * i4 + 0] -= cur[i4][0] * xj;
;             if (4 * i4 + 1 > j) x[4 * i4 + 1] -= cur[i4][1] * xj;
;             if (4 * i4 + 2 > j) x[4 * i4 + 2] -= cur[i4][2] * xj;
;             if (4 * i4 + 3 > j) x[4 * i4 + 3] -= cur[i4][3] * xj;
;             if (j + 1 < 63 && i4 >= (j + 2) / 4) cur[i4] = *(const PG8_LAS f32x4*)(sLt + (j + 1) * 64 + 4 * i4); }
;         asm volatile("" ::: "memory");
;     }
; }
; __device__ __forceinline__ void phase_prep(const Args& a, PG8_LAS unsigned char* lds) {
;     ...
;             __builtin_amdgcn_s_setprio(3);
;             solve64(x, sL);
;             __builtin_amdgcn_s_setprio(0);
; #pragma unroll
;             for (int cc = 0; cc < 2; ++cc) { const int ct = 2 * lw + cc;
;                 pv[cc][0] = *(const bf16x8*)(vTb + (size_t)(16 * ct + r) * 64 + 8 * q); pv[cc][1] = *(const bf16x8*)(vTb + (size_t)(16 * ct + r) * 64 + 32 + 8 * q);
;                 pk[cc][0] = *(const bf16x8*)(kTb + (size_t)(16 * ct + r) * 64 + 8 * q); pk[cc][1] = *(const bf16x8*)(kTb + (size_t)(16 * ct + r) * 64 + 32 + 8 * q); }
;             const float bj = sB[lane], bej = bj * sE[lane];
	v_pk_fma_f32 v[92:93], v[246:247], v[86:87], v[92:93] op_sel:[0,1,0] op_sel_hi:[1,1,1] neg_lo:[1,0,0] neg_hi:[1,0,0]
	v_pk_fma_f32 v[94:95], v[248:249], v[86:87], v[94:95] op_sel:[0,1,0] op_sel_hi:[1,1,1] neg_lo:[1,0,0] neg_hi:[1,0,0]
	s_waitcnt lgkmcnt(9)
	v_fma_f32 v89, -v1, v88, v89
	v_pk_fma_f32 v[90:91], v[2:3], v[88:89], v[90:91] op_sel:[0,0,0] op_sel_hi:[1,0,1] neg_lo:[1,0,0] neg_hi:[1,0,0]
	s_waitcnt lgkmcnt(8)
	v_pk_fma_f32 v[92:93], v[4:5], v[88:89], v[92:93] op_sel:[0,0,0] op_sel_hi:[1,0,1] neg_lo:[1,0,0] neg_hi:[1,0,0]
	v_pk_fma_f32 v[94:95], v[6:7], v[88:89], v[94:95] op_sel:[0,0,0] op_sel_hi:[1,0,1] neg_lo:[1,0,0] neg_hi:[1,0,0]
	s_waitcnt lgkmcnt(7)
	v_pk_fma_f32 v[90:91], v[10:11], v[88:89], v[90:91] op_sel:[0,1,0] op_sel_hi:[1,1,1] neg_lo:[1,0,0] neg_hi:[1,0,0]
	s_waitcnt lgkmcnt(6)
	v_pk_fma_f32 v[92:93], v[12:13], v[88:89], v[92:93] op_sel:[0,1,0] op_sel_hi:[1,1,1] neg_lo:[1,0,0] neg_hi:[1,0,0]
	v_pk_fma_f32 v[94:95], v[14:15], v[88:89], v[94:95] op_sel:[0,1,0] op_sel_hi:[1,1,1] neg_lo:[1,0,0] neg_hi:[1,0,0]
	s_waitcnt lgkmcnt(5)
	v_fma_f32 v91, -v19, v90, v91
	s_waitcnt lgkmcnt(4)
	v_pk_fma_f32 v[92:93], v[20:21], v[90:91], v[92:93] op_sel:[0,0,0] op_sel_hi:[1,0,1] neg_lo:[1,0,0] neg_hi:[1,0,0]
	v_pk_fma_f32 v[94:95], v[22:23], v[90:91], v[94:95] op_sel:[0,0,0] op_sel_hi:[1,0,1] neg_lo:[1,0,0] neg_hi:[1,0,0]
	s_waitcnt lgkmcnt(3)
	v_pk_fma_f32 v[92:93], v[24:25], v[90:91], v[92:93] op_sel:[0,1,0] op_sel_hi:[1,1,1] neg_lo:[1,0,0] neg_hi:[1,0,0]
	v_pk_fma_f32 v[94:95], v[26:27], v[90:91], v[94:95] op_sel:[0,1,0] op_sel_hi:[1,1,1] neg_lo:[1,0,0] neg_hi:[1,0,0]
	s_waitcnt lgkmcnt(2)
	v_fma_f32 v93, -v29, v92, v93
	v_pk_fma_f32 v[94:95], v[30:31], v[92:93], v[94:95] op_sel:[0,0,0] op_sel_hi:[1,0,1] neg_lo:[1,0,0] neg_hi:[1,0,0]
	s_waitcnt lgkmcnt(1)
	v_pk_fma_f32 v[94:95], v[128:129], v[92:93], v[94:95] op_sel:[0,1,0] op_sel_hi:[1,1,1] neg_lo:[1,0,0] neg_hi:[1,0,0]
	s_waitcnt lgkmcnt(0)
	v_fma_f32 v95, -v233, v94, v95
	v_mov_b32_e32 v107, v94
	v_mov_b32_e32 v0, v95
	v_mov_b32_e32 v95, v93
	v_mov_b32_e32 v94, v92
	v_mov_b32_e32 v93, v0
	v_mov_b32_e32 v92, v91
	v_mov_b32_e32 v91, v90
	v_mov_b32_e32 v90, v89
	v_mov_b32_e32 v89, v88
	v_mov_b32_e32 v88, v87
	v_mov_b32_e32 v87, v86
	v_mov_b32_e32 v86, v85
	v_mov_b32_e32 v85, v84
	v_mov_b32_e32 v84, v83
	v_mov_b32_e32 v83, v82
	v_mov_b32_e32 v82, v81
	v_mov_b32_e32 v81, v80
	v_mov_b32_e32 v80, v79
	v_mov_b32_e32 v79, v78
	v_mov_b32_e32 v78, v77
	v_mov_b32_e32 v77, v76
	v_mov_b32_e32 v76, v75
	v_mov_b32_e32 v75, v74
	v_mov_b32_e32 v74, v73
	v_mov_b32_e32 v73, v72
	v_mov_b32_e32 v72, v71
	v_mov_b32_e32 v71, v70
	v_mov_b32_e32 v70, v69
	v_mov_b32_e32 v69, v68
	v_mov_b32_e32 v68, v67
	v_mov_b32_e32 v67, v66
	v_mov_b32_e32 v66, v65
	v_mov_b32_e32 v65, v64
	v_mov_b32_e32 v64, v63
	v_mov_b32_e32 v63, v62
	v_mov_b32_e32 v62, v61
	v_mov_b32_e32 v61, v60
	v_mov_b32_e32 v60, v59
	v_mov_b32_e32 v59, v58
	v_mov_b32_e32 v58, v57
	v_mov_b32_e32 v57, v56
	v_mov_b32_e32 v56, v55
	v_mov_b32_e32 v55, v54
	v_mov_b32_e32 v54, v53
	v_mov_b32_e32 v53, v52
	v_mov_b32_e32 v52, v51
	v_mov_b32_e32 v51, v50
	v_mov_b32_e32 v50, v49
	v_mov_b32_e32 v49, v48
	v_mov_b32_e32 v48, v47
	v_mov_b32_e32 v47, v46
	v_mov_b32_e32 v46, v45
	v_mov_b32_e32 v45, v44
	v_mov_b32_e32 v44, v43
	v_mov_b32_e32 v43, v42
	v_mov_b32_e32 v42, v41
	v_mov_b32_e32 v41, v40
	v_mov_b32_e32 v40, v39
	v_mov_b32_e32 v39, v38
	v_mov_b32_e32 v38, v37
	v_mov_b32_e32 v37, v36
	v_mov_b32_e32 v36, v35
	v_mov_b32_e32 v35, v34
	v_mov_b32_e32 v34, v33
	s_setprio 0
	v_mov_b32_e32 v115, v97
	v_lshl_add_u64 v[0:1], s[22:23], 0, v[114:115]
	v_lshl_add_u64 v[8:9], s[20:21], 0, v[114:115]
	v_lshl_add_u64 v[16:17], v[0:1], 0, v[96:97]
	v_lshl_add_u64 v[24:25], v[8:9], 0, v[96:97]
	global_load_dwordx4 v[0:3], v[16:17], off
	global_load_dwordx4 v[4:7], v[16:17], off offset:64
	global_load_dwordx4 v[8:11], v[24:25], off
	global_load_dwordx4 v[12:15], v[24:25], off offset:64
	global_load_dwordx4 v[20:23], v[16:17], off offset:2048
	global_load_dwordx4 v[28:31], v[16:17], off offset:2112
	s_nop 0
	global_load_dwordx4 v[16:19], v[24:25], off offset:2048
	s_nop 0
	global_load_dwordx4 v[24:27], v[24:25], off offset:2112
	ds_read2st64_b32 v[32:33], v130 offset0:1 offset1:2
	s_waitcnt lgkmcnt(0)
; #define PG8_LAS __attribute__((address_space(3)))
; __device__ __forceinline__ bf16_t f2bf(float x) { return (bf16_t)(pk2(x, x) & 0xffffu); }
; __device__ __forceinline__ void phase_prep(const Args& a, PG8_LAS unsigned char* lds) {
;     ...
;             const float bj = sB[lane], bej = bj * sE[lane];
; #pragma unroll
;             for (int i = 0; i < 64; ++i) { *(PG8_LAS bf16_t*)(Tu + (i * 72 + lane) * 2) = f2bf(x[i] * bj); *(PG8_LAS bf16_t*)(Tw + (i * 72 + lane) * 2) = f2bf(x[i] * bej); }
	v_mul_f32_e32 v109, v139, v32
	v_mul_f32_e32 v33, v32, v33
	v_cvt_pk_bf16_f32 v109, v109, v109
	ds_write_b16 v205, v109 offset:17408
	v_mul_f32_e32 v109, v139, v33
	v_cvt_pk_bf16_f32 v109, v109, v109
	ds_write_b16 v205, v109 offset:26624
	v_mul_f32_e32 v109, v34, v32
	v_mul_f32_e32 v34, v34, v33
	v_cvt_pk_bf16_f32 v109, v109, v109
	ds_write_b16 v205, v109 offset:17552
	v_cvt_pk_bf16_f32 v34, v34, v34
	ds_write_b16 v205, v34 offset:26768
	v_mul_f32_e32 v34, v35, v32
	v_cvt_pk_bf16_f32 v34, v34, v34
	ds_write_b16 v205, v34 offset:17696
	v_mul_f32_e32 v34, v35, v33
	v_cvt_pk_bf16_f32 v34, v34, v34
	ds_write_b16 v205, v34 offset:26912
	v_mul_f32_e32 v34, v36, v32
	v_cvt_pk_bf16_f32 v34, v34, v34
	ds_write_b16 v205, v34 offset:17840
	v_mul_f32_e32 v34, v36, v33
	v_cvt_pk_bf16_f32 v34, v34, v34
	ds_write_b16 v205, v34 offset:27056
	v_mul_f32_e32 v34, v37, v32
	v_cvt_pk_bf16_f32 v34, v34, v34
	ds_write_b16 v205, v34 offset:17984
	v_mul_f32_e32 v34, v37, v33
	v_cvt_pk_bf16_f32 v34, v34, v34
	ds_write_b16 v205, v34 offset:27200
	v_mul_f32_e32 v34, v38, v32
	v_cvt_pk_bf16_f32 v34, v34, v34
	ds_write_b16 v205, v34 offset:18128
	v_mul_f32_e32 v34, v38, v33
	v_cvt_pk_bf16_f32 v34, v34, v34
	ds_write_b16 v205, v34 offset:27344
	v_mul_f32_e32 v34, v39, v32
	v_cvt_pk_bf16_f32 v34, v34, v34
	ds_write_b16 v205, v34 offset:18272
	v_mul_f32_e32 v34, v39, v33
	v_cvt_pk_bf16_f32 v34, v34, v34
	ds_write_b16 v205, v34 offset:27488
	v_mul_f32_e32 v34, v40, v32
	v_cvt_pk_bf16_f32 v34, v34, v34
	ds_write_b16 v205, v34 offset:18416
	v_mul_f32_e32 v34, v40, v33
	v_cvt_pk_bf16_f32 v34, v34, v34
	ds_write_b16 v205, v34 offset:27632
	v_mul_f32_e32 v34, v41, v32
	v_cvt_pk_bf16_f32 v34, v34, v34
	ds_write_b16 v205, v34 offset:18560
	v_mul_f32_e32 v34, v41, v33
	v_cvt_pk_bf16_f32 v34, v34, v34
	ds_write_b16 v205, v34 offset:27776
	v_mul_f32_e32 v34, v42, v32
	v_cvt_pk_bf16_f32 v34, v34, v34
	ds_write_b16 v205, v34 offset:18704
	v_mul_f32_e32 v34, v42, v33
	v_cvt_pk_bf16_f32 v34, v34, v34
	ds_write_b16 v205, v34 offset:27920
	v_mul_f32_e32 v34, v43, v32
	v_cvt_pk_bf16_f32 v34, v34, v34
	ds_write_b16 v205, v34 offset:18848
	v_mul_f32_e32 v34, v43, v33
	v_cvt_pk_bf16_f32 v34, v34, v34
	ds_write_b16 v205, v34 offset:28064
	v_mul_f32_e32 v34, v44, v32
	v_cvt_pk_bf16_f32 v34, v34, v34
	ds_write_b16 v205, v34 offset:18992
	v_mul_f32_e32 v34, v44, v33
	v_cvt_pk_bf16_f32 v34, v34, v34
	ds_write_b16 v205, v34 offset:28208
	v_mul_f32_e32 v34, v45, v32
	v_cvt_pk_bf16_f32 v34, v34, v34
	ds_write_b16 v205, v34 offset:19136
	v_mul_f32_e32 v34, v45, v33
	v_cvt_pk_bf16_f32 v34, v34, v34
	ds_write_b16 v205, v34 offset:28352
	v_mul_f32_e32 v34, v46, v32
	v_cvt_pk_bf16_f32 v34, v34, v34
	ds_write_b16 v205, v34 offset:19280
	v_mul_f32_e32 v34, v46, v33
	v_cvt_pk_bf16_f32 v34, v34, v34
	ds_write_b16 v205, v34 offset:28496
	v_mul_f32_e32 v34, v47, v32
	v_cvt_pk_bf16_f32 v34, v34, v34
	ds_write_b16 v205, v34 offset:19424
	v_mul_f32_e32 v34, v47, v33
	v_cvt_pk_bf16_f32 v34, v34, v34
	ds_write_b16 v205, v34 offset:28640
	v_mul_f32_e32 v34, v48, v32
	v_cvt_pk_bf16_f32 v34, v34, v34
	ds_write_b16 v205, v34 offset:19568
	v_mul_f32_e32 v34, v48, v33
	v_cvt_pk_bf16_f32 v34, v34, v34
	ds_write_b16 v205, v34 offset:28784
	v_mul_f32_e32 v34, v49, v32
	v_cvt_pk_bf16_f32 v34, v34, v34
	ds_write_b16 v205, v34 offset:19712
	v_mul_f32_e32 v34, v49, v33
	v_cvt_pk_bf16_f32 v34, v34, v34
	ds_write_b16 v205, v34 offset:28928
	v_mul_f32_e32 v34, v50, v32
	v_cvt_pk_bf16_f32 v34, v34, v34
	ds_write_b16 v205, v34 offset:19856
	v_mul_f32_e32 v34, v50, v33
	v_cvt_pk_bf16_f32 v34, v34, v34
	ds_write_b16 v205, v34 offset:29072
	v_mul_f32_e32 v34, v51, v32
	v_cvt_pk_bf16_f32 v34, v34, v34
	ds_write_b16 v205, v34 offset:20000
	v_mul_f32_e32 v34, v51, v33
	v_cvt_pk_bf16_f32 v34, v34, v34
	ds_write_b16 v205, v34 offset:29216
	v_mul_f32_e32 v34, v52, v32
	v_cvt_pk_bf16_f32 v34, v34, v34
	ds_write_b16 v205, v34 offset:20144
	v_mul_f32_e32 v34, v52, v33
	v_cvt_pk_bf16_f32 v34, v34, v34
	ds_write_b16 v205, v34 offset:29360
	v_mul_f32_e32 v34, v53, v32
	v_cvt_pk_bf16_f32 v34, v34, v34
	ds_write_b16 v205, v34 offset:20288
	v_mul_f32_e32 v34, v53, v33
	v_cvt_pk_bf16_f32 v34, v34, v34
	ds_write_b16 v205, v34 offset:29504
	v_mul_f32_e32 v34, v54, v32
	v_cvt_pk_bf16_f32 v34, v34, v34
	ds_write_b16 v205, v34 offset:20432
	v_mul_f32_e32 v34, v54, v33
	v_cvt_pk_bf16_f32 v34, v34, v34
	ds_write_b16 v205, v34 offset:29648
	v_mul_f32_e32 v34, v55, v32
	v_cvt_pk_bf16_f32 v34, v34, v34
	ds_write_b16 v205, v34 offset:20576
	v_mul_f32_e32 v34, v55, v33
	v_cvt_pk_bf16_f32 v34, v34, v34
	ds_write_b16 v205, v34 offset:29792
	v_mul_f32_e32 v34, v56, v32
	v_cvt_pk_bf16_f32 v34, v34, v34
	ds_write_b16 v205, v34 offset:20720
	v_mul_f32_e32 v34, v56, v33
	v_cvt_pk_bf16_f32 v34, v34, v34
	ds_write_b16 v205, v34 offset:29936
	v_mul_f32_e32 v34, v57, v32
	v_cvt_pk_bf16_f32 v34, v34, v34
	ds_write_b16 v205, v34 offset:20864
	v_mul_f32_e32 v34, v57, v33
	v_cvt_pk_bf16_f32 v34, v34, v34
	ds_write_b16 v205, v34 offset:30080
	v_mul_f32_e32 v34, v58, v32
	v_cvt_pk_bf16_f32 v34, v34, v34
	ds_write_b16 v205, v34 offset:21008
	v_mul_f32_e32 v34, v58, v33
	v_cvt_pk_bf16_f32 v34, v34, v34
	ds_write_b16 v205, v34 offset:30224
	v_mul_f32_e32 v34, v59, v32
	v_cvt_pk_bf16_f32 v34, v34, v34
	ds_write_b16 v205, v34 offset:21152
	v_mul_f32_e32 v34, v59, v33
	v_cvt_pk_bf16_f32 v34, v34, v34
	ds_write_b16 v205, v34 offset:30368
	v_mul_f32_e32 v34, v60, v32
	v_cvt_pk_bf16_f32 v34, v34, v34
	ds_write_b16 v205, v34 offset:21296
	v_mul_f32_e32 v34, v60, v33
	v_cvt_pk_bf16_f32 v34, v34, v34
	ds_write_b16 v205, v34 offset:30512
	v_mul_f32_e32 v34, v61, v32
	v_cvt_pk_bf16_f32 v34, v34, v34
; #define PG8_LAS __attribute__((address_space(3)))
; __device__ __forceinline__ bf16_t f2bf(float x) { return (bf16_t)(pk2(x, x) & 0xffffu); }
; __device__ __forceinline__ void phase_prep(const Args& a, PG8_LAS unsigned char* lds) {
;     ...
;             const float bj = sB[lane], bej = bj * sE[lane];
; #pragma unroll
;             for (int i = 0; i < 64; ++i) { *(PG8_LAS bf16_t*)(Tu + (i * 72 + lane) * 2) = f2bf(x[i] * bj); *(PG8_LAS bf16_t*)(Tw + (i * 72 + lane) * 2) = f2bf(x[i] * bej); }
	ds_write_b16 v205, v34 offset:21440
	v_mul_f32_e32 v34, v61, v33
	v_cvt_pk_bf16_f32 v34, v34, v34
	ds_write_b16 v205, v34 offset:30656
	v_mul_f32_e32 v34, v62, v32
	v_cvt_pk_bf16_f32 v34, v34, v34
	ds_write_b16 v205, v34 offset:21584
	v_mul_f32_e32 v34, v62, v33
	v_cvt_pk_bf16_f32 v34, v34, v34
	ds_write_b16 v205, v34 offset:30800
	v_mul_f32_e32 v34, v63, v32
	v_cvt_pk_bf16_f32 v34, v34, v34
	ds_write_b16 v205, v34 offset:21728
	v_mul_f32_e32 v34, v63, v33
	v_cvt_pk_bf16_f32 v34, v34, v34
	ds_write_b16 v205, v34 offset:30944
	v_mul_f32_e32 v34, v64, v32
	v_cvt_pk_bf16_f32 v34, v34, v34
	ds_write_b16 v205, v34 offset:21872
	v_mul_f32_e32 v34, v64, v33
	v_cvt_pk_bf16_f32 v34, v34, v34
	ds_write_b16 v205, v34 offset:31088
	v_mul_f32_e32 v34, v65, v32
	v_cvt_pk_bf16_f32 v34, v34, v34
	ds_write_b16 v205, v34 offset:22016
	v_mul_f32_e32 v34, v65, v33
	v_cvt_pk_bf16_f32 v34, v34, v34
	ds_write_b16 v205, v34 offset:31232
	v_mul_f32_e32 v34, v66, v32
	v_cvt_pk_bf16_f32 v34, v34, v34
	ds_write_b16 v205, v34 offset:22160
	v_mul_f32_e32 v34, v66, v33
	v_cvt_pk_bf16_f32 v34, v34, v34
	ds_write_b16 v205, v34 offset:31376
	v_mul_f32_e32 v34, v67, v32
	v_cvt_pk_bf16_f32 v34, v34, v34
	ds_write_b16 v205, v34 offset:22304
	v_mul_f32_e32 v34, v67, v33
	v_cvt_pk_bf16_f32 v34, v34, v34
	ds_write_b16 v205, v34 offset:31520
	v_mul_f32_e32 v34, v68, v32
	v_cvt_pk_bf16_f32 v34, v34, v34
	ds_write_b16 v205, v34 offset:22448
	v_mul_f32_e32 v34, v68, v33
	v_cvt_pk_bf16_f32 v34, v34, v34
	ds_write_b16 v205, v34 offset:31664
	v_mul_f32_e32 v34, v69, v32
	v_cvt_pk_bf16_f32 v34, v34, v34
	ds_write_b16 v205, v34 offset:22592
	v_mul_f32_e32 v34, v69, v33
	v_cvt_pk_bf16_f32 v34, v34, v34
	ds_write_b16 v205, v34 offset:31808
	v_mul_f32_e32 v34, v70, v32
	v_cvt_pk_bf16_f32 v34, v34, v34
	ds_write_b16 v205, v34 offset:22736
	v_mul_f32_e32 v34, v70, v33
	v_cvt_pk_bf16_f32 v34, v34, v34
	ds_write_b16 v205, v34 offset:31952
	v_mul_f32_e32 v34, v71, v32
	v_cvt_pk_bf16_f32 v34, v34, v34
	ds_write_b16 v205, v34 offset:22880
	v_mul_f32_e32 v34, v71, v33
	v_cvt_pk_bf16_f32 v34, v34, v34
	ds_write_b16 v205, v34 offset:32096
	v_mul_f32_e32 v34, v72, v32
	v_cvt_pk_bf16_f32 v34, v34, v34
	ds_write_b16 v205, v34 offset:23024
	v_mul_f32_e32 v34, v72, v33
	v_cvt_pk_bf16_f32 v34, v34, v34
	ds_write_b16 v205, v34 offset:32240
	v_mul_f32_e32 v34, v73, v32
	v_cvt_pk_bf16_f32 v34, v34, v34
	ds_write_b16 v205, v34 offset:23168
	v_mul_f32_e32 v34, v73, v33
	v_cvt_pk_bf16_f32 v34, v34, v34
	ds_write_b16 v205, v34 offset:32384
	v_mul_f32_e32 v34, v74, v32
	v_cvt_pk_bf16_f32 v34, v34, v34
	ds_write_b16 v205, v34 offset:23312
	v_mul_f32_e32 v34, v74, v33
	v_cvt_pk_bf16_f32 v34, v34, v34
	ds_write_b16 v205, v34 offset:32528
	v_mul_f32_e32 v34, v75, v32
	v_cvt_pk_bf16_f32 v34, v34, v34
	ds_write_b16 v205, v34 offset:23456
	v_mul_f32_e32 v34, v75, v33
	v_cvt_pk_bf16_f32 v34, v34, v34
	ds_write_b16 v205, v34 offset:32672
	v_mul_f32_e32 v34, v76, v32
	v_cvt_pk_bf16_f32 v34, v34, v34
	ds_write_b16 v205, v34 offset:23600
	v_mul_f32_e32 v34, v76, v33
	v_cvt_pk_bf16_f32 v34, v34, v34
	ds_write_b16 v205, v34 offset:32816
	v_mul_f32_e32 v34, v77, v32
	v_cvt_pk_bf16_f32 v34, v34, v34
	ds_write_b16 v205, v34 offset:23744
	v_mul_f32_e32 v34, v77, v33
	v_cvt_pk_bf16_f32 v34, v34, v34
	ds_write_b16 v205, v34 offset:32960
	v_mul_f32_e32 v34, v78, v32
	v_cvt_pk_bf16_f32 v34, v34, v34
	ds_write_b16 v205, v34 offset:23888
	v_mul_f32_e32 v34, v78, v33
	v_cvt_pk_bf16_f32 v34, v34, v34
	ds_write_b16 v205, v34 offset:33104
	v_mul_f32_e32 v34, v79, v32
; #define PG8_LAS __attribute__((address_space(3)))
; __device__ __forceinline__ bf16_t f2bf(float x) { return (bf16_t)(pk2(x, x) & 0xffffu); }
; __device__ __forceinline__ void phase_prep(const Args& a, PG8_LAS unsigned char* lds) {
;     ...
;             const float bj = sB[lane], bej = bj * sE[lane];
; #pragma unroll
;             for (int i = 0; i < 64; ++i) { *(PG8_LAS bf16_t*)(Tu + (i * 72 + lane) * 2) = f2bf(x[i] * bj); *(PG8_LAS bf16_t*)(Tw + (i * 72 + lane) * 2) = f2bf(x[i] * bej); }
	v_cvt_pk_bf16_f32 v34, v34, v34
	ds_write_b16 v205, v34 offset:24032
	v_mul_f32_e32 v34, v79, v33
	v_cvt_pk_bf16_f32 v34, v34, v34
	ds_write_b16 v205, v34 offset:33248
	v_mul_f32_e32 v34, v80, v32
	v_cvt_pk_bf16_f32 v34, v34, v34
	ds_write_b16 v205, v34 offset:24176
	v_mul_f32_e32 v34, v80, v33
	v_cvt_pk_bf16_f32 v34, v34, v34
	ds_write_b16 v205, v34 offset:33392
	v_mul_f32_e32 v34, v81, v32
	v_cvt_pk_bf16_f32 v34, v34, v34
	ds_write_b16 v205, v34 offset:24320
	v_mul_f32_e32 v34, v81, v33
	v_cvt_pk_bf16_f32 v34, v34, v34
	ds_write_b16 v205, v34 offset:33536
	v_mul_f32_e32 v34, v82, v32
	v_cvt_pk_bf16_f32 v34, v34, v34
	ds_write_b16 v205, v34 offset:24464
	v_mul_f32_e32 v34, v82, v33
	v_cvt_pk_bf16_f32 v34, v34, v34
	ds_write_b16 v205, v34 offset:33680
	v_mul_f32_e32 v34, v83, v32
	v_cvt_pk_bf16_f32 v34, v34, v34
	ds_write_b16 v205, v34 offset:24608
	v_mul_f32_e32 v34, v83, v33
	v_cvt_pk_bf16_f32 v34, v34, v34
	ds_write_b16 v205, v34 offset:33824
	v_mul_f32_e32 v34, v84, v32
	v_cvt_pk_bf16_f32 v34, v34, v34
	ds_write_b16 v205, v34 offset:24752
	v_mul_f32_e32 v34, v84, v33
	v_cvt_pk_bf16_f32 v34, v34, v34
	ds_write_b16 v205, v34 offset:33968
	v_mul_f32_e32 v34, v85, v32
	v_cvt_pk_bf16_f32 v34, v34, v34
	ds_write_b16 v205, v34 offset:24896
	v_mul_f32_e32 v34, v85, v33
	v_cvt_pk_bf16_f32 v34, v34, v34
	ds_write_b16 v205, v34 offset:34112
	v_mul_f32_e32 v34, v86, v32
	v_cvt_pk_bf16_f32 v34, v34, v34
	ds_write_b16 v205, v34 offset:25040
	v_mul_f32_e32 v34, v86, v33
	v_cvt_pk_bf16_f32 v34, v34, v34
	ds_write_b16 v205, v34 offset:34256
	v_mul_f32_e32 v34, v87, v32
	v_cvt_pk_bf16_f32 v34, v34, v34
	ds_write_b16 v205, v34 offset:25184
	v_mul_f32_e32 v34, v87, v33
	v_cvt_pk_bf16_f32 v34, v34, v34
	ds_write_b16 v205, v34 offset:34400
	v_mul_f32_e32 v34, v88, v32
	v_cvt_pk_bf16_f32 v34, v34, v34
	ds_write_b16 v205, v34 offset:25328
	v_mul_f32_e32 v34, v88, v33
	v_cvt_pk_bf16_f32 v34, v34, v34
	ds_write_b16 v205, v34 offset:34544
	v_mul_f32_e32 v34, v89, v32
	v_cvt_pk_bf16_f32 v34, v34, v34
	ds_write_b16 v227, v34 offset:17408
	v_mul_f32_e32 v34, v89, v33
	v_cvt_pk_bf16_f32 v34, v34, v34
	ds_write_b16 v227, v34 offset:26624
	v_mul_f32_e32 v34, v90, v32
	v_cvt_pk_bf16_f32 v34, v34, v34
	ds_write_b16 v205, v34 offset:25616
	v_mul_f32_e32 v34, v90, v33
	v_cvt_pk_bf16_f32 v34, v34, v34
	ds_write_b16 v205, v34 offset:34832
	v_mul_f32_e32 v34, v91, v32
	v_cvt_pk_bf16_f32 v34, v34, v34
	ds_write_b16 v205, v34 offset:25760
	v_mul_f32_e32 v34, v91, v33
	v_cvt_pk_bf16_f32 v34, v34, v34
	ds_write_b16 v205, v34 offset:34976
	v_mul_f32_e32 v34, v92, v32
	v_cvt_pk_bf16_f32 v34, v34, v34
	ds_write_b16 v205, v34 offset:25904
	v_mul_f32_e32 v34, v92, v33
	v_cvt_pk_bf16_f32 v34, v34, v34
	ds_write_b16 v205, v34 offset:35120
	v_mul_f32_e32 v34, v94, v32
	v_cvt_pk_bf16_f32 v34, v34, v34
	ds_write_b16 v205, v34 offset:26048
	v_mul_f32_e32 v34, v94, v33
	v_cvt_pk_bf16_f32 v34, v34, v34
	ds_write_b16 v205, v34 offset:35264
	v_mul_f32_e32 v34, v95, v32
	v_cvt_pk_bf16_f32 v34, v34, v34
	ds_write_b16 v205, v34 offset:26192
	v_mul_f32_e32 v34, v95, v33
	v_cvt_pk_bf16_f32 v34, v34, v34
	ds_write_b16 v205, v34 offset:35408
	v_mul_f32_e32 v34, v107, v32
	v_cvt_pk_bf16_f32 v34, v34, v34
	ds_write_b16 v205, v34 offset:26336
	v_mul_f32_e32 v34, v107, v33
	v_mul_f32_e32 v32, v93, v32
	v_cvt_pk_bf16_f32 v34, v34, v34
	ds_write_b16 v205, v34 offset:35552
	v_cvt_pk_bf16_f32 v32, v32, v32
	ds_write_b16 v205, v32 offset:26480
	v_mul_f32_e32 v32, v93, v33
	v_cvt_pk_bf16_f32 v32, v32, v32
	ds_write_b16 v205, v32 offset:35696
	s_branch .LBB0_252
